# MFMA accumulate-chain order, variant m,half,n,k: the activation fragment pair is held for 8 consecutive MFMAs, weight fragments all distinct
# speedup vs baseline: 1.0104x; 1.0104x over previous
; #define PG8_STAGE(bufoff, gbase, voff) do { _Pragma("unroll") for (int _i = 0; _i < 2; ++_i) \
;         __builtin_amdgcn_global_load_lds((const unsigned*)((const char*)(gbase) + (voff)[_i]), (PG8_LAS unsigned*)(lds + (bufoff) + ldsw + _i * 8192), 16, 0, 0); } while (0)
; #define PG8_LDA(dst, b, h) do { _Pragma("unroll") for (int m = 0; m < 4; ++m) _Pragma("unroll") for (int k = 0; k < 2; ++k) dst[m][k] = *(const PG8_LAS bf16x8*)(lds + PG8_SA(b, h) + aoff + m * 2048 + k * 1024); } while (0)
; #define PG8_LDB(dst, b, h) do { _Pragma("unroll") for (int n = 0; n < 2; ++n) _Pragma("unroll") for (int k = 0; k < 2; ++k) dst[n][k] = *(const PG8_LAS bf16x8*)(lds + PG8_SB(b, h) + boff + n * 2048 + k * 1024); } while (0)
; #define PG8_MMA(ai, bj, At, Bt) do { __builtin_amdgcn_s_setprio(1); _Pragma("unroll") for (int m = 0; m < 4; ++m) _Pragma("unroll") for (int n = 0; n < 2; ++n) _Pragma("unroll") for (int k = 0; k < 2; ++k) \
;         acc[ai][bj][m][n] = __builtin_amdgcn_mfma_f32_16x16x32_bf16(Bt[n][k], At[m][k], acc[ai][bj][m][n], 0, 0, 0); __builtin_amdgcn_s_setprio(0); } while (0)
; #define PG8_WAIT_V(n) asm volatile("s_waitcnt vmcnt(" #n ")" ::: "memory")
; #define PG8_WAIT_L(n) asm volatile("s_waitcnt lgkmcnt(" #n ")" ::: "memory")
; #define PG8_BAR __builtin_amdgcn_s_barrier()
; template <class Epi, class Sched, bool ALIGN_EPI = false, bool SP2 = false>
; __device__ __forceinline__ void gemm_phase(PG8_LAS unsigned char* lds, const Gemm g, const Sched& S, const Epi& E) {
;     ...
;             const char* a1 = cA + (size_t)(t + 1) * kstep;
;             const char* a2 = last ? nA : cA + (size_t)(t + 2) * kstep; const char* b2 = last ? nB : cB + (size_t)(t + 2) * kstep;
;             const char* a3 = a2 + kstep; const char* b3 = b2 + kstep;
;             if (last && has_next) S.a_ready(nxt);
;             if constexpr (SP2) {
;             PG8_LDB(B0, 0, 0); PG8_LDB(B1, 0, 1); PG8_SCHED; PG8_LDA(At, 0, 0); PG8_STAGE(PG8_SA(1, 1), a1 + hstep, voffA);
;             PG8_WAIT_V(8); PG8_WAIT_L(0); PG8_BAR; PG8_MMA(0, 0, At, B0); PG8_MMA(0, 1, At, B1); PG8_BAR; PG8_SCHED;
;             PG8_LDA(At, 0, 1); PG8_STAGE(PG8_SB(0, 0), b2, voffB); PG8_STAGE(PG8_SB(0, 1), b2 + hstep, voffB); PG8_STAGE(PG8_SA(0, 0), a2, voffA);
;             PG8_WAIT_V(8); PG8_WAIT_L(0); PG8_BAR; PG8_MMA(1, 0, At, B0); PG8_MMA(1, 1, At, B1); PG8_BAR; PG8_SCHED;
.Labo_peel:
	ds_read_b128 v[68:71], v254
	ds_read_b128 v[72:75], v254 offset:1024
	ds_read_b128 v[76:79], v254 offset:2048
	ds_read_b128 v[80:83], v254 offset:3072
	ds_read_b128 v[174:177], v254 offset:16384
	ds_read_b128 v[182:185], v254 offset:17408
	ds_read_b128 v[186:189], v254 offset:18432
	ds_read_b128 v[210:213], v254 offset:19456
	s_add_u32 s2, s0, 0xfffc0080
	s_addc_u32 s3, s1, -1
	s_cmp_eq_u32 s56, 12
	s_cselect_b32 s5, s27, s3
	s_cselect_b32 s4, s52, s2
	s_cselect_b32 s3, s25, s55
	s_cselect_b32 s2, s53, s54
	s_add_i32 m0, s29, 0xc000
	ds_read_b128 v[214:217], v179
	ds_read_b128 v[218:221], v179 offset:1024
	ds_read_b128 v[222:225], v179 offset:2048
	ds_read_b128 v[226:229], v179 offset:3072
	ds_read_b128 v[230:233], v179 offset:4096
	ds_read_b128 v[234:237], v179 offset:5120
	ds_read_b128 v[238:241], v179 offset:6144
	ds_read_b128 v[242:245], v179 offset:7168
	global_load_lds_dwordx4 v170, s[0:1]
	s_add_i32 m0, s29, 0xe000
	s_nop 0
	global_load_lds_dwordx4 v172, s[0:1]
	s_waitcnt vmcnt(8)
	s_waitcnt lgkmcnt(0)
	s_barrier
	s_setprio 1
	v_mfma_f32_16x16x32_bf16 v[140:143], v[68:71], v[214:217], 0
	v_mfma_f32_16x16x32_bf16 v[140:143], v[72:75], v[218:221], v[140:143]
	v_mfma_f32_16x16x32_bf16 v[136:139], v[76:79], v[214:217], 0
	v_mfma_f32_16x16x32_bf16 v[136:139], v[80:83], v[218:221], v[136:139]
	v_mfma_f32_16x16x32_bf16 v[132:135], v[174:177], v[214:217], 0
	v_mfma_f32_16x16x32_bf16 v[132:135], v[182:185], v[218:221], v[132:135]
	v_mfma_f32_16x16x32_bf16 v[128:131], v[186:189], v[214:217], 0
	v_mfma_f32_16x16x32_bf16 v[128:131], v[210:213], v[218:221], v[128:131]
	v_mfma_f32_16x16x32_bf16 v[124:127], v[68:71], v[222:225], 0
	v_mfma_f32_16x16x32_bf16 v[124:127], v[72:75], v[226:229], v[124:127]
	v_mfma_f32_16x16x32_bf16 v[120:123], v[76:79], v[222:225], 0
	v_mfma_f32_16x16x32_bf16 v[120:123], v[80:83], v[226:229], v[120:123]
	v_mfma_f32_16x16x32_bf16 v[116:119], v[174:177], v[222:225], 0
	v_mfma_f32_16x16x32_bf16 v[116:119], v[182:185], v[226:229], v[116:119]
	v_mfma_f32_16x16x32_bf16 v[112:115], v[186:189], v[222:225], 0
	v_mfma_f32_16x16x32_bf16 v[112:115], v[210:213], v[226:229], v[112:115]
	v_mfma_f32_16x16x32_bf16 v[108:111], v[68:71], v[230:233], 0
	v_mfma_f32_16x16x32_bf16 v[108:111], v[72:75], v[234:237], v[108:111]
	v_mfma_f32_16x16x32_bf16 v[104:107], v[76:79], v[230:233], 0
	v_mfma_f32_16x16x32_bf16 v[104:107], v[80:83], v[234:237], v[104:107]
	v_mfma_f32_16x16x32_bf16 v[100:103], v[174:177], v[230:233], 0
	v_mfma_f32_16x16x32_bf16 v[100:103], v[182:185], v[234:237], v[100:103]
	v_mfma_f32_16x16x32_bf16 v[96:99], v[186:189], v[230:233], 0
	v_mfma_f32_16x16x32_bf16 v[96:99], v[210:213], v[234:237], v[96:99]
	v_mfma_f32_16x16x32_bf16 v[92:95], v[68:71], v[238:241], 0
	v_mfma_f32_16x16x32_bf16 v[92:95], v[72:75], v[242:245], v[92:95]
	v_mfma_f32_16x16x32_bf16 v[88:91], v[76:79], v[238:241], 0
	v_mfma_f32_16x16x32_bf16 v[88:91], v[80:83], v[242:245], v[88:91]
	v_mfma_f32_16x16x32_bf16 v[84:87], v[174:177], v[238:241], 0
	v_mfma_f32_16x16x32_bf16 v[84:87], v[182:185], v[242:245], v[84:87]
	v_mfma_f32_16x16x32_bf16 v[64:67], v[186:189], v[238:241], 0
	v_mfma_f32_16x16x32_bf16 v[64:67], v[210:213], v[242:245], v[64:67]
	s_setprio 0
	s_barrier
	s_mov_b32 m0, s30
	s_add_u32 s58, s2, 0x40000
	s_addc_u32 s59, s3, 0
	ds_read_b128 v[214:217], v179 offset:16384
	ds_read_b128 v[218:221], v179 offset:17408
	ds_read_b128 v[222:225], v179 offset:18432
	ds_read_b128 v[226:229], v179 offset:19456
	ds_read_b128 v[230:233], v179 offset:20480
	ds_read_b128 v[234:237], v179 offset:21504
	ds_read_b128 v[238:241], v179 offset:22528
	ds_read_b128 v[242:245], v179 offset:23552
	global_load_lds_dwordx4 v166, s[2:3]
	s_mov_b32 m0, s31
	s_nop 0
	global_load_lds_dwordx4 v162, s[2:3]
	s_mov_b32 m0, s33
	s_nop 0
	global_load_lds_dwordx4 v166, s[58:59]
	s_mov_b32 m0, s34
	s_nop 0
	global_load_lds_dwordx4 v162, s[58:59]
	s_mov_b32 m0, s29
	s_nop 0
	global_load_lds_dwordx4 v168, s[4:5]
	s_mov_b32 m0, s35
	s_nop 0
	global_load_lds_dwordx4 v164, s[4:5]
	s_waitcnt vmcnt(8)
	s_waitcnt lgkmcnt(0)
	s_barrier
	s_setprio 1
	v_mfma_f32_16x16x32_bf16 v[60:63], v[68:71], v[214:217], 0
	v_mfma_f32_16x16x32_bf16 v[60:63], v[72:75], v[218:221], v[60:63]
	v_mfma_f32_16x16x32_bf16 v[56:59], v[76:79], v[214:217], 0
	v_mfma_f32_16x16x32_bf16 v[56:59], v[80:83], v[218:221], v[56:59]
	v_mfma_f32_16x16x32_bf16 v[52:55], v[174:177], v[214:217], 0
	v_mfma_f32_16x16x32_bf16 v[52:55], v[182:185], v[218:221], v[52:55]
	v_mfma_f32_16x16x32_bf16 v[48:51], v[186:189], v[214:217], 0
	v_mfma_f32_16x16x32_bf16 v[48:51], v[210:213], v[218:221], v[48:51]
	v_mfma_f32_16x16x32_bf16 v[44:47], v[68:71], v[222:225], 0
	v_mfma_f32_16x16x32_bf16 v[44:47], v[72:75], v[226:229], v[44:47]
	v_mfma_f32_16x16x32_bf16 v[40:43], v[76:79], v[222:225], 0
	v_mfma_f32_16x16x32_bf16 v[40:43], v[80:83], v[226:229], v[40:43]
	v_mfma_f32_16x16x32_bf16 v[36:39], v[174:177], v[222:225], 0
	v_mfma_f32_16x16x32_bf16 v[36:39], v[182:185], v[226:229], v[36:39]
	v_mfma_f32_16x16x32_bf16 v[32:35], v[186:189], v[222:225], 0
	v_mfma_f32_16x16x32_bf16 v[32:35], v[210:213], v[226:229], v[32:35]
	v_mfma_f32_16x16x32_bf16 v[28:31], v[68:71], v[230:233], 0
	v_mfma_f32_16x16x32_bf16 v[28:31], v[72:75], v[234:237], v[28:31]
	v_mfma_f32_16x16x32_bf16 v[24:27], v[76:79], v[230:233], 0
	v_mfma_f32_16x16x32_bf16 v[24:27], v[80:83], v[234:237], v[24:27]
	v_mfma_f32_16x16x32_bf16 v[20:23], v[174:177], v[230:233], 0
	v_mfma_f32_16x16x32_bf16 v[20:23], v[182:185], v[234:237], v[20:23]
	v_mfma_f32_16x16x32_bf16 v[16:19], v[186:189], v[230:233], 0
	v_mfma_f32_16x16x32_bf16 v[16:19], v[210:213], v[234:237], v[16:19]
	v_mfma_f32_16x16x32_bf16 v[12:15], v[68:71], v[238:241], 0
	v_mfma_f32_16x16x32_bf16 v[12:15], v[72:75], v[242:245], v[12:15]
	v_mfma_f32_16x16x32_bf16 v[8:11], v[76:79], v[238:241], 0
	v_mfma_f32_16x16x32_bf16 v[8:11], v[80:83], v[242:245], v[8:11]
	v_mfma_f32_16x16x32_bf16 v[4:7], v[174:177], v[238:241], 0
	v_mfma_f32_16x16x32_bf16 v[4:7], v[182:185], v[242:245], v[4:7]
	v_mfma_f32_16x16x32_bf16 v[0:3], v[186:189], v[238:241], 0
	v_mfma_f32_16x16x32_bf16 v[0:3], v[210:213], v[242:245], v[0:3]
	s_setprio 0
	s_barrier
; #define PG8_STAGE(bufoff, gbase, voff) do { _Pragma("unroll") for (int _i = 0; _i < 2; ++_i) \
;         __builtin_amdgcn_global_load_lds((const unsigned*)((const char*)(gbase) + (voff)[_i]), (PG8_LAS unsigned*)(lds + (bufoff) + ldsw + _i * 8192), 16, 0, 0); } while (0)
; #define PG8_LDA(dst, b, h) do { _Pragma("unroll") for (int m = 0; m < 4; ++m) _Pragma("unroll") for (int k = 0; k < 2; ++k) dst[m][k] = *(const PG8_LAS bf16x8*)(lds + PG8_SA(b, h) + aoff + m * 2048 + k * 1024); } while (0)
; #define PG8_LDB(dst, b, h) do { _Pragma("unroll") for (int n = 0; n < 2; ++n) _Pragma("unroll") for (int k = 0; k < 2; ++k) dst[n][k] = *(const PG8_LAS bf16x8*)(lds + PG8_SB(b, h) + boff + n * 2048 + k * 1024); } while (0)
; #define PG8_MMA(ai, bj, At, Bt) do { __builtin_amdgcn_s_setprio(1); _Pragma("unroll") for (int m = 0; m < 4; ++m) _Pragma("unroll") for (int n = 0; n < 2; ++n) _Pragma("unroll") for (int k = 0; k < 2; ++k) \
;         acc[ai][bj][m][n] = __builtin_amdgcn_mfma_f32_16x16x32_bf16(Bt[n][k], At[m][k], acc[ai][bj][m][n], 0, 0, 0); __builtin_amdgcn_s_setprio(0); } while (0)
; #define PG8_WAIT_V(n) asm volatile("s_waitcnt vmcnt(" #n ")" ::: "memory")
; #define PG8_WAIT_L(n) asm volatile("s_waitcnt lgkmcnt(" #n ")" ::: "memory")
; #define PG8_BAR __builtin_amdgcn_s_barrier()
; #define PG8_SCHED __builtin_amdgcn_sched_barrier(0)
; template <class Epi, class Sched, bool ALIGN_EPI = false, bool SP2 = false>
; __device__ __forceinline__ void gemm_phase(PG8_LAS unsigned char* lds, const Gemm g, const Sched& S, const Epi& E) {
;     ...
;         for (int t = 0; t < nt; t += 2) {
;     ...
;             PG8_LDB(B0, 1, 0); PG8_LDB(B1, 1, 1); PG8_SCHED; PG8_LDA(At, 1, 0); PG8_STAGE(PG8_SA(0, 1), a2 + hstep, voffA);
;             PG8_WAIT_V(8); PG8_WAIT_L(0); PG8_BAR; PG8_MMA(0, 0, At, B0); PG8_MMA(0, 1, At, B1); PG8_BAR; PG8_SCHED;
;             PG8_LDA(At, 1, 1); PG8_STAGE(PG8_SB(1, 0), b3, voffB); PG8_STAGE(PG8_SB(1, 1), b3 + hstep, voffB); PG8_STAGE(PG8_SA(1, 0), a3, voffA);
;             PG8_WAIT_V(8); PG8_WAIT_L(0); PG8_BAR; PG8_MMA(1, 0, At, B0); PG8_MMA(1, 1, At, B1); PG8_BAR; PG8_SCHED;
	ds_read_b128 v[68:71], v254 offset:32768
	ds_read_b128 v[72:75], v254 offset:33792
	ds_read_b128 v[76:79], v254 offset:34816
	ds_read_b128 v[80:83], v254 offset:35840
	ds_read_b128 v[174:177], v254 offset:49152
	ds_read_b128 v[182:185], v254 offset:50176
	ds_read_b128 v[186:189], v254 offset:51200
	ds_read_b128 v[210:213], v254 offset:52224
	s_add_u32 s4, s4, 0x40000
	s_addc_u32 s5, s5, 0
	s_mov_b32 m0, s40
	ds_read_b128 v[214:217], v179 offset:32768
	ds_read_b128 v[218:221], v179 offset:33792
	ds_read_b128 v[222:225], v179 offset:34816
	ds_read_b128 v[226:229], v179 offset:35840
	ds_read_b128 v[230:233], v179 offset:36864
	ds_read_b128 v[234:237], v179 offset:37888
	ds_read_b128 v[238:241], v179 offset:38912
	ds_read_b128 v[242:245], v179 offset:39936
	global_load_lds_dwordx4 v168, s[4:5]
	s_mov_b32 m0, s41
	s_nop 0
	global_load_lds_dwordx4 v164, s[4:5]
	s_waitcnt vmcnt(8)
	s_waitcnt lgkmcnt(0)
	s_barrier
	s_setprio 1
	v_mfma_f32_16x16x32_bf16 v[140:143], v[68:71], v[214:217], v[140:143]
	v_mfma_f32_16x16x32_bf16 v[140:143], v[72:75], v[218:221], v[140:143]
	v_mfma_f32_16x16x32_bf16 v[136:139], v[76:79], v[214:217], v[136:139]
	v_mfma_f32_16x16x32_bf16 v[136:139], v[80:83], v[218:221], v[136:139]
	v_mfma_f32_16x16x32_bf16 v[132:135], v[174:177], v[214:217], v[132:135]
	v_mfma_f32_16x16x32_bf16 v[132:135], v[182:185], v[218:221], v[132:135]
	v_mfma_f32_16x16x32_bf16 v[128:131], v[186:189], v[214:217], v[128:131]
	v_mfma_f32_16x16x32_bf16 v[128:131], v[210:213], v[218:221], v[128:131]
	v_mfma_f32_16x16x32_bf16 v[124:127], v[68:71], v[222:225], v[124:127]
	v_mfma_f32_16x16x32_bf16 v[124:127], v[72:75], v[226:229], v[124:127]
	v_mfma_f32_16x16x32_bf16 v[120:123], v[76:79], v[222:225], v[120:123]
	v_mfma_f32_16x16x32_bf16 v[120:123], v[80:83], v[226:229], v[120:123]
	v_mfma_f32_16x16x32_bf16 v[116:119], v[174:177], v[222:225], v[116:119]
	v_mfma_f32_16x16x32_bf16 v[116:119], v[182:185], v[226:229], v[116:119]
	v_mfma_f32_16x16x32_bf16 v[112:115], v[186:189], v[222:225], v[112:115]
	v_mfma_f32_16x16x32_bf16 v[112:115], v[210:213], v[226:229], v[112:115]
	v_mfma_f32_16x16x32_bf16 v[108:111], v[68:71], v[230:233], v[108:111]
	v_mfma_f32_16x16x32_bf16 v[108:111], v[72:75], v[234:237], v[108:111]
	v_mfma_f32_16x16x32_bf16 v[104:107], v[76:79], v[230:233], v[104:107]
	v_mfma_f32_16x16x32_bf16 v[104:107], v[80:83], v[234:237], v[104:107]
	v_mfma_f32_16x16x32_bf16 v[100:103], v[174:177], v[230:233], v[100:103]
	v_mfma_f32_16x16x32_bf16 v[100:103], v[182:185], v[234:237], v[100:103]
	v_mfma_f32_16x16x32_bf16 v[96:99], v[186:189], v[230:233], v[96:99]
	v_mfma_f32_16x16x32_bf16 v[96:99], v[210:213], v[234:237], v[96:99]
	v_mfma_f32_16x16x32_bf16 v[92:95], v[68:71], v[238:241], v[92:95]
	v_mfma_f32_16x16x32_bf16 v[92:95], v[72:75], v[242:245], v[92:95]
	v_mfma_f32_16x16x32_bf16 v[88:91], v[76:79], v[238:241], v[88:91]
	v_mfma_f32_16x16x32_bf16 v[88:91], v[80:83], v[242:245], v[88:91]
	v_mfma_f32_16x16x32_bf16 v[84:87], v[174:177], v[238:241], v[84:87]
	v_mfma_f32_16x16x32_bf16 v[84:87], v[182:185], v[242:245], v[84:87]
	v_mfma_f32_16x16x32_bf16 v[64:67], v[186:189], v[238:241], v[64:67]
	v_mfma_f32_16x16x32_bf16 v[64:67], v[210:213], v[242:245], v[64:67]
	s_setprio 0
	s_barrier
	s_mov_b32 m0, s45
	s_add_u32 s2, s2, 0x40080
	s_addc_u32 s3, s3, 0
	ds_read_b128 v[214:217], v179 offset:49152
	ds_read_b128 v[218:221], v179 offset:50176
	ds_read_b128 v[222:225], v179 offset:51200
	ds_read_b128 v[226:229], v179 offset:52224
	ds_read_b128 v[230:233], v179 offset:53248
	ds_read_b128 v[234:237], v179 offset:54272
	ds_read_b128 v[238:241], v179 offset:55296
	ds_read_b128 v[242:245], v179 offset:56320
	s_add_u32 s98, s2, 0xfffc0000
	s_addc_u32 s99, s3, -1
	global_load_lds_dwordx4 v166, s[98:99]
	s_mov_b32 m0, s46
	s_nop 0
	global_load_lds_dwordx4 v162, s[98:99]
	s_mov_b32 m0, s49
	s_nop 0
	global_load_lds_dwordx4 v166, s[2:3]
	s_mov_b32 m0, s50
	s_nop 0
	global_load_lds_dwordx4 v162, s[2:3]
	s_mov_b32 m0, s47
	s_nop 0
	s_add_u32 s100, s4, 0xfffc0080
	s_addc_u32 s101, s5, -1
	global_load_lds_dwordx4 v168, s[100:101]
	s_mov_b32 m0, s48
	s_nop 0
	global_load_lds_dwordx4 v164, s[100:101]
	s_waitcnt vmcnt(8)
	s_waitcnt lgkmcnt(0)
	s_barrier
	s_setprio 1
	v_mfma_f32_16x16x32_bf16 v[60:63], v[68:71], v[214:217], v[60:63]
	v_mfma_f32_16x16x32_bf16 v[60:63], v[72:75], v[218:221], v[60:63]
	v_mfma_f32_16x16x32_bf16 v[56:59], v[76:79], v[214:217], v[56:59]
	v_mfma_f32_16x16x32_bf16 v[56:59], v[80:83], v[218:221], v[56:59]
	v_mfma_f32_16x16x32_bf16 v[52:55], v[174:177], v[214:217], v[52:55]
	v_mfma_f32_16x16x32_bf16 v[52:55], v[182:185], v[218:221], v[52:55]
	v_mfma_f32_16x16x32_bf16 v[48:51], v[186:189], v[214:217], v[48:51]
	v_mfma_f32_16x16x32_bf16 v[48:51], v[210:213], v[218:221], v[48:51]
	v_mfma_f32_16x16x32_bf16 v[44:47], v[68:71], v[222:225], v[44:47]
	v_mfma_f32_16x16x32_bf16 v[44:47], v[72:75], v[226:229], v[44:47]
	v_mfma_f32_16x16x32_bf16 v[40:43], v[76:79], v[222:225], v[40:43]
	v_mfma_f32_16x16x32_bf16 v[40:43], v[80:83], v[226:229], v[40:43]
	v_mfma_f32_16x16x32_bf16 v[36:39], v[174:177], v[222:225], v[36:39]
	v_mfma_f32_16x16x32_bf16 v[36:39], v[182:185], v[226:229], v[36:39]
	v_mfma_f32_16x16x32_bf16 v[32:35], v[186:189], v[222:225], v[32:35]
	v_mfma_f32_16x16x32_bf16 v[32:35], v[210:213], v[226:229], v[32:35]
	v_mfma_f32_16x16x32_bf16 v[28:31], v[68:71], v[230:233], v[28:31]
	v_mfma_f32_16x16x32_bf16 v[28:31], v[72:75], v[234:237], v[28:31]
	v_mfma_f32_16x16x32_bf16 v[24:27], v[76:79], v[230:233], v[24:27]
	v_mfma_f32_16x16x32_bf16 v[24:27], v[80:83], v[234:237], v[24:27]
	v_mfma_f32_16x16x32_bf16 v[20:23], v[174:177], v[230:233], v[20:23]
	v_mfma_f32_16x16x32_bf16 v[20:23], v[182:185], v[234:237], v[20:23]
	v_mfma_f32_16x16x32_bf16 v[16:19], v[186:189], v[230:233], v[16:19]
	v_mfma_f32_16x16x32_bf16 v[16:19], v[210:213], v[234:237], v[16:19]
	v_mfma_f32_16x16x32_bf16 v[12:15], v[68:71], v[238:241], v[12:15]
	v_mfma_f32_16x16x32_bf16 v[12:15], v[72:75], v[242:245], v[12:15]
	v_mfma_f32_16x16x32_bf16 v[8:11], v[76:79], v[238:241], v[8:11]
	v_mfma_f32_16x16x32_bf16 v[8:11], v[80:83], v[242:245], v[8:11]
	v_mfma_f32_16x16x32_bf16 v[4:7], v[174:177], v[238:241], v[4:7]
	v_mfma_f32_16x16x32_bf16 v[4:7], v[182:185], v[242:245], v[4:7]
	v_mfma_f32_16x16x32_bf16 v[0:3], v[186:189], v[238:241], v[0:3]
	v_mfma_f32_16x16x32_bf16 v[0:3], v[210:213], v[242:245], v[0:3]
	s_setprio 0
	s_barrier
	s_add_i32 s56, s56, 2
	s_add_u32 s0, s0, 0x100
	s_addc_u32 s1, s1, 0
	s_add_u32 s54, s54, 0x100
	s_addc_u32 s55, s55, 0
	s_cmp_gt_u32 s56, 13
; #define PG8_STAGE(bufoff, gbase, voff) do { _Pragma("unroll") for (int _i = 0; _i < 2; ++_i) \
;         __builtin_amdgcn_global_load_lds((const unsigned*)((const char*)(gbase) + (voff)[_i]), (PG8_LAS unsigned*)(lds + (bufoff) + ldsw + _i * 8192), 16, 0, 0); } while (0)
; #define PG8_LDA(dst, b, h) do { _Pragma("unroll") for (int m = 0; m < 4; ++m) _Pragma("unroll") for (int k = 0; k < 2; ++k) dst[m][k] = *(const PG8_LAS bf16x8*)(lds + PG8_SA(b, h) + aoff + m * 2048 + k * 1024); } while (0)
; #define PG8_LDB(dst, b, h) do { _Pragma("unroll") for (int n = 0; n < 2; ++n) _Pragma("unroll") for (int k = 0; k < 2; ++k) dst[n][k] = *(const PG8_LAS bf16x8*)(lds + PG8_SB(b, h) + boff + n * 2048 + k * 1024); } while (0)
; #define PG8_MMA(ai, bj, At, Bt) do { __builtin_amdgcn_s_setprio(1); _Pragma("unroll") for (int m = 0; m < 4; ++m) _Pragma("unroll") for (int n = 0; n < 2; ++n) _Pragma("unroll") for (int k = 0; k < 2; ++k) \
;         acc[ai][bj][m][n] = __builtin_amdgcn_mfma_f32_16x16x32_bf16(Bt[n][k], At[m][k], acc[ai][bj][m][n], 0, 0, 0); __builtin_amdgcn_s_setprio(0); } while (0)
; #define PG8_WAIT_V(n) asm volatile("s_waitcnt vmcnt(" #n ")" ::: "memory")
; #define PG8_WAIT_L(n) asm volatile("s_waitcnt lgkmcnt(" #n ")" ::: "memory")
; #define PG8_BAR __builtin_amdgcn_s_barrier()
; template <class Epi, class Sched, bool ALIGN_EPI = false, bool SP2 = false>
; __device__ __forceinline__ void gemm_phase(PG8_LAS unsigned char* lds, const Gemm g, const Sched& S, const Epi& E) {
;     ...
;             const char* a1 = cA + (size_t)(t + 1) * kstep;
;             const char* a2 = last ? nA : cA + (size_t)(t + 2) * kstep; const char* b2 = last ? nB : cB + (size_t)(t + 2) * kstep;
;             const char* a3 = a2 + kstep; const char* b3 = b2 + kstep;
;             if (last && has_next) S.a_ready(nxt);
;             if constexpr (SP2) {
;             PG8_LDB(B0, 0, 0); PG8_LDB(B1, 0, 1); PG8_SCHED; PG8_LDA(At, 0, 0); PG8_STAGE(PG8_SA(1, 1), a1 + hstep, voffA);
;             PG8_WAIT_V(8); PG8_WAIT_L(0); PG8_BAR; PG8_MMA(0, 0, At, B0); PG8_MMA(0, 1, At, B1); PG8_BAR; PG8_SCHED;
;             PG8_LDA(At, 0, 1); PG8_STAGE(PG8_SB(0, 0), b2, voffB); PG8_STAGE(PG8_SB(0, 1), b2 + hstep, voffB); PG8_STAGE(PG8_SA(0, 0), a2, voffA);
;             PG8_WAIT_V(8); PG8_WAIT_L(0); PG8_BAR; PG8_MMA(1, 0, At, B0); PG8_MMA(1, 1, At, B1); PG8_BAR; PG8_SCHED;
.LBB0_327:
	ds_read_b128 v[68:71], v254
	ds_read_b128 v[72:75], v254 offset:1024
	ds_read_b128 v[76:79], v254 offset:2048
	ds_read_b128 v[80:83], v254 offset:3072
	ds_read_b128 v[174:177], v254 offset:16384
	ds_read_b128 v[182:185], v254 offset:17408
	ds_read_b128 v[186:189], v254 offset:18432
	ds_read_b128 v[210:213], v254 offset:19456
	s_add_u32 s2, s0, 0xfffc0080
	s_addc_u32 s3, s1, -1
	s_cmp_eq_u32 s56, 12
	s_cselect_b32 s5, s27, s3
	s_cselect_b32 s4, s52, s2
	s_cselect_b32 s3, s25, s55
	s_cselect_b32 s2, s53, s54
	s_add_i32 m0, s29, 0xc000
	ds_read_b128 v[214:217], v179
	ds_read_b128 v[218:221], v179 offset:1024
	ds_read_b128 v[222:225], v179 offset:2048
	ds_read_b128 v[226:229], v179 offset:3072
	ds_read_b128 v[230:233], v179 offset:4096
	ds_read_b128 v[234:237], v179 offset:5120
	ds_read_b128 v[238:241], v179 offset:6144
	ds_read_b128 v[242:245], v179 offset:7168
	global_load_lds_dwordx4 v170, s[0:1]
	s_add_i32 m0, s29, 0xe000
	s_nop 0
	global_load_lds_dwordx4 v172, s[0:1]
	s_waitcnt vmcnt(8)
	s_waitcnt lgkmcnt(0)
	s_barrier
	s_setprio 1
	v_mfma_f32_16x16x32_bf16 v[140:143], v[68:71], v[214:217], v[140:143]
	v_mfma_f32_16x16x32_bf16 v[140:143], v[72:75], v[218:221], v[140:143]
	v_mfma_f32_16x16x32_bf16 v[136:139], v[76:79], v[214:217], v[136:139]
	v_mfma_f32_16x16x32_bf16 v[136:139], v[80:83], v[218:221], v[136:139]
	v_mfma_f32_16x16x32_bf16 v[132:135], v[174:177], v[214:217], v[132:135]
	v_mfma_f32_16x16x32_bf16 v[132:135], v[182:185], v[218:221], v[132:135]
	v_mfma_f32_16x16x32_bf16 v[128:131], v[186:189], v[214:217], v[128:131]
	v_mfma_f32_16x16x32_bf16 v[128:131], v[210:213], v[218:221], v[128:131]
	v_mfma_f32_16x16x32_bf16 v[124:127], v[68:71], v[222:225], v[124:127]
	v_mfma_f32_16x16x32_bf16 v[124:127], v[72:75], v[226:229], v[124:127]
	v_mfma_f32_16x16x32_bf16 v[120:123], v[76:79], v[222:225], v[120:123]
	v_mfma_f32_16x16x32_bf16 v[120:123], v[80:83], v[226:229], v[120:123]
	v_mfma_f32_16x16x32_bf16 v[116:119], v[174:177], v[222:225], v[116:119]
	v_mfma_f32_16x16x32_bf16 v[116:119], v[182:185], v[226:229], v[116:119]
	v_mfma_f32_16x16x32_bf16 v[112:115], v[186:189], v[222:225], v[112:115]
	v_mfma_f32_16x16x32_bf16 v[112:115], v[210:213], v[226:229], v[112:115]
	v_mfma_f32_16x16x32_bf16 v[108:111], v[68:71], v[230:233], v[108:111]
	v_mfma_f32_16x16x32_bf16 v[108:111], v[72:75], v[234:237], v[108:111]
	v_mfma_f32_16x16x32_bf16 v[104:107], v[76:79], v[230:233], v[104:107]
	v_mfma_f32_16x16x32_bf16 v[104:107], v[80:83], v[234:237], v[104:107]
	v_mfma_f32_16x16x32_bf16 v[100:103], v[174:177], v[230:233], v[100:103]
	v_mfma_f32_16x16x32_bf16 v[100:103], v[182:185], v[234:237], v[100:103]
	v_mfma_f32_16x16x32_bf16 v[96:99], v[186:189], v[230:233], v[96:99]
	v_mfma_f32_16x16x32_bf16 v[96:99], v[210:213], v[234:237], v[96:99]
	v_mfma_f32_16x16x32_bf16 v[92:95], v[68:71], v[238:241], v[92:95]
	v_mfma_f32_16x16x32_bf16 v[92:95], v[72:75], v[242:245], v[92:95]
	v_mfma_f32_16x16x32_bf16 v[88:91], v[76:79], v[238:241], v[88:91]
	v_mfma_f32_16x16x32_bf16 v[88:91], v[80:83], v[242:245], v[88:91]
	v_mfma_f32_16x16x32_bf16 v[84:87], v[174:177], v[238:241], v[84:87]
	v_mfma_f32_16x16x32_bf16 v[84:87], v[182:185], v[242:245], v[84:87]
	v_mfma_f32_16x16x32_bf16 v[64:67], v[186:189], v[238:241], v[64:67]
	v_mfma_f32_16x16x32_bf16 v[64:67], v[210:213], v[242:245], v[64:67]
	s_setprio 0
	s_barrier
	s_mov_b32 m0, s30
	s_add_u32 s58, s2, 0x40000
	s_addc_u32 s59, s3, 0
	ds_read_b128 v[214:217], v179 offset:16384
	ds_read_b128 v[218:221], v179 offset:17408
	ds_read_b128 v[222:225], v179 offset:18432
	ds_read_b128 v[226:229], v179 offset:19456
	ds_read_b128 v[230:233], v179 offset:20480
	ds_read_b128 v[234:237], v179 offset:21504
	ds_read_b128 v[238:241], v179 offset:22528
	ds_read_b128 v[242:245], v179 offset:23552
	global_load_lds_dwordx4 v166, s[2:3]
	s_mov_b32 m0, s31
	s_nop 0
	global_load_lds_dwordx4 v162, s[2:3]
	s_mov_b32 m0, s33
	s_nop 0
	global_load_lds_dwordx4 v166, s[58:59]
	s_mov_b32 m0, s34
	s_nop 0
	global_load_lds_dwordx4 v162, s[58:59]
	s_mov_b32 m0, s29
	s_nop 0
	global_load_lds_dwordx4 v168, s[4:5]
	s_mov_b32 m0, s35
	s_nop 0
	global_load_lds_dwordx4 v164, s[4:5]
	s_waitcnt vmcnt(8)
	s_waitcnt lgkmcnt(0)
	s_barrier
	s_setprio 1
	v_mfma_f32_16x16x32_bf16 v[60:63], v[68:71], v[214:217], v[60:63]
	v_mfma_f32_16x16x32_bf16 v[60:63], v[72:75], v[218:221], v[60:63]
	v_mfma_f32_16x16x32_bf16 v[56:59], v[76:79], v[214:217], v[56:59]
	v_mfma_f32_16x16x32_bf16 v[56:59], v[80:83], v[218:221], v[56:59]
	v_mfma_f32_16x16x32_bf16 v[52:55], v[174:177], v[214:217], v[52:55]
	v_mfma_f32_16x16x32_bf16 v[52:55], v[182:185], v[218:221], v[52:55]
	v_mfma_f32_16x16x32_bf16 v[48:51], v[186:189], v[214:217], v[48:51]
	v_mfma_f32_16x16x32_bf16 v[48:51], v[210:213], v[218:221], v[48:51]
	v_mfma_f32_16x16x32_bf16 v[44:47], v[68:71], v[222:225], v[44:47]
	v_mfma_f32_16x16x32_bf16 v[44:47], v[72:75], v[226:229], v[44:47]
	v_mfma_f32_16x16x32_bf16 v[40:43], v[76:79], v[222:225], v[40:43]
	v_mfma_f32_16x16x32_bf16 v[40:43], v[80:83], v[226:229], v[40:43]
	v_mfma_f32_16x16x32_bf16 v[36:39], v[174:177], v[222:225], v[36:39]
	v_mfma_f32_16x16x32_bf16 v[36:39], v[182:185], v[226:229], v[36:39]
	v_mfma_f32_16x16x32_bf16 v[32:35], v[186:189], v[222:225], v[32:35]
	v_mfma_f32_16x16x32_bf16 v[32:35], v[210:213], v[226:229], v[32:35]
	v_mfma_f32_16x16x32_bf16 v[28:31], v[68:71], v[230:233], v[28:31]
	v_mfma_f32_16x16x32_bf16 v[28:31], v[72:75], v[234:237], v[28:31]
	v_mfma_f32_16x16x32_bf16 v[24:27], v[76:79], v[230:233], v[24:27]
	v_mfma_f32_16x16x32_bf16 v[24:27], v[80:83], v[234:237], v[24:27]
	v_mfma_f32_16x16x32_bf16 v[20:23], v[174:177], v[230:233], v[20:23]
	v_mfma_f32_16x16x32_bf16 v[20:23], v[182:185], v[234:237], v[20:23]
	v_mfma_f32_16x16x32_bf16 v[16:19], v[186:189], v[230:233], v[16:19]
	v_mfma_f32_16x16x32_bf16 v[16:19], v[210:213], v[234:237], v[16:19]
	v_mfma_f32_16x16x32_bf16 v[12:15], v[68:71], v[238:241], v[12:15]
	v_mfma_f32_16x16x32_bf16 v[12:15], v[72:75], v[242:245], v[12:15]
	v_mfma_f32_16x16x32_bf16 v[8:11], v[76:79], v[238:241], v[8:11]
	v_mfma_f32_16x16x32_bf16 v[8:11], v[80:83], v[242:245], v[8:11]
	v_mfma_f32_16x16x32_bf16 v[4:7], v[174:177], v[238:241], v[4:7]
	v_mfma_f32_16x16x32_bf16 v[4:7], v[182:185], v[242:245], v[4:7]
	v_mfma_f32_16x16x32_bf16 v[0:3], v[186:189], v[238:241], v[0:3]
	v_mfma_f32_16x16x32_bf16 v[0:3], v[210:213], v[242:245], v[0:3]
	s_setprio 0
	s_barrier
; #define PG8_STAGE(bufoff, gbase, voff) do { _Pragma("unroll") for (int _i = 0; _i < 2; ++_i) \
;         __builtin_amdgcn_global_load_lds((const unsigned*)((const char*)(gbase) + (voff)[_i]), (PG8_LAS unsigned*)(lds + (bufoff) + ldsw + _i * 8192), 16, 0, 0); } while (0)
; #define PG8_LDA(dst, b, h) do { _Pragma("unroll") for (int m = 0; m < 4; ++m) _Pragma("unroll") for (int k = 0; k < 2; ++k) dst[m][k] = *(const PG8_LAS bf16x8*)(lds + PG8_SA(b, h) + aoff + m * 2048 + k * 1024); } while (0)
; #define PG8_LDB(dst, b, h) do { _Pragma("unroll") for (int n = 0; n < 2; ++n) _Pragma("unroll") for (int k = 0; k < 2; ++k) dst[n][k] = *(const PG8_LAS bf16x8*)(lds + PG8_SB(b, h) + boff + n * 2048 + k * 1024); } while (0)
; #define PG8_MMA(ai, bj, At, Bt) do { __builtin_amdgcn_s_setprio(1); _Pragma("unroll") for (int m = 0; m < 4; ++m) _Pragma("unroll") for (int n = 0; n < 2; ++n) _Pragma("unroll") for (int k = 0; k < 2; ++k) \
;         acc[ai][bj][m][n] = __builtin_amdgcn_mfma_f32_16x16x32_bf16(Bt[n][k], At[m][k], acc[ai][bj][m][n], 0, 0, 0); __builtin_amdgcn_s_setprio(0); } while (0)
; #define PG8_WAIT_V(n) asm volatile("s_waitcnt vmcnt(" #n ")" ::: "memory")
; #define PG8_WAIT_L(n) asm volatile("s_waitcnt lgkmcnt(" #n ")" ::: "memory")
; #define PG8_BAR __builtin_amdgcn_s_barrier()
; #define PG8_SCHED __builtin_amdgcn_sched_barrier(0)
; template <class Epi, class Sched, bool ALIGN_EPI = false, bool SP2 = false>
; __device__ __forceinline__ void gemm_phase(PG8_LAS unsigned char* lds, const Gemm g, const Sched& S, const Epi& E) {
;     ...
;         for (int t = 0; t < nt; t += 2) {
;     ...
;             PG8_LDB(B0, 1, 0); PG8_LDB(B1, 1, 1); PG8_SCHED; PG8_LDA(At, 1, 0); PG8_STAGE(PG8_SA(0, 1), a2 + hstep, voffA);
;             PG8_WAIT_V(8); PG8_WAIT_L(0); PG8_BAR; PG8_MMA(0, 0, At, B0); PG8_MMA(0, 1, At, B1); PG8_BAR; PG8_SCHED;
;             PG8_LDA(At, 1, 1); PG8_STAGE(PG8_SB(1, 0), b3, voffB); PG8_STAGE(PG8_SB(1, 1), b3 + hstep, voffB); PG8_STAGE(PG8_SA(1, 0), a3, voffA);
;             PG8_WAIT_V(8); PG8_WAIT_L(0); PG8_BAR; PG8_MMA(1, 0, At, B0); PG8_MMA(1, 1, At, B1); PG8_BAR; PG8_SCHED;
;     ...
;         if constexpr (ALIGN_EPI) { if (wr == 0) PG8_BAR; }
	ds_read_b128 v[68:71], v254 offset:32768
	ds_read_b128 v[72:75], v254 offset:33792
	ds_read_b128 v[76:79], v254 offset:34816
	ds_read_b128 v[80:83], v254 offset:35840
	ds_read_b128 v[174:177], v254 offset:49152
	ds_read_b128 v[182:185], v254 offset:50176
	ds_read_b128 v[186:189], v254 offset:51200
	ds_read_b128 v[210:213], v254 offset:52224
	s_add_u32 s4, s4, 0x40000
	s_addc_u32 s5, s5, 0
	s_mov_b32 m0, s40
	ds_read_b128 v[214:217], v179 offset:32768
	ds_read_b128 v[218:221], v179 offset:33792
	ds_read_b128 v[222:225], v179 offset:34816
	ds_read_b128 v[226:229], v179 offset:35840
	ds_read_b128 v[230:233], v179 offset:36864
	ds_read_b128 v[234:237], v179 offset:37888
	ds_read_b128 v[238:241], v179 offset:38912
	ds_read_b128 v[242:245], v179 offset:39936
	global_load_lds_dwordx4 v168, s[4:5]
	s_mov_b32 m0, s41
	s_nop 0
	global_load_lds_dwordx4 v164, s[4:5]
	s_waitcnt vmcnt(8)
	s_waitcnt lgkmcnt(0)
	s_barrier
	s_setprio 1
	v_mfma_f32_16x16x32_bf16 v[140:143], v[68:71], v[214:217], v[140:143]
	v_mfma_f32_16x16x32_bf16 v[140:143], v[72:75], v[218:221], v[140:143]
	v_mfma_f32_16x16x32_bf16 v[136:139], v[76:79], v[214:217], v[136:139]
	v_mfma_f32_16x16x32_bf16 v[136:139], v[80:83], v[218:221], v[136:139]
	v_mfma_f32_16x16x32_bf16 v[132:135], v[174:177], v[214:217], v[132:135]
	v_mfma_f32_16x16x32_bf16 v[132:135], v[182:185], v[218:221], v[132:135]
	v_mfma_f32_16x16x32_bf16 v[128:131], v[186:189], v[214:217], v[128:131]
	v_mfma_f32_16x16x32_bf16 v[128:131], v[210:213], v[218:221], v[128:131]
	v_mfma_f32_16x16x32_bf16 v[124:127], v[68:71], v[222:225], v[124:127]
	v_mfma_f32_16x16x32_bf16 v[124:127], v[72:75], v[226:229], v[124:127]
	v_mfma_f32_16x16x32_bf16 v[120:123], v[76:79], v[222:225], v[120:123]
	v_mfma_f32_16x16x32_bf16 v[120:123], v[80:83], v[226:229], v[120:123]
	v_mfma_f32_16x16x32_bf16 v[116:119], v[174:177], v[222:225], v[116:119]
	v_mfma_f32_16x16x32_bf16 v[116:119], v[182:185], v[226:229], v[116:119]
	v_mfma_f32_16x16x32_bf16 v[112:115], v[186:189], v[222:225], v[112:115]
	v_mfma_f32_16x16x32_bf16 v[112:115], v[210:213], v[226:229], v[112:115]
	v_mfma_f32_16x16x32_bf16 v[108:111], v[68:71], v[230:233], v[108:111]
	v_mfma_f32_16x16x32_bf16 v[108:111], v[72:75], v[234:237], v[108:111]
	v_mfma_f32_16x16x32_bf16 v[104:107], v[76:79], v[230:233], v[104:107]
	v_mfma_f32_16x16x32_bf16 v[104:107], v[80:83], v[234:237], v[104:107]
	v_mfma_f32_16x16x32_bf16 v[100:103], v[174:177], v[230:233], v[100:103]
	v_mfma_f32_16x16x32_bf16 v[100:103], v[182:185], v[234:237], v[100:103]
	v_mfma_f32_16x16x32_bf16 v[96:99], v[186:189], v[230:233], v[96:99]
	v_mfma_f32_16x16x32_bf16 v[96:99], v[210:213], v[234:237], v[96:99]
	v_mfma_f32_16x16x32_bf16 v[92:95], v[68:71], v[238:241], v[92:95]
	v_mfma_f32_16x16x32_bf16 v[92:95], v[72:75], v[242:245], v[92:95]
	v_mfma_f32_16x16x32_bf16 v[88:91], v[76:79], v[238:241], v[88:91]
	v_mfma_f32_16x16x32_bf16 v[88:91], v[80:83], v[242:245], v[88:91]
	v_mfma_f32_16x16x32_bf16 v[84:87], v[174:177], v[238:241], v[84:87]
	v_mfma_f32_16x16x32_bf16 v[84:87], v[182:185], v[242:245], v[84:87]
	v_mfma_f32_16x16x32_bf16 v[64:67], v[186:189], v[238:241], v[64:67]
	v_mfma_f32_16x16x32_bf16 v[64:67], v[210:213], v[242:245], v[64:67]
	s_setprio 0
	s_barrier
	s_mov_b32 m0, s45
	s_add_u32 s2, s2, 0x40080
	s_addc_u32 s3, s3, 0
	ds_read_b128 v[214:217], v179 offset:49152
	ds_read_b128 v[218:221], v179 offset:50176
	ds_read_b128 v[222:225], v179 offset:51200
	ds_read_b128 v[226:229], v179 offset:52224
	ds_read_b128 v[230:233], v179 offset:53248
	ds_read_b128 v[234:237], v179 offset:54272
	ds_read_b128 v[238:241], v179 offset:55296
	ds_read_b128 v[242:245], v179 offset:56320
	s_add_u32 s98, s2, 0xfffc0000
	s_addc_u32 s99, s3, -1
	global_load_lds_dwordx4 v166, s[98:99]
	s_mov_b32 m0, s46
	s_nop 0
	global_load_lds_dwordx4 v162, s[98:99]
	s_mov_b32 m0, s49
	s_nop 0
	global_load_lds_dwordx4 v166, s[2:3]
	s_mov_b32 m0, s50
	s_nop 0
	global_load_lds_dwordx4 v162, s[2:3]
	s_mov_b32 m0, s47
	s_nop 0
	s_add_u32 s100, s4, 0xfffc0080
	s_addc_u32 s101, s5, -1
	global_load_lds_dwordx4 v168, s[100:101]
	s_mov_b32 m0, s48
	s_nop 0
	global_load_lds_dwordx4 v164, s[100:101]
	s_waitcnt vmcnt(8)
	s_waitcnt lgkmcnt(0)
	s_barrier
	s_setprio 1
	v_mfma_f32_16x16x32_bf16 v[60:63], v[68:71], v[214:217], v[60:63]
	v_mfma_f32_16x16x32_bf16 v[60:63], v[72:75], v[218:221], v[60:63]
	v_mfma_f32_16x16x32_bf16 v[56:59], v[76:79], v[214:217], v[56:59]
	v_mfma_f32_16x16x32_bf16 v[56:59], v[80:83], v[218:221], v[56:59]
	v_mfma_f32_16x16x32_bf16 v[52:55], v[174:177], v[214:217], v[52:55]
	v_mfma_f32_16x16x32_bf16 v[52:55], v[182:185], v[218:221], v[52:55]
	v_mfma_f32_16x16x32_bf16 v[48:51], v[186:189], v[214:217], v[48:51]
	v_mfma_f32_16x16x32_bf16 v[48:51], v[210:213], v[218:221], v[48:51]
	v_mfma_f32_16x16x32_bf16 v[44:47], v[68:71], v[222:225], v[44:47]
	v_mfma_f32_16x16x32_bf16 v[44:47], v[72:75], v[226:229], v[44:47]
	v_mfma_f32_16x16x32_bf16 v[40:43], v[76:79], v[222:225], v[40:43]
	v_mfma_f32_16x16x32_bf16 v[40:43], v[80:83], v[226:229], v[40:43]
	v_mfma_f32_16x16x32_bf16 v[36:39], v[174:177], v[222:225], v[36:39]
	v_mfma_f32_16x16x32_bf16 v[36:39], v[182:185], v[226:229], v[36:39]
	v_mfma_f32_16x16x32_bf16 v[32:35], v[186:189], v[222:225], v[32:35]
	v_mfma_f32_16x16x32_bf16 v[32:35], v[210:213], v[226:229], v[32:35]
	v_mfma_f32_16x16x32_bf16 v[28:31], v[68:71], v[230:233], v[28:31]
	v_mfma_f32_16x16x32_bf16 v[28:31], v[72:75], v[234:237], v[28:31]
	v_mfma_f32_16x16x32_bf16 v[24:27], v[76:79], v[230:233], v[24:27]
	v_mfma_f32_16x16x32_bf16 v[24:27], v[80:83], v[234:237], v[24:27]
	v_mfma_f32_16x16x32_bf16 v[20:23], v[174:177], v[230:233], v[20:23]
	v_mfma_f32_16x16x32_bf16 v[20:23], v[182:185], v[234:237], v[20:23]
	v_mfma_f32_16x16x32_bf16 v[16:19], v[186:189], v[230:233], v[16:19]
	v_mfma_f32_16x16x32_bf16 v[16:19], v[210:213], v[234:237], v[16:19]
	v_mfma_f32_16x16x32_bf16 v[12:15], v[68:71], v[238:241], v[12:15]
	v_mfma_f32_16x16x32_bf16 v[12:15], v[72:75], v[242:245], v[12:15]
	v_mfma_f32_16x16x32_bf16 v[8:11], v[76:79], v[238:241], v[8:11]
	v_mfma_f32_16x16x32_bf16 v[8:11], v[80:83], v[242:245], v[8:11]
	v_mfma_f32_16x16x32_bf16 v[4:7], v[174:177], v[238:241], v[4:7]
	v_mfma_f32_16x16x32_bf16 v[4:7], v[182:185], v[242:245], v[4:7]
	v_mfma_f32_16x16x32_bf16 v[0:3], v[186:189], v[238:241], v[0:3]
	v_mfma_f32_16x16x32_bf16 v[0:3], v[210:213], v[242:245], v[0:3]
	s_setprio 0
	s_barrier
	s_add_i32 s56, s56, 2
	s_add_u32 s0, s0, 0x100
	s_addc_u32 s1, s1, 0
	s_add_u32 s54, s54, 0x100
	s_addc_u32 s55, s55, 0
	s_cmp_gt_u32 s56, 13
	s_cbranch_scc0 .LBB0_327
	s_and_b64 vcc, exec, s[22:23]
	s_cbranch_vccz .LBB0_330
	s_barrier

; #define PG8_STAGE(bufoff, gbase, voff) do { _Pragma("unroll") for (int _i = 0; _i < 2; ++_i) \
;         __builtin_amdgcn_global_load_lds((const unsigned*)((const char*)(gbase) + (voff)[_i]), (PG8_LAS unsigned*)(lds + (bufoff) + ldsw + _i * 8192), 16, 0, 0); } while (0)
; #define PG8_LDA(dst, b, h) do { _Pragma("unroll") for (int m = 0; m < 4; ++m) _Pragma("unroll") for (int k = 0; k < 2; ++k) dst[m][k] = *(const PG8_LAS bf16x8*)(lds + PG8_SA(b, h) + aoff + m * 2048 + k * 1024); } while (0)
; #define PG8_LDB(dst, b, h) do { _Pragma("unroll") for (int n = 0; n < 2; ++n) _Pragma("unroll") for (int k = 0; k < 2; ++k) dst[n][k] = *(const PG8_LAS bf16x8*)(lds + PG8_SB(b, h) + boff + n * 2048 + k * 1024); } while (0)
; #define PG8_MMA(ai, bj, At, Bt) do { __builtin_amdgcn_s_setprio(1); _Pragma("unroll") for (int m = 0; m < 4; ++m) _Pragma("unroll") for (int n = 0; n < 2; ++n) _Pragma("unroll") for (int k = 0; k < 2; ++k) \
;         acc[ai][bj][m][n] = __builtin_amdgcn_mfma_f32_16x16x32_bf16(Bt[n][k], At[m][k], acc[ai][bj][m][n], 0, 0, 0); __builtin_amdgcn_s_setprio(0); } while (0)
; #define PG8_WAIT_V(n) asm volatile("s_waitcnt vmcnt(" #n ")" ::: "memory")
; #define PG8_WAIT_L(n) asm volatile("s_waitcnt lgkmcnt(" #n ")" ::: "memory")
; #define PG8_BAR __builtin_amdgcn_s_barrier()
; template <class Epi, class Sched, bool ALIGN_EPI = false, bool SP2 = false>
; __device__ __forceinline__ void gemm_phase(PG8_LAS unsigned char* lds, const Gemm g, const Sched& S, const Epi& E) {
;     ...
;             const char* a1 = cA + (size_t)(t + 1) * kstep;
;             const char* a2 = last ? nA : cA + (size_t)(t + 2) * kstep; const char* b2 = last ? nB : cB + (size_t)(t + 2) * kstep;
;             const char* a3 = a2 + kstep; const char* b3 = b2 + kstep;
;             if (last && has_next) S.a_ready(nxt);
;             if constexpr (SP2) {
;             PG8_LDB(B0, 0, 0); PG8_LDB(B1, 0, 1); PG8_SCHED; PG8_LDA(At, 0, 0); PG8_STAGE(PG8_SA(1, 1), a1 + hstep, voffA);
;             PG8_WAIT_V(8); PG8_WAIT_L(0); PG8_BAR; PG8_MMA(0, 0, At, B0); PG8_MMA(0, 1, At, B1); PG8_BAR; PG8_SCHED;
;             PG8_LDA(At, 0, 1); PG8_STAGE(PG8_SB(0, 0), b2, voffB); PG8_STAGE(PG8_SB(0, 1), b2 + hstep, voffB); PG8_STAGE(PG8_SA(0, 0), a2, voffA);
;             PG8_WAIT_V(8); PG8_WAIT_L(0); PG8_BAR; PG8_MMA(1, 0, At, B0); PG8_MMA(1, 1, At, B1); PG8_BAR; PG8_SCHED;
.Lup_peel:
	ds_read_b128 v[140:143], v254
	ds_read_b128 v[168:171], v254 offset:1024
	ds_read_b128 v[172:175], v254 offset:2048
	ds_read_b128 v[176:179], v254 offset:3072
	ds_read_b128 v[180:183], v254 offset:16384
	ds_read_b128 v[184:187], v254 offset:17408
	ds_read_b128 v[188:191], v254 offset:18432
	ds_read_b128 v[210:213], v254 offset:19456
	s_add_u32 s16, s14, 0xfffc0080
	s_addc_u32 s17, s15, -1
	s_cmp_eq_u32 s53, 12
	s_cselect_b32 s19, s7, s17
	s_cselect_b32 s18, s49, s16
	s_cselect_b32 s17, s5, s52
	s_cselect_b32 s16, s50, s51
	s_mov_b32 m0, s43
	ds_read_b128 v[214:217], v165
	ds_read_b128 v[218:221], v165 offset:1024
	ds_read_b128 v[222:225], v165 offset:2048
	ds_read_b128 v[226:229], v165 offset:3072
	ds_read_b128 v[230:233], v165 offset:4096
	ds_read_b128 v[234:237], v165 offset:5120
	ds_read_b128 v[238:241], v165 offset:6144
	ds_read_b128 v[242:245], v165 offset:7168
	global_load_lds_dwordx4 v136, s[14:15]
	s_mov_b32 m0, s44
	s_nop 0
	global_load_lds_dwordx4 v138, s[14:15]
	s_waitcnt vmcnt(8)
	s_waitcnt lgkmcnt(0)
	s_barrier
	s_setprio 1
	v_mfma_f32_16x16x32_bf16 v[124:127], v[140:143], v[214:217], 0
	v_mfma_f32_16x16x32_bf16 v[124:127], v[168:171], v[218:221], v[124:127]
	v_mfma_f32_16x16x32_bf16 v[116:119], v[172:175], v[214:217], 0
	v_mfma_f32_16x16x32_bf16 v[116:119], v[176:179], v[218:221], v[116:119]
	v_mfma_f32_16x16x32_bf16 v[120:123], v[180:183], v[214:217], 0
	v_mfma_f32_16x16x32_bf16 v[120:123], v[184:187], v[218:221], v[120:123]
	v_mfma_f32_16x16x32_bf16 v[112:115], v[188:191], v[214:217], 0
	v_mfma_f32_16x16x32_bf16 v[112:115], v[210:213], v[218:221], v[112:115]
	v_mfma_f32_16x16x32_bf16 v[108:111], v[140:143], v[222:225], 0
	v_mfma_f32_16x16x32_bf16 v[108:111], v[168:171], v[226:229], v[108:111]
	v_mfma_f32_16x16x32_bf16 v[100:103], v[172:175], v[222:225], 0
	v_mfma_f32_16x16x32_bf16 v[100:103], v[176:179], v[226:229], v[100:103]
	v_mfma_f32_16x16x32_bf16 v[104:107], v[180:183], v[222:225], 0
	v_mfma_f32_16x16x32_bf16 v[104:107], v[184:187], v[226:229], v[104:107]
	v_mfma_f32_16x16x32_bf16 v[96:99], v[188:191], v[222:225], 0
	v_mfma_f32_16x16x32_bf16 v[96:99], v[210:213], v[226:229], v[96:99]
	v_mfma_f32_16x16x32_bf16 v[92:95], v[140:143], v[230:233], 0
	v_mfma_f32_16x16x32_bf16 v[92:95], v[168:171], v[234:237], v[92:95]
	v_mfma_f32_16x16x32_bf16 v[84:87], v[172:175], v[230:233], 0
	v_mfma_f32_16x16x32_bf16 v[84:87], v[176:179], v[234:237], v[84:87]
	v_mfma_f32_16x16x32_bf16 v[88:91], v[180:183], v[230:233], 0
	v_mfma_f32_16x16x32_bf16 v[88:91], v[184:187], v[234:237], v[88:91]
	v_mfma_f32_16x16x32_bf16 v[80:83], v[188:191], v[230:233], 0
	v_mfma_f32_16x16x32_bf16 v[80:83], v[210:213], v[234:237], v[80:83]
	v_mfma_f32_16x16x32_bf16 v[76:79], v[140:143], v[238:241], 0
	v_mfma_f32_16x16x32_bf16 v[76:79], v[168:171], v[242:245], v[76:79]
	v_mfma_f32_16x16x32_bf16 v[68:71], v[172:175], v[238:241], 0
	v_mfma_f32_16x16x32_bf16 v[68:71], v[176:179], v[242:245], v[68:71]
	v_mfma_f32_16x16x32_bf16 v[72:75], v[180:183], v[238:241], 0
	v_mfma_f32_16x16x32_bf16 v[72:75], v[184:187], v[242:245], v[72:75]
	v_mfma_f32_16x16x32_bf16 v[64:67], v[188:191], v[238:241], 0
	v_mfma_f32_16x16x32_bf16 v[64:67], v[210:213], v[242:245], v[64:67]
	s_setprio 0
	s_barrier
	s_mov_b32 m0, s27
	s_add_u32 s54, s16, 0x40000
	s_addc_u32 s55, s17, 0
	ds_read_b128 v[214:217], v165 offset:16384
	ds_read_b128 v[218:221], v165 offset:17408
	ds_read_b128 v[222:225], v165 offset:18432
	ds_read_b128 v[226:229], v165 offset:19456
	ds_read_b128 v[230:233], v165 offset:20480
	ds_read_b128 v[234:237], v165 offset:21504
	ds_read_b128 v[238:241], v165 offset:22528
	ds_read_b128 v[242:245], v165 offset:23552
	global_load_lds_dwordx4 v132, s[16:17]
	s_mov_b32 m0, s28
	s_nop 0
	global_load_lds_dwordx4 v128, s[16:17]
	s_mov_b32 m0, s29
	s_nop 0
	global_load_lds_dwordx4 v132, s[54:55]
	s_mov_b32 m0, s30
	s_nop 0
	global_load_lds_dwordx4 v128, s[54:55]
	s_mov_b32 m0, s22
	s_nop 0
	global_load_lds_dwordx4 v134, s[18:19]
	s_mov_b32 m0, s31
	s_nop 0
	global_load_lds_dwordx4 v130, s[18:19]
	s_waitcnt vmcnt(8)
	s_waitcnt lgkmcnt(0)
	s_barrier
	s_setprio 1
	v_mfma_f32_16x16x32_bf16 v[60:63], v[140:143], v[214:217], 0
	v_mfma_f32_16x16x32_bf16 v[60:63], v[168:171], v[218:221], v[60:63]
	v_mfma_f32_16x16x32_bf16 v[52:55], v[172:175], v[214:217], 0
	v_mfma_f32_16x16x32_bf16 v[52:55], v[176:179], v[218:221], v[52:55]
	v_mfma_f32_16x16x32_bf16 v[56:59], v[180:183], v[214:217], 0
	v_mfma_f32_16x16x32_bf16 v[56:59], v[184:187], v[218:221], v[56:59]
	v_mfma_f32_16x16x32_bf16 v[48:51], v[188:191], v[214:217], 0
	v_mfma_f32_16x16x32_bf16 v[48:51], v[210:213], v[218:221], v[48:51]
	v_mfma_f32_16x16x32_bf16 v[44:47], v[140:143], v[222:225], 0
	v_mfma_f32_16x16x32_bf16 v[44:47], v[168:171], v[226:229], v[44:47]
	v_mfma_f32_16x16x32_bf16 v[36:39], v[172:175], v[222:225], 0
	v_mfma_f32_16x16x32_bf16 v[36:39], v[176:179], v[226:229], v[36:39]
	v_mfma_f32_16x16x32_bf16 v[40:43], v[180:183], v[222:225], 0
	v_mfma_f32_16x16x32_bf16 v[40:43], v[184:187], v[226:229], v[40:43]
	v_mfma_f32_16x16x32_bf16 v[32:35], v[188:191], v[222:225], 0
	v_mfma_f32_16x16x32_bf16 v[32:35], v[210:213], v[226:229], v[32:35]
	v_mfma_f32_16x16x32_bf16 v[28:31], v[140:143], v[230:233], 0
	v_mfma_f32_16x16x32_bf16 v[28:31], v[168:171], v[234:237], v[28:31]
	v_mfma_f32_16x16x32_bf16 v[20:23], v[172:175], v[230:233], 0
	v_mfma_f32_16x16x32_bf16 v[20:23], v[176:179], v[234:237], v[20:23]
	v_mfma_f32_16x16x32_bf16 v[24:27], v[180:183], v[230:233], 0
	v_mfma_f32_16x16x32_bf16 v[24:27], v[184:187], v[234:237], v[24:27]
	v_mfma_f32_16x16x32_bf16 v[16:19], v[188:191], v[230:233], 0
	v_mfma_f32_16x16x32_bf16 v[16:19], v[210:213], v[234:237], v[16:19]
	v_mfma_f32_16x16x32_bf16 v[12:15], v[140:143], v[238:241], 0
	v_mfma_f32_16x16x32_bf16 v[12:15], v[168:171], v[242:245], v[12:15]
	v_mfma_f32_16x16x32_bf16 v[4:7], v[172:175], v[238:241], 0
	v_mfma_f32_16x16x32_bf16 v[4:7], v[176:179], v[242:245], v[4:7]
	v_mfma_f32_16x16x32_bf16 v[8:11], v[180:183], v[238:241], 0
	v_mfma_f32_16x16x32_bf16 v[8:11], v[184:187], v[242:245], v[8:11]
	v_mfma_f32_16x16x32_bf16 v[0:3], v[188:191], v[238:241], 0
	v_mfma_f32_16x16x32_bf16 v[0:3], v[210:213], v[242:245], v[0:3]
	s_setprio 0
	s_barrier
; #define PG8_STAGE(bufoff, gbase, voff) do { _Pragma("unroll") for (int _i = 0; _i < 2; ++_i) \
;         __builtin_amdgcn_global_load_lds((const unsigned*)((const char*)(gbase) + (voff)[_i]), (PG8_LAS unsigned*)(lds + (bufoff) + ldsw + _i * 8192), 16, 0, 0); } while (0)
; #define PG8_LDA(dst, b, h) do { _Pragma("unroll") for (int m = 0; m < 4; ++m) _Pragma("unroll") for (int k = 0; k < 2; ++k) dst[m][k] = *(const PG8_LAS bf16x8*)(lds + PG8_SA(b, h) + aoff + m * 2048 + k * 1024); } while (0)
; #define PG8_LDB(dst, b, h) do { _Pragma("unroll") for (int n = 0; n < 2; ++n) _Pragma("unroll") for (int k = 0; k < 2; ++k) dst[n][k] = *(const PG8_LAS bf16x8*)(lds + PG8_SB(b, h) + boff + n * 2048 + k * 1024); } while (0)
; #define PG8_MMA(ai, bj, At, Bt) do { __builtin_amdgcn_s_setprio(1); _Pragma("unroll") for (int m = 0; m < 4; ++m) _Pragma("unroll") for (int n = 0; n < 2; ++n) _Pragma("unroll") for (int k = 0; k < 2; ++k) \
;         acc[ai][bj][m][n] = __builtin_amdgcn_mfma_f32_16x16x32_bf16(Bt[n][k], At[m][k], acc[ai][bj][m][n], 0, 0, 0); __builtin_amdgcn_s_setprio(0); } while (0)
; #define PG8_WAIT_V(n) asm volatile("s_waitcnt vmcnt(" #n ")" ::: "memory")
; #define PG8_WAIT_L(n) asm volatile("s_waitcnt lgkmcnt(" #n ")" ::: "memory")
; #define PG8_BAR __builtin_amdgcn_s_barrier()
; #define PG8_SCHED __builtin_amdgcn_sched_barrier(0)
; template <class Epi, class Sched, bool ALIGN_EPI = false, bool SP2 = false>
; __device__ __forceinline__ void gemm_phase(PG8_LAS unsigned char* lds, const Gemm g, const Sched& S, const Epi& E) {
;     ...
;         for (int t = 0; t < nt; t += 2) {
;     ...
;             PG8_LDB(B0, 1, 0); PG8_LDB(B1, 1, 1); PG8_SCHED; PG8_LDA(At, 1, 0); PG8_STAGE(PG8_SA(0, 1), a2 + hstep, voffA);
;             PG8_WAIT_V(8); PG8_WAIT_L(0); PG8_BAR; PG8_MMA(0, 0, At, B0); PG8_MMA(0, 1, At, B1); PG8_BAR; PG8_SCHED;
;             PG8_LDA(At, 1, 1); PG8_STAGE(PG8_SB(1, 0), b3, voffB); PG8_STAGE(PG8_SB(1, 1), b3 + hstep, voffB); PG8_STAGE(PG8_SA(1, 0), a3, voffA);
;             PG8_WAIT_V(8); PG8_WAIT_L(0); PG8_BAR; PG8_MMA(1, 0, At, B0); PG8_MMA(1, 1, At, B1); PG8_BAR; PG8_SCHED;
	ds_read_b128 v[140:143], v254 offset:32768
	ds_read_b128 v[168:171], v254 offset:33792
	ds_read_b128 v[172:175], v254 offset:34816
	ds_read_b128 v[176:179], v254 offset:35840
	ds_read_b128 v[180:183], v254 offset:49152
	ds_read_b128 v[184:187], v254 offset:50176
	ds_read_b128 v[188:191], v254 offset:51200
	ds_read_b128 v[210:213], v254 offset:52224
	s_add_u32 s18, s18, 0x40000
	s_addc_u32 s19, s19, 0
	s_mov_b32 m0, s33
	ds_read_b128 v[214:217], v165 offset:32768
	ds_read_b128 v[218:221], v165 offset:33792
	ds_read_b128 v[222:225], v165 offset:34816
	ds_read_b128 v[226:229], v165 offset:35840
	ds_read_b128 v[230:233], v165 offset:36864
	ds_read_b128 v[234:237], v165 offset:37888
	ds_read_b128 v[238:241], v165 offset:38912
	ds_read_b128 v[242:245], v165 offset:39936
	global_load_lds_dwordx4 v134, s[18:19]
	s_mov_b32 m0, s34
	s_nop 0
	global_load_lds_dwordx4 v130, s[18:19]
	s_waitcnt vmcnt(8)
	s_waitcnt lgkmcnt(0)
	s_barrier
	s_setprio 1
	v_mfma_f32_16x16x32_bf16 v[124:127], v[140:143], v[214:217], v[124:127]
	v_mfma_f32_16x16x32_bf16 v[124:127], v[168:171], v[218:221], v[124:127]
	v_mfma_f32_16x16x32_bf16 v[116:119], v[172:175], v[214:217], v[116:119]
	v_mfma_f32_16x16x32_bf16 v[116:119], v[176:179], v[218:221], v[116:119]
	v_mfma_f32_16x16x32_bf16 v[120:123], v[180:183], v[214:217], v[120:123]
	v_mfma_f32_16x16x32_bf16 v[120:123], v[184:187], v[218:221], v[120:123]
	v_mfma_f32_16x16x32_bf16 v[112:115], v[188:191], v[214:217], v[112:115]
	v_mfma_f32_16x16x32_bf16 v[112:115], v[210:213], v[218:221], v[112:115]
	v_mfma_f32_16x16x32_bf16 v[108:111], v[140:143], v[222:225], v[108:111]
	v_mfma_f32_16x16x32_bf16 v[108:111], v[168:171], v[226:229], v[108:111]
	v_mfma_f32_16x16x32_bf16 v[100:103], v[172:175], v[222:225], v[100:103]
	v_mfma_f32_16x16x32_bf16 v[100:103], v[176:179], v[226:229], v[100:103]
	v_mfma_f32_16x16x32_bf16 v[104:107], v[180:183], v[222:225], v[104:107]
	v_mfma_f32_16x16x32_bf16 v[104:107], v[184:187], v[226:229], v[104:107]
	v_mfma_f32_16x16x32_bf16 v[96:99], v[188:191], v[222:225], v[96:99]
	v_mfma_f32_16x16x32_bf16 v[96:99], v[210:213], v[226:229], v[96:99]
	v_mfma_f32_16x16x32_bf16 v[92:95], v[140:143], v[230:233], v[92:95]
	v_mfma_f32_16x16x32_bf16 v[92:95], v[168:171], v[234:237], v[92:95]
	v_mfma_f32_16x16x32_bf16 v[84:87], v[172:175], v[230:233], v[84:87]
	v_mfma_f32_16x16x32_bf16 v[84:87], v[176:179], v[234:237], v[84:87]
	v_mfma_f32_16x16x32_bf16 v[88:91], v[180:183], v[230:233], v[88:91]
	v_mfma_f32_16x16x32_bf16 v[88:91], v[184:187], v[234:237], v[88:91]
	v_mfma_f32_16x16x32_bf16 v[80:83], v[188:191], v[230:233], v[80:83]
	v_mfma_f32_16x16x32_bf16 v[80:83], v[210:213], v[234:237], v[80:83]
	v_mfma_f32_16x16x32_bf16 v[76:79], v[140:143], v[238:241], v[76:79]
	v_mfma_f32_16x16x32_bf16 v[76:79], v[168:171], v[242:245], v[76:79]
	v_mfma_f32_16x16x32_bf16 v[68:71], v[172:175], v[238:241], v[68:71]
	v_mfma_f32_16x16x32_bf16 v[68:71], v[176:179], v[242:245], v[68:71]
	v_mfma_f32_16x16x32_bf16 v[72:75], v[180:183], v[238:241], v[72:75]
	v_mfma_f32_16x16x32_bf16 v[72:75], v[184:187], v[242:245], v[72:75]
	v_mfma_f32_16x16x32_bf16 v[64:67], v[188:191], v[238:241], v[64:67]
	v_mfma_f32_16x16x32_bf16 v[64:67], v[210:213], v[242:245], v[64:67]
	s_setprio 0
	s_barrier
	s_mov_b32 m0, s37
	s_add_u32 s16, s16, 0x40080
	s_addc_u32 s17, s17, 0
	ds_read_b128 v[214:217], v165 offset:49152
	ds_read_b128 v[218:221], v165 offset:50176
	ds_read_b128 v[222:225], v165 offset:51200
	ds_read_b128 v[226:229], v165 offset:52224
	ds_read_b128 v[230:233], v165 offset:53248
	ds_read_b128 v[234:237], v165 offset:54272
	ds_read_b128 v[238:241], v165 offset:55296
	ds_read_b128 v[242:245], v165 offset:56320
	s_add_u32 s98, s16, 0xfffc0000
	s_addc_u32 s99, s17, -1
	global_load_lds_dwordx4 v132, s[98:99]
	s_mov_b32 m0, s38
	s_nop 0
	global_load_lds_dwordx4 v128, s[98:99]
	s_mov_b32 m0, s41
	s_nop 0
	global_load_lds_dwordx4 v132, s[16:17]
	s_mov_b32 m0, s42
	s_nop 0
	global_load_lds_dwordx4 v128, s[16:17]
	s_mov_b32 m0, s39
	s_nop 0
	s_add_u32 s100, s18, 0xfffc0080
	s_addc_u32 s101, s19, -1
	global_load_lds_dwordx4 v134, s[100:101]
	s_mov_b32 m0, s40
	s_nop 0
	global_load_lds_dwordx4 v130, s[100:101]
	s_waitcnt vmcnt(8)
	s_waitcnt lgkmcnt(0)
	s_barrier
	s_setprio 1
	v_mfma_f32_16x16x32_bf16 v[60:63], v[140:143], v[214:217], v[60:63]
	v_mfma_f32_16x16x32_bf16 v[60:63], v[168:171], v[218:221], v[60:63]
	v_mfma_f32_16x16x32_bf16 v[52:55], v[172:175], v[214:217], v[52:55]
	v_mfma_f32_16x16x32_bf16 v[52:55], v[176:179], v[218:221], v[52:55]
	v_mfma_f32_16x16x32_bf16 v[56:59], v[180:183], v[214:217], v[56:59]
	v_mfma_f32_16x16x32_bf16 v[56:59], v[184:187], v[218:221], v[56:59]
	v_mfma_f32_16x16x32_bf16 v[48:51], v[188:191], v[214:217], v[48:51]
	v_mfma_f32_16x16x32_bf16 v[48:51], v[210:213], v[218:221], v[48:51]
	v_mfma_f32_16x16x32_bf16 v[44:47], v[140:143], v[222:225], v[44:47]
	v_mfma_f32_16x16x32_bf16 v[44:47], v[168:171], v[226:229], v[44:47]
	v_mfma_f32_16x16x32_bf16 v[36:39], v[172:175], v[222:225], v[36:39]
	v_mfma_f32_16x16x32_bf16 v[36:39], v[176:179], v[226:229], v[36:39]
	v_mfma_f32_16x16x32_bf16 v[40:43], v[180:183], v[222:225], v[40:43]
	v_mfma_f32_16x16x32_bf16 v[40:43], v[184:187], v[226:229], v[40:43]
	v_mfma_f32_16x16x32_bf16 v[32:35], v[188:191], v[222:225], v[32:35]
	v_mfma_f32_16x16x32_bf16 v[32:35], v[210:213], v[226:229], v[32:35]
	v_mfma_f32_16x16x32_bf16 v[28:31], v[140:143], v[230:233], v[28:31]
	v_mfma_f32_16x16x32_bf16 v[28:31], v[168:171], v[234:237], v[28:31]
	v_mfma_f32_16x16x32_bf16 v[20:23], v[172:175], v[230:233], v[20:23]
	v_mfma_f32_16x16x32_bf16 v[20:23], v[176:179], v[234:237], v[20:23]
	v_mfma_f32_16x16x32_bf16 v[24:27], v[180:183], v[230:233], v[24:27]
	v_mfma_f32_16x16x32_bf16 v[24:27], v[184:187], v[234:237], v[24:27]
	v_mfma_f32_16x16x32_bf16 v[16:19], v[188:191], v[230:233], v[16:19]
	v_mfma_f32_16x16x32_bf16 v[16:19], v[210:213], v[234:237], v[16:19]
	v_mfma_f32_16x16x32_bf16 v[12:15], v[140:143], v[238:241], v[12:15]
	v_mfma_f32_16x16x32_bf16 v[12:15], v[168:171], v[242:245], v[12:15]
	v_mfma_f32_16x16x32_bf16 v[4:7], v[172:175], v[238:241], v[4:7]
	v_mfma_f32_16x16x32_bf16 v[4:7], v[176:179], v[242:245], v[4:7]
	v_mfma_f32_16x16x32_bf16 v[8:11], v[180:183], v[238:241], v[8:11]
	v_mfma_f32_16x16x32_bf16 v[8:11], v[184:187], v[242:245], v[8:11]
	v_mfma_f32_16x16x32_bf16 v[0:3], v[188:191], v[238:241], v[0:3]
	v_mfma_f32_16x16x32_bf16 v[0:3], v[210:213], v[242:245], v[0:3]
	s_setprio 0
	s_barrier
	s_add_i32 s53, s53, 2
	s_add_u32 s14, s14, 0x100
	s_addc_u32 s15, s15, 0
	s_add_u32 s51, s51, 0x100
	s_addc_u32 s52, s52, 0
	s_cmp_gt_u32 s53, 13
; #define PG8_STAGE(bufoff, gbase, voff) do { _Pragma("unroll") for (int _i = 0; _i < 2; ++_i) \
;         __builtin_amdgcn_global_load_lds((const unsigned*)((const char*)(gbase) + (voff)[_i]), (PG8_LAS unsigned*)(lds + (bufoff) + ldsw + _i * 8192), 16, 0, 0); } while (0)
; #define PG8_LDA(dst, b, h) do { _Pragma("unroll") for (int m = 0; m < 4; ++m) _Pragma("unroll") for (int k = 0; k < 2; ++k) dst[m][k] = *(const PG8_LAS bf16x8*)(lds + PG8_SA(b, h) + aoff + m * 2048 + k * 1024); } while (0)
; #define PG8_LDB(dst, b, h) do { _Pragma("unroll") for (int n = 0; n < 2; ++n) _Pragma("unroll") for (int k = 0; k < 2; ++k) dst[n][k] = *(const PG8_LAS bf16x8*)(lds + PG8_SB(b, h) + boff + n * 2048 + k * 1024); } while (0)
; #define PG8_MMA(ai, bj, At, Bt) do { __builtin_amdgcn_s_setprio(1); _Pragma("unroll") for (int m = 0; m < 4; ++m) _Pragma("unroll") for (int n = 0; n < 2; ++n) _Pragma("unroll") for (int k = 0; k < 2; ++k) \
;         acc[ai][bj][m][n] = __builtin_amdgcn_mfma_f32_16x16x32_bf16(Bt[n][k], At[m][k], acc[ai][bj][m][n], 0, 0, 0); __builtin_amdgcn_s_setprio(0); } while (0)
; #define PG8_WAIT_V(n) asm volatile("s_waitcnt vmcnt(" #n ")" ::: "memory")
; #define PG8_WAIT_L(n) asm volatile("s_waitcnt lgkmcnt(" #n ")" ::: "memory")
; #define PG8_BAR __builtin_amdgcn_s_barrier()
; template <class Epi, class Sched, bool ALIGN_EPI = false, bool SP2 = false>
; __device__ __forceinline__ void gemm_phase(PG8_LAS unsigned char* lds, const Gemm g, const Sched& S, const Epi& E) {
;     ...
;             const char* a1 = cA + (size_t)(t + 1) * kstep;
;             const char* a2 = last ? nA : cA + (size_t)(t + 2) * kstep; const char* b2 = last ? nB : cB + (size_t)(t + 2) * kstep;
;             const char* a3 = a2 + kstep; const char* b3 = b2 + kstep;
;             if (last && has_next) S.a_ready(nxt);
;             if constexpr (SP2) {
;             PG8_LDB(B0, 0, 0); PG8_LDB(B1, 0, 1); PG8_SCHED; PG8_LDA(At, 0, 0); PG8_STAGE(PG8_SA(1, 1), a1 + hstep, voffA);
;             PG8_WAIT_V(8); PG8_WAIT_L(0); PG8_BAR; PG8_MMA(0, 0, At, B0); PG8_MMA(0, 1, At, B1); PG8_BAR; PG8_SCHED;
;             PG8_LDA(At, 0, 1); PG8_STAGE(PG8_SB(0, 0), b2, voffB); PG8_STAGE(PG8_SB(0, 1), b2 + hstep, voffB); PG8_STAGE(PG8_SA(0, 0), a2, voffA);
;             PG8_WAIT_V(8); PG8_WAIT_L(0); PG8_BAR; PG8_MMA(1, 0, At, B0); PG8_MMA(1, 1, At, B1); PG8_BAR; PG8_SCHED;
.LBB0_446:
	ds_read_b128 v[140:143], v254
	ds_read_b128 v[168:171], v254 offset:1024
	ds_read_b128 v[172:175], v254 offset:2048
	ds_read_b128 v[176:179], v254 offset:3072
	ds_read_b128 v[180:183], v254 offset:16384
	ds_read_b128 v[184:187], v254 offset:17408
	ds_read_b128 v[188:191], v254 offset:18432
	ds_read_b128 v[210:213], v254 offset:19456
	s_add_u32 s16, s14, 0xfffc0080
	s_addc_u32 s17, s15, -1
	s_cmp_eq_u32 s53, 12
	s_cselect_b32 s19, s7, s17
	s_cselect_b32 s18, s49, s16
	s_cselect_b32 s17, s5, s52
	s_cselect_b32 s16, s50, s51
	s_mov_b32 m0, s43
	ds_read_b128 v[214:217], v165
	ds_read_b128 v[218:221], v165 offset:1024
	ds_read_b128 v[222:225], v165 offset:2048
	ds_read_b128 v[226:229], v165 offset:3072
	ds_read_b128 v[230:233], v165 offset:4096
	ds_read_b128 v[234:237], v165 offset:5120
	ds_read_b128 v[238:241], v165 offset:6144
	ds_read_b128 v[242:245], v165 offset:7168
	global_load_lds_dwordx4 v136, s[14:15]
	s_mov_b32 m0, s44
	s_nop 0
	global_load_lds_dwordx4 v138, s[14:15]
	s_waitcnt vmcnt(8)
	s_waitcnt lgkmcnt(0)
	s_barrier
	s_setprio 1
	v_mfma_f32_16x16x32_bf16 v[124:127], v[140:143], v[214:217], v[124:127]
	v_mfma_f32_16x16x32_bf16 v[124:127], v[168:171], v[218:221], v[124:127]
	v_mfma_f32_16x16x32_bf16 v[116:119], v[172:175], v[214:217], v[116:119]
	v_mfma_f32_16x16x32_bf16 v[116:119], v[176:179], v[218:221], v[116:119]
	v_mfma_f32_16x16x32_bf16 v[120:123], v[180:183], v[214:217], v[120:123]
	v_mfma_f32_16x16x32_bf16 v[120:123], v[184:187], v[218:221], v[120:123]
	v_mfma_f32_16x16x32_bf16 v[112:115], v[188:191], v[214:217], v[112:115]
	v_mfma_f32_16x16x32_bf16 v[112:115], v[210:213], v[218:221], v[112:115]
	v_mfma_f32_16x16x32_bf16 v[108:111], v[140:143], v[222:225], v[108:111]
	v_mfma_f32_16x16x32_bf16 v[108:111], v[168:171], v[226:229], v[108:111]
	v_mfma_f32_16x16x32_bf16 v[100:103], v[172:175], v[222:225], v[100:103]
	v_mfma_f32_16x16x32_bf16 v[100:103], v[176:179], v[226:229], v[100:103]
	v_mfma_f32_16x16x32_bf16 v[104:107], v[180:183], v[222:225], v[104:107]
	v_mfma_f32_16x16x32_bf16 v[104:107], v[184:187], v[226:229], v[104:107]
	v_mfma_f32_16x16x32_bf16 v[96:99], v[188:191], v[222:225], v[96:99]
	v_mfma_f32_16x16x32_bf16 v[96:99], v[210:213], v[226:229], v[96:99]
	v_mfma_f32_16x16x32_bf16 v[92:95], v[140:143], v[230:233], v[92:95]
	v_mfma_f32_16x16x32_bf16 v[92:95], v[168:171], v[234:237], v[92:95]
	v_mfma_f32_16x16x32_bf16 v[84:87], v[172:175], v[230:233], v[84:87]
	v_mfma_f32_16x16x32_bf16 v[84:87], v[176:179], v[234:237], v[84:87]
	v_mfma_f32_16x16x32_bf16 v[88:91], v[180:183], v[230:233], v[88:91]
	v_mfma_f32_16x16x32_bf16 v[88:91], v[184:187], v[234:237], v[88:91]
	v_mfma_f32_16x16x32_bf16 v[80:83], v[188:191], v[230:233], v[80:83]
	v_mfma_f32_16x16x32_bf16 v[80:83], v[210:213], v[234:237], v[80:83]
	v_mfma_f32_16x16x32_bf16 v[76:79], v[140:143], v[238:241], v[76:79]
	v_mfma_f32_16x16x32_bf16 v[76:79], v[168:171], v[242:245], v[76:79]
	v_mfma_f32_16x16x32_bf16 v[68:71], v[172:175], v[238:241], v[68:71]
	v_mfma_f32_16x16x32_bf16 v[68:71], v[176:179], v[242:245], v[68:71]
	v_mfma_f32_16x16x32_bf16 v[72:75], v[180:183], v[238:241], v[72:75]
	v_mfma_f32_16x16x32_bf16 v[72:75], v[184:187], v[242:245], v[72:75]
	v_mfma_f32_16x16x32_bf16 v[64:67], v[188:191], v[238:241], v[64:67]
	v_mfma_f32_16x16x32_bf16 v[64:67], v[210:213], v[242:245], v[64:67]
	s_setprio 0
	s_barrier
	s_mov_b32 m0, s27
	s_add_u32 s54, s16, 0x40000
	s_addc_u32 s55, s17, 0
	ds_read_b128 v[214:217], v165 offset:16384
	ds_read_b128 v[218:221], v165 offset:17408
	ds_read_b128 v[222:225], v165 offset:18432
	ds_read_b128 v[226:229], v165 offset:19456
	ds_read_b128 v[230:233], v165 offset:20480
	ds_read_b128 v[234:237], v165 offset:21504
	ds_read_b128 v[238:241], v165 offset:22528
	ds_read_b128 v[242:245], v165 offset:23552
	global_load_lds_dwordx4 v132, s[16:17]
	s_mov_b32 m0, s28
	s_nop 0
	global_load_lds_dwordx4 v128, s[16:17]
	s_mov_b32 m0, s29
	s_nop 0
	global_load_lds_dwordx4 v132, s[54:55]
	s_mov_b32 m0, s30
	s_nop 0
	global_load_lds_dwordx4 v128, s[54:55]
	s_mov_b32 m0, s22
	s_nop 0
	global_load_lds_dwordx4 v134, s[18:19]
	s_mov_b32 m0, s31
	s_nop 0
	global_load_lds_dwordx4 v130, s[18:19]
	s_waitcnt vmcnt(8)
	s_waitcnt lgkmcnt(0)
	s_barrier
	s_setprio 1
	v_mfma_f32_16x16x32_bf16 v[60:63], v[140:143], v[214:217], v[60:63]
	v_mfma_f32_16x16x32_bf16 v[60:63], v[168:171], v[218:221], v[60:63]
	v_mfma_f32_16x16x32_bf16 v[52:55], v[172:175], v[214:217], v[52:55]
	v_mfma_f32_16x16x32_bf16 v[52:55], v[176:179], v[218:221], v[52:55]
	v_mfma_f32_16x16x32_bf16 v[56:59], v[180:183], v[214:217], v[56:59]
	v_mfma_f32_16x16x32_bf16 v[56:59], v[184:187], v[218:221], v[56:59]
	v_mfma_f32_16x16x32_bf16 v[48:51], v[188:191], v[214:217], v[48:51]
	v_mfma_f32_16x16x32_bf16 v[48:51], v[210:213], v[218:221], v[48:51]
	v_mfma_f32_16x16x32_bf16 v[44:47], v[140:143], v[222:225], v[44:47]
	v_mfma_f32_16x16x32_bf16 v[44:47], v[168:171], v[226:229], v[44:47]
	v_mfma_f32_16x16x32_bf16 v[36:39], v[172:175], v[222:225], v[36:39]
	v_mfma_f32_16x16x32_bf16 v[36:39], v[176:179], v[226:229], v[36:39]
	v_mfma_f32_16x16x32_bf16 v[40:43], v[180:183], v[222:225], v[40:43]
	v_mfma_f32_16x16x32_bf16 v[40:43], v[184:187], v[226:229], v[40:43]
	v_mfma_f32_16x16x32_bf16 v[32:35], v[188:191], v[222:225], v[32:35]
	v_mfma_f32_16x16x32_bf16 v[32:35], v[210:213], v[226:229], v[32:35]
	v_mfma_f32_16x16x32_bf16 v[28:31], v[140:143], v[230:233], v[28:31]
	v_mfma_f32_16x16x32_bf16 v[28:31], v[168:171], v[234:237], v[28:31]
	v_mfma_f32_16x16x32_bf16 v[20:23], v[172:175], v[230:233], v[20:23]
	v_mfma_f32_16x16x32_bf16 v[20:23], v[176:179], v[234:237], v[20:23]
	v_mfma_f32_16x16x32_bf16 v[24:27], v[180:183], v[230:233], v[24:27]
	v_mfma_f32_16x16x32_bf16 v[24:27], v[184:187], v[234:237], v[24:27]
	v_mfma_f32_16x16x32_bf16 v[16:19], v[188:191], v[230:233], v[16:19]
	v_mfma_f32_16x16x32_bf16 v[16:19], v[210:213], v[234:237], v[16:19]
	v_mfma_f32_16x16x32_bf16 v[12:15], v[140:143], v[238:241], v[12:15]
	v_mfma_f32_16x16x32_bf16 v[12:15], v[168:171], v[242:245], v[12:15]
	v_mfma_f32_16x16x32_bf16 v[4:7], v[172:175], v[238:241], v[4:7]
	v_mfma_f32_16x16x32_bf16 v[4:7], v[176:179], v[242:245], v[4:7]
	v_mfma_f32_16x16x32_bf16 v[8:11], v[180:183], v[238:241], v[8:11]
	v_mfma_f32_16x16x32_bf16 v[8:11], v[184:187], v[242:245], v[8:11]
	v_mfma_f32_16x16x32_bf16 v[0:3], v[188:191], v[238:241], v[0:3]
	v_mfma_f32_16x16x32_bf16 v[0:3], v[210:213], v[242:245], v[0:3]
	s_setprio 0
	s_barrier
; #define PG8_STAGE(bufoff, gbase, voff) do { _Pragma("unroll") for (int _i = 0; _i < 2; ++_i) \
;         __builtin_amdgcn_global_load_lds((const unsigned*)((const char*)(gbase) + (voff)[_i]), (PG8_LAS unsigned*)(lds + (bufoff) + ldsw + _i * 8192), 16, 0, 0); } while (0)
; #define PG8_LDA(dst, b, h) do { _Pragma("unroll") for (int m = 0; m < 4; ++m) _Pragma("unroll") for (int k = 0; k < 2; ++k) dst[m][k] = *(const PG8_LAS bf16x8*)(lds + PG8_SA(b, h) + aoff + m * 2048 + k * 1024); } while (0)
; #define PG8_LDB(dst, b, h) do { _Pragma("unroll") for (int n = 0; n < 2; ++n) _Pragma("unroll") for (int k = 0; k < 2; ++k) dst[n][k] = *(const PG8_LAS bf16x8*)(lds + PG8_SB(b, h) + boff + n * 2048 + k * 1024); } while (0)
; #define PG8_MMA(ai, bj, At, Bt) do { __builtin_amdgcn_s_setprio(1); _Pragma("unroll") for (int m = 0; m < 4; ++m) _Pragma("unroll") for (int n = 0; n < 2; ++n) _Pragma("unroll") for (int k = 0; k < 2; ++k) \
;         acc[ai][bj][m][n] = __builtin_amdgcn_mfma_f32_16x16x32_bf16(Bt[n][k], At[m][k], acc[ai][bj][m][n], 0, 0, 0); __builtin_amdgcn_s_setprio(0); } while (0)
; #define PG8_WAIT_V(n) asm volatile("s_waitcnt vmcnt(" #n ")" ::: "memory")
; #define PG8_WAIT_L(n) asm volatile("s_waitcnt lgkmcnt(" #n ")" ::: "memory")
; #define PG8_BAR __builtin_amdgcn_s_barrier()
; #define PG8_SCHED __builtin_amdgcn_sched_barrier(0)
; template <class Epi, class Sched, bool ALIGN_EPI = false, bool SP2 = false>
; __device__ __forceinline__ void gemm_phase(PG8_LAS unsigned char* lds, const Gemm g, const Sched& S, const Epi& E) {
;     ...
;         for (int t = 0; t < nt; t += 2) {
;     ...
;             PG8_LDB(B0, 1, 0); PG8_LDB(B1, 1, 1); PG8_SCHED; PG8_LDA(At, 1, 0); PG8_STAGE(PG8_SA(0, 1), a2 + hstep, voffA);
;             PG8_WAIT_V(8); PG8_WAIT_L(0); PG8_BAR; PG8_MMA(0, 0, At, B0); PG8_MMA(0, 1, At, B1); PG8_BAR; PG8_SCHED;
;             PG8_LDA(At, 1, 1); PG8_STAGE(PG8_SB(1, 0), b3, voffB); PG8_STAGE(PG8_SB(1, 1), b3 + hstep, voffB); PG8_STAGE(PG8_SA(1, 0), a3, voffA);
;             PG8_WAIT_V(8); PG8_WAIT_L(0); PG8_BAR; PG8_MMA(1, 0, At, B0); PG8_MMA(1, 1, At, B1); PG8_BAR; PG8_SCHED;
;     ...
;         if constexpr (ALIGN_EPI) { if (wr == 0) PG8_BAR; }
	ds_read_b128 v[140:143], v254 offset:32768
	ds_read_b128 v[168:171], v254 offset:33792
	ds_read_b128 v[172:175], v254 offset:34816
	ds_read_b128 v[176:179], v254 offset:35840
	ds_read_b128 v[180:183], v254 offset:49152
	ds_read_b128 v[184:187], v254 offset:50176
	ds_read_b128 v[188:191], v254 offset:51200
	ds_read_b128 v[210:213], v254 offset:52224
	s_add_u32 s18, s18, 0x40000
	s_addc_u32 s19, s19, 0
	s_mov_b32 m0, s33
	ds_read_b128 v[214:217], v165 offset:32768
	ds_read_b128 v[218:221], v165 offset:33792
	ds_read_b128 v[222:225], v165 offset:34816
	ds_read_b128 v[226:229], v165 offset:35840
	ds_read_b128 v[230:233], v165 offset:36864
	ds_read_b128 v[234:237], v165 offset:37888
	ds_read_b128 v[238:241], v165 offset:38912
	ds_read_b128 v[242:245], v165 offset:39936
	global_load_lds_dwordx4 v134, s[18:19]
	s_mov_b32 m0, s34
	s_nop 0
	global_load_lds_dwordx4 v130, s[18:19]
	s_waitcnt vmcnt(8)
	s_waitcnt lgkmcnt(0)
	s_barrier
	s_setprio 1
	v_mfma_f32_16x16x32_bf16 v[124:127], v[140:143], v[214:217], v[124:127]
	v_mfma_f32_16x16x32_bf16 v[124:127], v[168:171], v[218:221], v[124:127]
	v_mfma_f32_16x16x32_bf16 v[116:119], v[172:175], v[214:217], v[116:119]
	v_mfma_f32_16x16x32_bf16 v[116:119], v[176:179], v[218:221], v[116:119]
	v_mfma_f32_16x16x32_bf16 v[120:123], v[180:183], v[214:217], v[120:123]
	v_mfma_f32_16x16x32_bf16 v[120:123], v[184:187], v[218:221], v[120:123]
	v_mfma_f32_16x16x32_bf16 v[112:115], v[188:191], v[214:217], v[112:115]
	v_mfma_f32_16x16x32_bf16 v[112:115], v[210:213], v[218:221], v[112:115]
	v_mfma_f32_16x16x32_bf16 v[108:111], v[140:143], v[222:225], v[108:111]
	v_mfma_f32_16x16x32_bf16 v[108:111], v[168:171], v[226:229], v[108:111]
	v_mfma_f32_16x16x32_bf16 v[100:103], v[172:175], v[222:225], v[100:103]
	v_mfma_f32_16x16x32_bf16 v[100:103], v[176:179], v[226:229], v[100:103]
	v_mfma_f32_16x16x32_bf16 v[104:107], v[180:183], v[222:225], v[104:107]
	v_mfma_f32_16x16x32_bf16 v[104:107], v[184:187], v[226:229], v[104:107]
	v_mfma_f32_16x16x32_bf16 v[96:99], v[188:191], v[222:225], v[96:99]
	v_mfma_f32_16x16x32_bf16 v[96:99], v[210:213], v[226:229], v[96:99]
	v_mfma_f32_16x16x32_bf16 v[92:95], v[140:143], v[230:233], v[92:95]
	v_mfma_f32_16x16x32_bf16 v[92:95], v[168:171], v[234:237], v[92:95]
	v_mfma_f32_16x16x32_bf16 v[84:87], v[172:175], v[230:233], v[84:87]
	v_mfma_f32_16x16x32_bf16 v[84:87], v[176:179], v[234:237], v[84:87]
	v_mfma_f32_16x16x32_bf16 v[88:91], v[180:183], v[230:233], v[88:91]
	v_mfma_f32_16x16x32_bf16 v[88:91], v[184:187], v[234:237], v[88:91]
	v_mfma_f32_16x16x32_bf16 v[80:83], v[188:191], v[230:233], v[80:83]
	v_mfma_f32_16x16x32_bf16 v[80:83], v[210:213], v[234:237], v[80:83]
	v_mfma_f32_16x16x32_bf16 v[76:79], v[140:143], v[238:241], v[76:79]
	v_mfma_f32_16x16x32_bf16 v[76:79], v[168:171], v[242:245], v[76:79]
	v_mfma_f32_16x16x32_bf16 v[68:71], v[172:175], v[238:241], v[68:71]
	v_mfma_f32_16x16x32_bf16 v[68:71], v[176:179], v[242:245], v[68:71]
	v_mfma_f32_16x16x32_bf16 v[72:75], v[180:183], v[238:241], v[72:75]
	v_mfma_f32_16x16x32_bf16 v[72:75], v[184:187], v[242:245], v[72:75]
	v_mfma_f32_16x16x32_bf16 v[64:67], v[188:191], v[238:241], v[64:67]
	v_mfma_f32_16x16x32_bf16 v[64:67], v[210:213], v[242:245], v[64:67]
	s_setprio 0
	s_barrier
	s_mov_b32 m0, s37
	s_add_u32 s16, s16, 0x40080
	s_addc_u32 s17, s17, 0
	ds_read_b128 v[214:217], v165 offset:49152
	ds_read_b128 v[218:221], v165 offset:50176
	ds_read_b128 v[222:225], v165 offset:51200
	ds_read_b128 v[226:229], v165 offset:52224
	ds_read_b128 v[230:233], v165 offset:53248
	ds_read_b128 v[234:237], v165 offset:54272
	ds_read_b128 v[238:241], v165 offset:55296
	ds_read_b128 v[242:245], v165 offset:56320
	s_add_u32 s98, s16, 0xfffc0000
	s_addc_u32 s99, s17, -1
	global_load_lds_dwordx4 v132, s[98:99]
	s_mov_b32 m0, s38
	s_nop 0
	global_load_lds_dwordx4 v128, s[98:99]
	s_mov_b32 m0, s41
	s_nop 0
	global_load_lds_dwordx4 v132, s[16:17]
	s_mov_b32 m0, s42
	s_nop 0
	global_load_lds_dwordx4 v128, s[16:17]
	s_mov_b32 m0, s39
	s_nop 0
	s_add_u32 s100, s18, 0xfffc0080
	s_addc_u32 s101, s19, -1
	global_load_lds_dwordx4 v134, s[100:101]
	s_mov_b32 m0, s40
	s_nop 0
	global_load_lds_dwordx4 v130, s[100:101]
	s_waitcnt vmcnt(8)
	s_waitcnt lgkmcnt(0)
	s_barrier
	s_setprio 1
	v_mfma_f32_16x16x32_bf16 v[60:63], v[140:143], v[214:217], v[60:63]
	v_mfma_f32_16x16x32_bf16 v[60:63], v[168:171], v[218:221], v[60:63]
	v_mfma_f32_16x16x32_bf16 v[52:55], v[172:175], v[214:217], v[52:55]
	v_mfma_f32_16x16x32_bf16 v[52:55], v[176:179], v[218:221], v[52:55]
	v_mfma_f32_16x16x32_bf16 v[56:59], v[180:183], v[214:217], v[56:59]
	v_mfma_f32_16x16x32_bf16 v[56:59], v[184:187], v[218:221], v[56:59]
	v_mfma_f32_16x16x32_bf16 v[48:51], v[188:191], v[214:217], v[48:51]
	v_mfma_f32_16x16x32_bf16 v[48:51], v[210:213], v[218:221], v[48:51]
	v_mfma_f32_16x16x32_bf16 v[44:47], v[140:143], v[222:225], v[44:47]
	v_mfma_f32_16x16x32_bf16 v[44:47], v[168:171], v[226:229], v[44:47]
	v_mfma_f32_16x16x32_bf16 v[36:39], v[172:175], v[222:225], v[36:39]
	v_mfma_f32_16x16x32_bf16 v[36:39], v[176:179], v[226:229], v[36:39]
	v_mfma_f32_16x16x32_bf16 v[40:43], v[180:183], v[222:225], v[40:43]
	v_mfma_f32_16x16x32_bf16 v[40:43], v[184:187], v[226:229], v[40:43]
	v_mfma_f32_16x16x32_bf16 v[32:35], v[188:191], v[222:225], v[32:35]
	v_mfma_f32_16x16x32_bf16 v[32:35], v[210:213], v[226:229], v[32:35]
	v_mfma_f32_16x16x32_bf16 v[28:31], v[140:143], v[230:233], v[28:31]
	v_mfma_f32_16x16x32_bf16 v[28:31], v[168:171], v[234:237], v[28:31]
	v_mfma_f32_16x16x32_bf16 v[20:23], v[172:175], v[230:233], v[20:23]
	v_mfma_f32_16x16x32_bf16 v[20:23], v[176:179], v[234:237], v[20:23]
	v_mfma_f32_16x16x32_bf16 v[24:27], v[180:183], v[230:233], v[24:27]
	v_mfma_f32_16x16x32_bf16 v[24:27], v[184:187], v[234:237], v[24:27]
	v_mfma_f32_16x16x32_bf16 v[16:19], v[188:191], v[230:233], v[16:19]
	v_mfma_f32_16x16x32_bf16 v[16:19], v[210:213], v[234:237], v[16:19]
	v_mfma_f32_16x16x32_bf16 v[12:15], v[140:143], v[238:241], v[12:15]
	v_mfma_f32_16x16x32_bf16 v[12:15], v[168:171], v[242:245], v[12:15]
	v_mfma_f32_16x16x32_bf16 v[4:7], v[172:175], v[238:241], v[4:7]
	v_mfma_f32_16x16x32_bf16 v[4:7], v[176:179], v[242:245], v[4:7]
	v_mfma_f32_16x16x32_bf16 v[8:11], v[180:183], v[238:241], v[8:11]
	v_mfma_f32_16x16x32_bf16 v[8:11], v[184:187], v[242:245], v[8:11]
	v_mfma_f32_16x16x32_bf16 v[0:3], v[188:191], v[238:241], v[0:3]
	v_mfma_f32_16x16x32_bf16 v[0:3], v[210:213], v[242:245], v[0:3]
	s_setprio 0
	s_barrier
	s_add_i32 s53, s53, 2
	s_add_u32 s14, s14, 0x100
	s_addc_u32 s15, s15, 0
	s_add_u32 s51, s51, 0x100
	s_addc_u32 s52, s52, 0
	s_cmp_gt_u32 s53, 13
	s_cbranch_scc0 .LBB0_446
	s_and_b64 vcc, exec, s[2:3]
	s_cbranch_vccz .LBB0_449
	s_barrier

; #define PG8_STAGE(bufoff, gbase, voff) do { _Pragma("unroll") for (int _i = 0; _i < 2; ++_i) \
;         __builtin_amdgcn_global_load_lds((const unsigned*)((const char*)(gbase) + (voff)[_i]), (PG8_LAS unsigned*)(lds + (bufoff) + ldsw + _i * 8192), 16, 0, 0); } while (0)
; #define PG8_LDA(dst, b, h) do { _Pragma("unroll") for (int m = 0; m < 4; ++m) _Pragma("unroll") for (int k = 0; k < 2; ++k) dst[m][k] = *(const PG8_LAS bf16x8*)(lds + PG8_SA(b, h) + aoff + m * 2048 + k * 1024); } while (0)
; #define PG8_LDB(dst, b, h) do { _Pragma("unroll") for (int n = 0; n < 2; ++n) _Pragma("unroll") for (int k = 0; k < 2; ++k) dst[n][k] = *(const PG8_LAS bf16x8*)(lds + PG8_SB(b, h) + boff + n * 2048 + k * 1024); } while (0)
; #define PG8_MMA(ai, bj, At, Bt) do { __builtin_amdgcn_s_setprio(1); _Pragma("unroll") for (int m = 0; m < 4; ++m) _Pragma("unroll") for (int n = 0; n < 2; ++n) _Pragma("unroll") for (int k = 0; k < 2; ++k) \
;         acc[ai][bj][m][n] = __builtin_amdgcn_mfma_f32_16x16x32_bf16(Bt[n][k], At[m][k], acc[ai][bj][m][n], 0, 0, 0); __builtin_amdgcn_s_setprio(0); } while (0)
; #define PG8_WAIT_V(n) asm volatile("s_waitcnt vmcnt(" #n ")" ::: "memory")
; #define PG8_WAIT_L(n) asm volatile("s_waitcnt lgkmcnt(" #n ")" ::: "memory")
; #define PG8_BAR __builtin_amdgcn_s_barrier()
; template <class Epi, class Sched, bool ALIGN_EPI = false, bool SP2 = false>
; __device__ __forceinline__ void gemm_phase(PG8_LAS unsigned char* lds, const Gemm g, const Sched& S, const Epi& E) {
;     ...
;             const char* a1 = cA + (size_t)(t + 1) * kstep;
;             const char* a2 = last ? nA : cA + (size_t)(t + 2) * kstep; const char* b2 = last ? nB : cB + (size_t)(t + 2) * kstep;
;             const char* a3 = a2 + kstep; const char* b3 = b2 + kstep;
;             if (last && has_next) S.a_ready(nxt);
;             if constexpr (SP2) {
;             PG8_LDB(B0, 0, 0); PG8_LDB(B1, 0, 1); PG8_SCHED; PG8_LDA(At, 0, 0); PG8_STAGE(PG8_SA(1, 1), a1 + hstep, voffA);
;             PG8_WAIT_V(8); PG8_WAIT_L(0); PG8_BAR; PG8_MMA(0, 0, At, B0); PG8_MMA(0, 1, At, B1); PG8_BAR; PG8_SCHED;
;             PG8_LDA(At, 0, 1); PG8_STAGE(PG8_SB(0, 0), b2, voffB); PG8_STAGE(PG8_SB(0, 1), b2 + hstep, voffB); PG8_STAGE(PG8_SA(0, 0), a2, voffA);
;             PG8_WAIT_V(8); PG8_WAIT_L(0); PG8_BAR; PG8_MMA(1, 0, At, B0); PG8_MMA(1, 1, At, B1); PG8_BAR; PG8_SCHED;
.Ldn_peel:
	ds_read_b128 v[128:131], v254
	ds_read_b128 v[132:135], v254 offset:1024
	ds_read_b128 v[136:139], v254 offset:2048
	ds_read_b128 v[140:143], v254 offset:3072
	ds_read_b128 v[174:177], v254 offset:16384
	ds_read_b128 v[184:187], v254 offset:17408
	ds_read_b128 v[188:191], v254 offset:18432
	ds_read_b128 v[210:213], v254 offset:19456
	s_add_u32 s2, s0, 0x100
	s_addc_u32 s3, s1, 0
	s_cmp_eq_u32 s13, 40
	s_cselect_b32 s7, s27, s3
	s_cselect_b32 s6, s26, s2
	s_cselect_b32 s5, s37, s11
	s_cselect_b32 s4, s36, s10
	s_add_i32 m0, s29, 0xc000
	ds_read_b128 v[214:217], v181
	ds_read_b128 v[218:221], v181 offset:1024
	ds_read_b128 v[222:225], v181 offset:2048
	ds_read_b128 v[226:229], v181 offset:3072
	ds_read_b128 v[230:233], v181 offset:4096
	ds_read_b128 v[234:237], v181 offset:5120
	ds_read_b128 v[238:241], v181 offset:6144
	ds_read_b128 v[242:245], v181 offset:7168
	global_load_lds_dwordx4 v170, s[0:1]
	s_add_i32 m0, s29, 0xe000
	s_nop 0
	global_load_lds_dwordx4 v172, s[0:1]
	s_waitcnt vmcnt(8)
	s_waitcnt lgkmcnt(0)
	s_barrier
	s_setprio 1
	v_mfma_f32_16x16x32_bf16 v[124:127], v[128:131], v[214:217], 0
	v_mfma_f32_16x16x32_bf16 v[124:127], v[132:135], v[218:221], v[124:127]
	v_mfma_f32_16x16x32_bf16 v[120:123], v[136:139], v[214:217], 0
	v_mfma_f32_16x16x32_bf16 v[120:123], v[140:143], v[218:221], v[120:123]
	v_mfma_f32_16x16x32_bf16 v[116:119], v[174:177], v[214:217], 0
	v_mfma_f32_16x16x32_bf16 v[116:119], v[184:187], v[218:221], v[116:119]
	v_mfma_f32_16x16x32_bf16 v[112:115], v[188:191], v[214:217], 0
	v_mfma_f32_16x16x32_bf16 v[112:115], v[210:213], v[218:221], v[112:115]
	v_mfma_f32_16x16x32_bf16 v[108:111], v[128:131], v[222:225], 0
	v_mfma_f32_16x16x32_bf16 v[108:111], v[132:135], v[226:229], v[108:111]
	v_mfma_f32_16x16x32_bf16 v[104:107], v[136:139], v[222:225], 0
	v_mfma_f32_16x16x32_bf16 v[104:107], v[140:143], v[226:229], v[104:107]
	v_mfma_f32_16x16x32_bf16 v[100:103], v[174:177], v[222:225], 0
	v_mfma_f32_16x16x32_bf16 v[100:103], v[184:187], v[226:229], v[100:103]
	v_mfma_f32_16x16x32_bf16 v[96:99], v[188:191], v[222:225], 0
	v_mfma_f32_16x16x32_bf16 v[96:99], v[210:213], v[226:229], v[96:99]
	v_mfma_f32_16x16x32_bf16 v[92:95], v[128:131], v[230:233], 0
	v_mfma_f32_16x16x32_bf16 v[92:95], v[132:135], v[234:237], v[92:95]
	v_mfma_f32_16x16x32_bf16 v[88:91], v[136:139], v[230:233], 0
	v_mfma_f32_16x16x32_bf16 v[88:91], v[140:143], v[234:237], v[88:91]
	v_mfma_f32_16x16x32_bf16 v[84:87], v[174:177], v[230:233], 0
	v_mfma_f32_16x16x32_bf16 v[84:87], v[184:187], v[234:237], v[84:87]
	v_mfma_f32_16x16x32_bf16 v[80:83], v[188:191], v[230:233], 0
	v_mfma_f32_16x16x32_bf16 v[80:83], v[210:213], v[234:237], v[80:83]
	v_mfma_f32_16x16x32_bf16 v[76:79], v[128:131], v[238:241], 0
	v_mfma_f32_16x16x32_bf16 v[76:79], v[132:135], v[242:245], v[76:79]
	v_mfma_f32_16x16x32_bf16 v[72:75], v[136:139], v[238:241], 0
	v_mfma_f32_16x16x32_bf16 v[72:75], v[140:143], v[242:245], v[72:75]
	v_mfma_f32_16x16x32_bf16 v[68:71], v[174:177], v[238:241], 0
	v_mfma_f32_16x16x32_bf16 v[68:71], v[184:187], v[242:245], v[68:71]
	v_mfma_f32_16x16x32_bf16 v[64:67], v[188:191], v[238:241], 0
	v_mfma_f32_16x16x32_bf16 v[64:67], v[210:213], v[242:245], v[64:67]
	s_setprio 0
	s_barrier
	s_mov_b32 m0, s35
	s_add_u32 s0, s4, 0xb0000
	s_addc_u32 s1, s5, 0
	ds_read_b128 v[214:217], v181 offset:16384
	ds_read_b128 v[218:221], v181 offset:17408
	ds_read_b128 v[222:225], v181 offset:18432
	ds_read_b128 v[226:229], v181 offset:19456
	ds_read_b128 v[230:233], v181 offset:20480
	ds_read_b128 v[234:237], v181 offset:21504
	ds_read_b128 v[238:241], v181 offset:22528
	ds_read_b128 v[242:245], v181 offset:23552
	global_load_lds_dwordx4 v166, s[4:5]
	s_mov_b32 m0, s38
	s_nop 0
	global_load_lds_dwordx4 v162, s[4:5]
	s_mov_b32 m0, s39
	s_nop 0
	global_load_lds_dwordx4 v166, s[0:1]
	s_mov_b32 m0, s40
	s_nop 0
	global_load_lds_dwordx4 v162, s[0:1]
	s_mov_b32 m0, s29
	s_nop 0
	global_load_lds_dwordx4 v168, s[6:7]
	s_mov_b32 m0, s41
	s_nop 0
	global_load_lds_dwordx4 v164, s[6:7]
	s_waitcnt vmcnt(8)
	s_waitcnt lgkmcnt(0)
	s_barrier
	s_setprio 1
	v_mfma_f32_16x16x32_bf16 v[60:63], v[128:131], v[214:217], 0
	v_mfma_f32_16x16x32_bf16 v[60:63], v[132:135], v[218:221], v[60:63]
	v_mfma_f32_16x16x32_bf16 v[56:59], v[136:139], v[214:217], 0
	v_mfma_f32_16x16x32_bf16 v[56:59], v[140:143], v[218:221], v[56:59]
	v_mfma_f32_16x16x32_bf16 v[52:55], v[174:177], v[214:217], 0
	v_mfma_f32_16x16x32_bf16 v[52:55], v[184:187], v[218:221], v[52:55]
	v_mfma_f32_16x16x32_bf16 v[48:51], v[188:191], v[214:217], 0
	v_mfma_f32_16x16x32_bf16 v[48:51], v[210:213], v[218:221], v[48:51]
	v_mfma_f32_16x16x32_bf16 v[44:47], v[128:131], v[222:225], 0
	v_mfma_f32_16x16x32_bf16 v[44:47], v[132:135], v[226:229], v[44:47]
	v_mfma_f32_16x16x32_bf16 v[40:43], v[136:139], v[222:225], 0
	v_mfma_f32_16x16x32_bf16 v[40:43], v[140:143], v[226:229], v[40:43]
	v_mfma_f32_16x16x32_bf16 v[36:39], v[174:177], v[222:225], 0
	v_mfma_f32_16x16x32_bf16 v[36:39], v[184:187], v[226:229], v[36:39]
	v_mfma_f32_16x16x32_bf16 v[32:35], v[188:191], v[222:225], 0
	v_mfma_f32_16x16x32_bf16 v[32:35], v[210:213], v[226:229], v[32:35]
	v_mfma_f32_16x16x32_bf16 v[28:31], v[128:131], v[230:233], 0
	v_mfma_f32_16x16x32_bf16 v[28:31], v[132:135], v[234:237], v[28:31]
	v_mfma_f32_16x16x32_bf16 v[24:27], v[136:139], v[230:233], 0
	v_mfma_f32_16x16x32_bf16 v[24:27], v[140:143], v[234:237], v[24:27]
	v_mfma_f32_16x16x32_bf16 v[20:23], v[174:177], v[230:233], 0
	v_mfma_f32_16x16x32_bf16 v[20:23], v[184:187], v[234:237], v[20:23]
	v_mfma_f32_16x16x32_bf16 v[16:19], v[188:191], v[230:233], 0
	v_mfma_f32_16x16x32_bf16 v[16:19], v[210:213], v[234:237], v[16:19]
	v_mfma_f32_16x16x32_bf16 v[12:15], v[128:131], v[238:241], 0
	v_mfma_f32_16x16x32_bf16 v[12:15], v[132:135], v[242:245], v[12:15]
	v_mfma_f32_16x16x32_bf16 v[8:11], v[136:139], v[238:241], 0
	v_mfma_f32_16x16x32_bf16 v[8:11], v[140:143], v[242:245], v[8:11]
	v_mfma_f32_16x16x32_bf16 v[4:7], v[174:177], v[238:241], 0
	v_mfma_f32_16x16x32_bf16 v[4:7], v[184:187], v[242:245], v[4:7]
	v_mfma_f32_16x16x32_bf16 v[0:3], v[188:191], v[238:241], 0
	v_mfma_f32_16x16x32_bf16 v[0:3], v[210:213], v[242:245], v[0:3]
	s_setprio 0
	s_barrier
; #define PG8_STAGE(bufoff, gbase, voff) do { _Pragma("unroll") for (int _i = 0; _i < 2; ++_i) \
;         __builtin_amdgcn_global_load_lds((const unsigned*)((const char*)(gbase) + (voff)[_i]), (PG8_LAS unsigned*)(lds + (bufoff) + ldsw + _i * 8192), 16, 0, 0); } while (0)
; #define PG8_LDA(dst, b, h) do { _Pragma("unroll") for (int m = 0; m < 4; ++m) _Pragma("unroll") for (int k = 0; k < 2; ++k) dst[m][k] = *(const PG8_LAS bf16x8*)(lds + PG8_SA(b, h) + aoff + m * 2048 + k * 1024); } while (0)
; #define PG8_LDB(dst, b, h) do { _Pragma("unroll") for (int n = 0; n < 2; ++n) _Pragma("unroll") for (int k = 0; k < 2; ++k) dst[n][k] = *(const PG8_LAS bf16x8*)(lds + PG8_SB(b, h) + boff + n * 2048 + k * 1024); } while (0)
; #define PG8_MMA(ai, bj, At, Bt) do { __builtin_amdgcn_s_setprio(1); _Pragma("unroll") for (int m = 0; m < 4; ++m) _Pragma("unroll") for (int n = 0; n < 2; ++n) _Pragma("unroll") for (int k = 0; k < 2; ++k) \
;         acc[ai][bj][m][n] = __builtin_amdgcn_mfma_f32_16x16x32_bf16(Bt[n][k], At[m][k], acc[ai][bj][m][n], 0, 0, 0); __builtin_amdgcn_s_setprio(0); } while (0)
; #define PG8_WAIT_V(n) asm volatile("s_waitcnt vmcnt(" #n ")" ::: "memory")
; #define PG8_WAIT_L(n) asm volatile("s_waitcnt lgkmcnt(" #n ")" ::: "memory")
; #define PG8_BAR __builtin_amdgcn_s_barrier()
; #define PG8_SCHED __builtin_amdgcn_sched_barrier(0)
; template <class Epi, class Sched, bool ALIGN_EPI = false, bool SP2 = false>
; __device__ __forceinline__ void gemm_phase(PG8_LAS unsigned char* lds, const Gemm g, const Sched& S, const Epi& E) {
;     ...
;         for (int t = 0; t < nt; t += 2) {
;     ...
;             PG8_LDB(B0, 1, 0); PG8_LDB(B1, 1, 1); PG8_SCHED; PG8_LDA(At, 1, 0); PG8_STAGE(PG8_SA(0, 1), a2 + hstep, voffA);
;             PG8_WAIT_V(8); PG8_WAIT_L(0); PG8_BAR; PG8_MMA(0, 0, At, B0); PG8_MMA(0, 1, At, B1); PG8_BAR; PG8_SCHED;
;             PG8_LDA(At, 1, 1); PG8_STAGE(PG8_SB(1, 0), b3, voffB); PG8_STAGE(PG8_SB(1, 1), b3 + hstep, voffB); PG8_STAGE(PG8_SA(1, 0), a3, voffA);
;             PG8_WAIT_V(8); PG8_WAIT_L(0); PG8_BAR; PG8_MMA(1, 0, At, B0); PG8_MMA(1, 1, At, B1); PG8_BAR; PG8_SCHED;
	ds_read_b128 v[128:131], v254 offset:32768
	ds_read_b128 v[132:135], v254 offset:33792
	ds_read_b128 v[136:139], v254 offset:34816
	ds_read_b128 v[140:143], v254 offset:35840
	ds_read_b128 v[174:177], v254 offset:49152
	ds_read_b128 v[184:187], v254 offset:50176
	ds_read_b128 v[188:191], v254 offset:51200
	ds_read_b128 v[210:213], v254 offset:52224
	s_add_u32 s0, s6, 0xb0000
	s_addc_u32 s1, s7, 0
	s_mov_b32 m0, s42
	ds_read_b128 v[214:217], v181 offset:32768
	ds_read_b128 v[218:221], v181 offset:33792
	ds_read_b128 v[222:225], v181 offset:34816
	ds_read_b128 v[226:229], v181 offset:35840
	ds_read_b128 v[230:233], v181 offset:36864
	ds_read_b128 v[234:237], v181 offset:37888
	ds_read_b128 v[238:241], v181 offset:38912
	ds_read_b128 v[242:245], v181 offset:39936
	global_load_lds_dwordx4 v168, s[0:1]
	s_mov_b32 m0, s43
	s_nop 0
	global_load_lds_dwordx4 v164, s[0:1]
	s_waitcnt vmcnt(8)
	s_waitcnt lgkmcnt(0)
	s_barrier
	s_setprio 1
	v_mfma_f32_16x16x32_bf16 v[124:127], v[128:131], v[214:217], v[124:127]
	v_mfma_f32_16x16x32_bf16 v[124:127], v[132:135], v[218:221], v[124:127]
	v_mfma_f32_16x16x32_bf16 v[120:123], v[136:139], v[214:217], v[120:123]
	v_mfma_f32_16x16x32_bf16 v[120:123], v[140:143], v[218:221], v[120:123]
	v_mfma_f32_16x16x32_bf16 v[116:119], v[174:177], v[214:217], v[116:119]
	v_mfma_f32_16x16x32_bf16 v[116:119], v[184:187], v[218:221], v[116:119]
	v_mfma_f32_16x16x32_bf16 v[112:115], v[188:191], v[214:217], v[112:115]
	v_mfma_f32_16x16x32_bf16 v[112:115], v[210:213], v[218:221], v[112:115]
	v_mfma_f32_16x16x32_bf16 v[108:111], v[128:131], v[222:225], v[108:111]
	v_mfma_f32_16x16x32_bf16 v[108:111], v[132:135], v[226:229], v[108:111]
	v_mfma_f32_16x16x32_bf16 v[104:107], v[136:139], v[222:225], v[104:107]
	v_mfma_f32_16x16x32_bf16 v[104:107], v[140:143], v[226:229], v[104:107]
	v_mfma_f32_16x16x32_bf16 v[100:103], v[174:177], v[222:225], v[100:103]
	v_mfma_f32_16x16x32_bf16 v[100:103], v[184:187], v[226:229], v[100:103]
	v_mfma_f32_16x16x32_bf16 v[96:99], v[188:191], v[222:225], v[96:99]
	v_mfma_f32_16x16x32_bf16 v[96:99], v[210:213], v[226:229], v[96:99]
	v_mfma_f32_16x16x32_bf16 v[92:95], v[128:131], v[230:233], v[92:95]
	v_mfma_f32_16x16x32_bf16 v[92:95], v[132:135], v[234:237], v[92:95]
	v_mfma_f32_16x16x32_bf16 v[88:91], v[136:139], v[230:233], v[88:91]
	v_mfma_f32_16x16x32_bf16 v[88:91], v[140:143], v[234:237], v[88:91]
	v_mfma_f32_16x16x32_bf16 v[84:87], v[174:177], v[230:233], v[84:87]
	v_mfma_f32_16x16x32_bf16 v[84:87], v[184:187], v[234:237], v[84:87]
	v_mfma_f32_16x16x32_bf16 v[80:83], v[188:191], v[230:233], v[80:83]
	v_mfma_f32_16x16x32_bf16 v[80:83], v[210:213], v[234:237], v[80:83]
	v_mfma_f32_16x16x32_bf16 v[76:79], v[128:131], v[238:241], v[76:79]
	v_mfma_f32_16x16x32_bf16 v[76:79], v[132:135], v[242:245], v[76:79]
	v_mfma_f32_16x16x32_bf16 v[72:75], v[136:139], v[238:241], v[72:75]
	v_mfma_f32_16x16x32_bf16 v[72:75], v[140:143], v[242:245], v[72:75]
	v_mfma_f32_16x16x32_bf16 v[68:71], v[174:177], v[238:241], v[68:71]
	v_mfma_f32_16x16x32_bf16 v[68:71], v[184:187], v[242:245], v[68:71]
	v_mfma_f32_16x16x32_bf16 v[64:67], v[188:191], v[238:241], v[64:67]
	v_mfma_f32_16x16x32_bf16 v[64:67], v[210:213], v[242:245], v[64:67]
	s_setprio 0
	s_barrier
	s_mov_b32 m0, s47
	s_add_u32 s0, s4, 0xb0080
	s_addc_u32 s1, s5, 0
	ds_read_b128 v[214:217], v181 offset:49152
	ds_read_b128 v[218:221], v181 offset:50176
	ds_read_b128 v[222:225], v181 offset:51200
	ds_read_b128 v[226:229], v181 offset:52224
	ds_read_b128 v[230:233], v181 offset:53248
	ds_read_b128 v[234:237], v181 offset:54272
	ds_read_b128 v[238:241], v181 offset:55296
	ds_read_b128 v[242:245], v181 offset:56320
	s_add_u32 s98, s4, 0x80
	s_addc_u32 s99, s5, 0
	global_load_lds_dwordx4 v166, s[98:99]
	s_mov_b32 m0, s48
	s_nop 0
	global_load_lds_dwordx4 v162, s[98:99]
	s_mov_b32 m0, s51
	s_nop 0
	global_load_lds_dwordx4 v166, s[0:1]
	s_mov_b32 m0, s52
	s_nop 0
	global_load_lds_dwordx4 v162, s[0:1]
	s_mov_b32 m0, s49
	s_nop 0
	s_add_u32 s100, s6, 0x80
	s_addc_u32 s101, s7, 0
	global_load_lds_dwordx4 v168, s[100:101]
	s_mov_b32 m0, s50
	s_nop 0
	global_load_lds_dwordx4 v164, s[100:101]
	s_waitcnt vmcnt(8)
	s_waitcnt lgkmcnt(0)
	s_barrier
	s_setprio 1
	v_mfma_f32_16x16x32_bf16 v[60:63], v[128:131], v[214:217], v[60:63]
	v_mfma_f32_16x16x32_bf16 v[60:63], v[132:135], v[218:221], v[60:63]
	v_mfma_f32_16x16x32_bf16 v[56:59], v[136:139], v[214:217], v[56:59]
	v_mfma_f32_16x16x32_bf16 v[56:59], v[140:143], v[218:221], v[56:59]
	v_mfma_f32_16x16x32_bf16 v[52:55], v[174:177], v[214:217], v[52:55]
	v_mfma_f32_16x16x32_bf16 v[52:55], v[184:187], v[218:221], v[52:55]
	v_mfma_f32_16x16x32_bf16 v[48:51], v[188:191], v[214:217], v[48:51]
	v_mfma_f32_16x16x32_bf16 v[48:51], v[210:213], v[218:221], v[48:51]
	v_mfma_f32_16x16x32_bf16 v[44:47], v[128:131], v[222:225], v[44:47]
	v_mfma_f32_16x16x32_bf16 v[44:47], v[132:135], v[226:229], v[44:47]
	v_mfma_f32_16x16x32_bf16 v[40:43], v[136:139], v[222:225], v[40:43]
	v_mfma_f32_16x16x32_bf16 v[40:43], v[140:143], v[226:229], v[40:43]
	v_mfma_f32_16x16x32_bf16 v[36:39], v[174:177], v[222:225], v[36:39]
	v_mfma_f32_16x16x32_bf16 v[36:39], v[184:187], v[226:229], v[36:39]
	v_mfma_f32_16x16x32_bf16 v[32:35], v[188:191], v[222:225], v[32:35]
	v_mfma_f32_16x16x32_bf16 v[32:35], v[210:213], v[226:229], v[32:35]
	v_mfma_f32_16x16x32_bf16 v[28:31], v[128:131], v[230:233], v[28:31]
	v_mfma_f32_16x16x32_bf16 v[28:31], v[132:135], v[234:237], v[28:31]
	v_mfma_f32_16x16x32_bf16 v[24:27], v[136:139], v[230:233], v[24:27]
	v_mfma_f32_16x16x32_bf16 v[24:27], v[140:143], v[234:237], v[24:27]
	v_mfma_f32_16x16x32_bf16 v[20:23], v[174:177], v[230:233], v[20:23]
	v_mfma_f32_16x16x32_bf16 v[20:23], v[184:187], v[234:237], v[20:23]
	v_mfma_f32_16x16x32_bf16 v[16:19], v[188:191], v[230:233], v[16:19]
	v_mfma_f32_16x16x32_bf16 v[16:19], v[210:213], v[234:237], v[16:19]
	v_mfma_f32_16x16x32_bf16 v[12:15], v[128:131], v[238:241], v[12:15]
	v_mfma_f32_16x16x32_bf16 v[12:15], v[132:135], v[242:245], v[12:15]
	v_mfma_f32_16x16x32_bf16 v[8:11], v[136:139], v[238:241], v[8:11]
	v_mfma_f32_16x16x32_bf16 v[8:11], v[140:143], v[242:245], v[8:11]
	v_mfma_f32_16x16x32_bf16 v[4:7], v[174:177], v[238:241], v[4:7]
	v_mfma_f32_16x16x32_bf16 v[4:7], v[184:187], v[242:245], v[4:7]
	v_mfma_f32_16x16x32_bf16 v[0:3], v[188:191], v[238:241], v[0:3]
	v_mfma_f32_16x16x32_bf16 v[0:3], v[210:213], v[242:245], v[0:3]
	s_setprio 0
	s_barrier
	s_add_i32 s13, s13, 2
	s_add_u32 s10, s10, 0x100
	s_addc_u32 s11, s11, 0
	s_cmp_gt_u32 s13, 41
	s_mov_b64 s[0:1], s[2:3]
; #define PG8_STAGE(bufoff, gbase, voff) do { _Pragma("unroll") for (int _i = 0; _i < 2; ++_i) \
;         __builtin_amdgcn_global_load_lds((const unsigned*)((const char*)(gbase) + (voff)[_i]), (PG8_LAS unsigned*)(lds + (bufoff) + ldsw + _i * 8192), 16, 0, 0); } while (0)
; #define PG8_LDA(dst, b, h) do { _Pragma("unroll") for (int m = 0; m < 4; ++m) _Pragma("unroll") for (int k = 0; k < 2; ++k) dst[m][k] = *(const PG8_LAS bf16x8*)(lds + PG8_SA(b, h) + aoff + m * 2048 + k * 1024); } while (0)
; #define PG8_LDB(dst, b, h) do { _Pragma("unroll") for (int n = 0; n < 2; ++n) _Pragma("unroll") for (int k = 0; k < 2; ++k) dst[n][k] = *(const PG8_LAS bf16x8*)(lds + PG8_SB(b, h) + boff + n * 2048 + k * 1024); } while (0)
; #define PG8_MMA(ai, bj, At, Bt) do { __builtin_amdgcn_s_setprio(1); _Pragma("unroll") for (int m = 0; m < 4; ++m) _Pragma("unroll") for (int n = 0; n < 2; ++n) _Pragma("unroll") for (int k = 0; k < 2; ++k) \
;         acc[ai][bj][m][n] = __builtin_amdgcn_mfma_f32_16x16x32_bf16(Bt[n][k], At[m][k], acc[ai][bj][m][n], 0, 0, 0); __builtin_amdgcn_s_setprio(0); } while (0)
; #define PG8_WAIT_V(n) asm volatile("s_waitcnt vmcnt(" #n ")" ::: "memory")
; #define PG8_WAIT_L(n) asm volatile("s_waitcnt lgkmcnt(" #n ")" ::: "memory")
; #define PG8_BAR __builtin_amdgcn_s_barrier()
; template <class Epi, class Sched, bool ALIGN_EPI = false, bool SP2 = false>
; __device__ __forceinline__ void gemm_phase(PG8_LAS unsigned char* lds, const Gemm g, const Sched& S, const Epi& E) {
;     ...
;             const char* a1 = cA + (size_t)(t + 1) * kstep;
;             const char* a2 = last ? nA : cA + (size_t)(t + 2) * kstep; const char* b2 = last ? nB : cB + (size_t)(t + 2) * kstep;
;             const char* a3 = a2 + kstep; const char* b3 = b2 + kstep;
;             if (last && has_next) S.a_ready(nxt);
;             if constexpr (SP2) {
;             PG8_LDB(B0, 0, 0); PG8_LDB(B1, 0, 1); PG8_SCHED; PG8_LDA(At, 0, 0); PG8_STAGE(PG8_SA(1, 1), a1 + hstep, voffA);
;             PG8_WAIT_V(8); PG8_WAIT_L(0); PG8_BAR; PG8_MMA(0, 0, At, B0); PG8_MMA(0, 1, At, B1); PG8_BAR; PG8_SCHED;
;             PG8_LDA(At, 0, 1); PG8_STAGE(PG8_SB(0, 0), b2, voffB); PG8_STAGE(PG8_SB(0, 1), b2 + hstep, voffB); PG8_STAGE(PG8_SA(0, 0), a2, voffA);
;             PG8_WAIT_V(8); PG8_WAIT_L(0); PG8_BAR; PG8_MMA(1, 0, At, B0); PG8_MMA(1, 1, At, B1); PG8_BAR; PG8_SCHED;
.LBB0_545:
	ds_read_b128 v[128:131], v254
	ds_read_b128 v[132:135], v254 offset:1024
	ds_read_b128 v[136:139], v254 offset:2048
	ds_read_b128 v[140:143], v254 offset:3072
	ds_read_b128 v[174:177], v254 offset:16384
	ds_read_b128 v[184:187], v254 offset:17408
	ds_read_b128 v[188:191], v254 offset:18432
	ds_read_b128 v[210:213], v254 offset:19456
	s_add_u32 s2, s0, 0x100
	s_addc_u32 s3, s1, 0
	s_cmp_eq_u32 s13, 40
	s_cselect_b32 s7, s27, s3
	s_cselect_b32 s6, s26, s2
	s_cselect_b32 s5, s37, s11
	s_cselect_b32 s4, s36, s10
	s_add_i32 m0, s29, 0xc000
	ds_read_b128 v[214:217], v181
	ds_read_b128 v[218:221], v181 offset:1024
	ds_read_b128 v[222:225], v181 offset:2048
	ds_read_b128 v[226:229], v181 offset:3072
	ds_read_b128 v[230:233], v181 offset:4096
	ds_read_b128 v[234:237], v181 offset:5120
	ds_read_b128 v[238:241], v181 offset:6144
	ds_read_b128 v[242:245], v181 offset:7168
	global_load_lds_dwordx4 v170, s[0:1]
	s_add_i32 m0, s29, 0xe000
	s_nop 0
	global_load_lds_dwordx4 v172, s[0:1]
	s_waitcnt vmcnt(8)
	s_waitcnt lgkmcnt(0)
	s_barrier
	s_setprio 1
	v_mfma_f32_16x16x32_bf16 v[124:127], v[128:131], v[214:217], v[124:127]
	v_mfma_f32_16x16x32_bf16 v[124:127], v[132:135], v[218:221], v[124:127]
	v_mfma_f32_16x16x32_bf16 v[120:123], v[136:139], v[214:217], v[120:123]
	v_mfma_f32_16x16x32_bf16 v[120:123], v[140:143], v[218:221], v[120:123]
	v_mfma_f32_16x16x32_bf16 v[116:119], v[174:177], v[214:217], v[116:119]
	v_mfma_f32_16x16x32_bf16 v[116:119], v[184:187], v[218:221], v[116:119]
	v_mfma_f32_16x16x32_bf16 v[112:115], v[188:191], v[214:217], v[112:115]
	v_mfma_f32_16x16x32_bf16 v[112:115], v[210:213], v[218:221], v[112:115]
	v_mfma_f32_16x16x32_bf16 v[108:111], v[128:131], v[222:225], v[108:111]
	v_mfma_f32_16x16x32_bf16 v[108:111], v[132:135], v[226:229], v[108:111]
	v_mfma_f32_16x16x32_bf16 v[104:107], v[136:139], v[222:225], v[104:107]
	v_mfma_f32_16x16x32_bf16 v[104:107], v[140:143], v[226:229], v[104:107]
	v_mfma_f32_16x16x32_bf16 v[100:103], v[174:177], v[222:225], v[100:103]
	v_mfma_f32_16x16x32_bf16 v[100:103], v[184:187], v[226:229], v[100:103]
	v_mfma_f32_16x16x32_bf16 v[96:99], v[188:191], v[222:225], v[96:99]
	v_mfma_f32_16x16x32_bf16 v[96:99], v[210:213], v[226:229], v[96:99]
	v_mfma_f32_16x16x32_bf16 v[92:95], v[128:131], v[230:233], v[92:95]
	v_mfma_f32_16x16x32_bf16 v[92:95], v[132:135], v[234:237], v[92:95]
	v_mfma_f32_16x16x32_bf16 v[88:91], v[136:139], v[230:233], v[88:91]
	v_mfma_f32_16x16x32_bf16 v[88:91], v[140:143], v[234:237], v[88:91]
	v_mfma_f32_16x16x32_bf16 v[84:87], v[174:177], v[230:233], v[84:87]
	v_mfma_f32_16x16x32_bf16 v[84:87], v[184:187], v[234:237], v[84:87]
	v_mfma_f32_16x16x32_bf16 v[80:83], v[188:191], v[230:233], v[80:83]
	v_mfma_f32_16x16x32_bf16 v[80:83], v[210:213], v[234:237], v[80:83]
	v_mfma_f32_16x16x32_bf16 v[76:79], v[128:131], v[238:241], v[76:79]
	v_mfma_f32_16x16x32_bf16 v[76:79], v[132:135], v[242:245], v[76:79]
	v_mfma_f32_16x16x32_bf16 v[72:75], v[136:139], v[238:241], v[72:75]
	v_mfma_f32_16x16x32_bf16 v[72:75], v[140:143], v[242:245], v[72:75]
	v_mfma_f32_16x16x32_bf16 v[68:71], v[174:177], v[238:241], v[68:71]
	v_mfma_f32_16x16x32_bf16 v[68:71], v[184:187], v[242:245], v[68:71]
	v_mfma_f32_16x16x32_bf16 v[64:67], v[188:191], v[238:241], v[64:67]
	v_mfma_f32_16x16x32_bf16 v[64:67], v[210:213], v[242:245], v[64:67]
	s_setprio 0
	s_barrier
	s_mov_b32 m0, s35
	s_add_u32 s0, s4, 0xb0000
	s_addc_u32 s1, s5, 0
	ds_read_b128 v[214:217], v181 offset:16384
	ds_read_b128 v[218:221], v181 offset:17408
	ds_read_b128 v[222:225], v181 offset:18432
	ds_read_b128 v[226:229], v181 offset:19456
	ds_read_b128 v[230:233], v181 offset:20480
	ds_read_b128 v[234:237], v181 offset:21504
	ds_read_b128 v[238:241], v181 offset:22528
	ds_read_b128 v[242:245], v181 offset:23552
	global_load_lds_dwordx4 v166, s[4:5]
	s_mov_b32 m0, s38
	s_nop 0
	global_load_lds_dwordx4 v162, s[4:5]
	s_mov_b32 m0, s39
	s_nop 0
	global_load_lds_dwordx4 v166, s[0:1]
	s_mov_b32 m0, s40
	s_nop 0
	global_load_lds_dwordx4 v162, s[0:1]
	s_mov_b32 m0, s29
	s_nop 0
	global_load_lds_dwordx4 v168, s[6:7]
	s_mov_b32 m0, s41
	s_nop 0
	global_load_lds_dwordx4 v164, s[6:7]
	s_waitcnt vmcnt(8)
	s_waitcnt lgkmcnt(0)
	s_barrier
	s_setprio 1
	v_mfma_f32_16x16x32_bf16 v[60:63], v[128:131], v[214:217], v[60:63]
	v_mfma_f32_16x16x32_bf16 v[60:63], v[132:135], v[218:221], v[60:63]
	v_mfma_f32_16x16x32_bf16 v[56:59], v[136:139], v[214:217], v[56:59]
	v_mfma_f32_16x16x32_bf16 v[56:59], v[140:143], v[218:221], v[56:59]
	v_mfma_f32_16x16x32_bf16 v[52:55], v[174:177], v[214:217], v[52:55]
	v_mfma_f32_16x16x32_bf16 v[52:55], v[184:187], v[218:221], v[52:55]
	v_mfma_f32_16x16x32_bf16 v[48:51], v[188:191], v[214:217], v[48:51]
	v_mfma_f32_16x16x32_bf16 v[48:51], v[210:213], v[218:221], v[48:51]
	v_mfma_f32_16x16x32_bf16 v[44:47], v[128:131], v[222:225], v[44:47]
	v_mfma_f32_16x16x32_bf16 v[44:47], v[132:135], v[226:229], v[44:47]
	v_mfma_f32_16x16x32_bf16 v[40:43], v[136:139], v[222:225], v[40:43]
	v_mfma_f32_16x16x32_bf16 v[40:43], v[140:143], v[226:229], v[40:43]
	v_mfma_f32_16x16x32_bf16 v[36:39], v[174:177], v[222:225], v[36:39]
	v_mfma_f32_16x16x32_bf16 v[36:39], v[184:187], v[226:229], v[36:39]
	v_mfma_f32_16x16x32_bf16 v[32:35], v[188:191], v[222:225], v[32:35]
	v_mfma_f32_16x16x32_bf16 v[32:35], v[210:213], v[226:229], v[32:35]
	v_mfma_f32_16x16x32_bf16 v[28:31], v[128:131], v[230:233], v[28:31]
	v_mfma_f32_16x16x32_bf16 v[28:31], v[132:135], v[234:237], v[28:31]
	v_mfma_f32_16x16x32_bf16 v[24:27], v[136:139], v[230:233], v[24:27]
	v_mfma_f32_16x16x32_bf16 v[24:27], v[140:143], v[234:237], v[24:27]
	v_mfma_f32_16x16x32_bf16 v[20:23], v[174:177], v[230:233], v[20:23]
	v_mfma_f32_16x16x32_bf16 v[20:23], v[184:187], v[234:237], v[20:23]
	v_mfma_f32_16x16x32_bf16 v[16:19], v[188:191], v[230:233], v[16:19]
	v_mfma_f32_16x16x32_bf16 v[16:19], v[210:213], v[234:237], v[16:19]
	v_mfma_f32_16x16x32_bf16 v[12:15], v[128:131], v[238:241], v[12:15]
	v_mfma_f32_16x16x32_bf16 v[12:15], v[132:135], v[242:245], v[12:15]
	v_mfma_f32_16x16x32_bf16 v[8:11], v[136:139], v[238:241], v[8:11]
	v_mfma_f32_16x16x32_bf16 v[8:11], v[140:143], v[242:245], v[8:11]
	v_mfma_f32_16x16x32_bf16 v[4:7], v[174:177], v[238:241], v[4:7]
	v_mfma_f32_16x16x32_bf16 v[4:7], v[184:187], v[242:245], v[4:7]
	v_mfma_f32_16x16x32_bf16 v[0:3], v[188:191], v[238:241], v[0:3]
	v_mfma_f32_16x16x32_bf16 v[0:3], v[210:213], v[242:245], v[0:3]
	s_setprio 0
	s_barrier
; #define PG8_STAGE(bufoff, gbase, voff) do { _Pragma("unroll") for (int _i = 0; _i < 2; ++_i) \
;         __builtin_amdgcn_global_load_lds((const unsigned*)((const char*)(gbase) + (voff)[_i]), (PG8_LAS unsigned*)(lds + (bufoff) + ldsw + _i * 8192), 16, 0, 0); } while (0)
; #define PG8_LDA(dst, b, h) do { _Pragma("unroll") for (int m = 0; m < 4; ++m) _Pragma("unroll") for (int k = 0; k < 2; ++k) dst[m][k] = *(const PG8_LAS bf16x8*)(lds + PG8_SA(b, h) + aoff + m * 2048 + k * 1024); } while (0)
; #define PG8_LDB(dst, b, h) do { _Pragma("unroll") for (int n = 0; n < 2; ++n) _Pragma("unroll") for (int k = 0; k < 2; ++k) dst[n][k] = *(const PG8_LAS bf16x8*)(lds + PG8_SB(b, h) + boff + n * 2048 + k * 1024); } while (0)
; #define PG8_MMA(ai, bj, At, Bt) do { __builtin_amdgcn_s_setprio(1); _Pragma("unroll") for (int m = 0; m < 4; ++m) _Pragma("unroll") for (int n = 0; n < 2; ++n) _Pragma("unroll") for (int k = 0; k < 2; ++k) \
;         acc[ai][bj][m][n] = __builtin_amdgcn_mfma_f32_16x16x32_bf16(Bt[n][k], At[m][k], acc[ai][bj][m][n], 0, 0, 0); __builtin_amdgcn_s_setprio(0); } while (0)
; #define PG8_WAIT_V(n) asm volatile("s_waitcnt vmcnt(" #n ")" ::: "memory")
; #define PG8_WAIT_L(n) asm volatile("s_waitcnt lgkmcnt(" #n ")" ::: "memory")
; #define PG8_BAR __builtin_amdgcn_s_barrier()
; #define PG8_SCHED __builtin_amdgcn_sched_barrier(0)
; template <class Epi, class Sched, bool ALIGN_EPI = false, bool SP2 = false>
; __device__ __forceinline__ void gemm_phase(PG8_LAS unsigned char* lds, const Gemm g, const Sched& S, const Epi& E) {
;     ...
;         for (int t = 0; t < nt; t += 2) {
;     ...
;             PG8_LDB(B0, 1, 0); PG8_LDB(B1, 1, 1); PG8_SCHED; PG8_LDA(At, 1, 0); PG8_STAGE(PG8_SA(0, 1), a2 + hstep, voffA);
;             PG8_WAIT_V(8); PG8_WAIT_L(0); PG8_BAR; PG8_MMA(0, 0, At, B0); PG8_MMA(0, 1, At, B1); PG8_BAR; PG8_SCHED;
;             PG8_LDA(At, 1, 1); PG8_STAGE(PG8_SB(1, 0), b3, voffB); PG8_STAGE(PG8_SB(1, 1), b3 + hstep, voffB); PG8_STAGE(PG8_SA(1, 0), a3, voffA);
;             PG8_WAIT_V(8); PG8_WAIT_L(0); PG8_BAR; PG8_MMA(1, 0, At, B0); PG8_MMA(1, 1, At, B1); PG8_BAR; PG8_SCHED;
;     ...
;         if constexpr (ALIGN_EPI) { if (wr == 0) PG8_BAR; }
	ds_read_b128 v[128:131], v254 offset:32768
	ds_read_b128 v[132:135], v254 offset:33792
	ds_read_b128 v[136:139], v254 offset:34816
	ds_read_b128 v[140:143], v254 offset:35840
	ds_read_b128 v[174:177], v254 offset:49152
	ds_read_b128 v[184:187], v254 offset:50176
	ds_read_b128 v[188:191], v254 offset:51200
	ds_read_b128 v[210:213], v254 offset:52224
	s_add_u32 s0, s6, 0xb0000
	s_addc_u32 s1, s7, 0
	s_mov_b32 m0, s42
	ds_read_b128 v[214:217], v181 offset:32768
	ds_read_b128 v[218:221], v181 offset:33792
	ds_read_b128 v[222:225], v181 offset:34816
	ds_read_b128 v[226:229], v181 offset:35840
	ds_read_b128 v[230:233], v181 offset:36864
	ds_read_b128 v[234:237], v181 offset:37888
	ds_read_b128 v[238:241], v181 offset:38912
	ds_read_b128 v[242:245], v181 offset:39936
	global_load_lds_dwordx4 v168, s[0:1]
	s_mov_b32 m0, s43
	s_nop 0
	global_load_lds_dwordx4 v164, s[0:1]
	s_waitcnt vmcnt(8)
	s_waitcnt lgkmcnt(0)
	s_barrier
	s_setprio 1
	v_mfma_f32_16x16x32_bf16 v[124:127], v[128:131], v[214:217], v[124:127]
	v_mfma_f32_16x16x32_bf16 v[124:127], v[132:135], v[218:221], v[124:127]
	v_mfma_f32_16x16x32_bf16 v[120:123], v[136:139], v[214:217], v[120:123]
	v_mfma_f32_16x16x32_bf16 v[120:123], v[140:143], v[218:221], v[120:123]
	v_mfma_f32_16x16x32_bf16 v[116:119], v[174:177], v[214:217], v[116:119]
	v_mfma_f32_16x16x32_bf16 v[116:119], v[184:187], v[218:221], v[116:119]
	v_mfma_f32_16x16x32_bf16 v[112:115], v[188:191], v[214:217], v[112:115]
	v_mfma_f32_16x16x32_bf16 v[112:115], v[210:213], v[218:221], v[112:115]
	v_mfma_f32_16x16x32_bf16 v[108:111], v[128:131], v[222:225], v[108:111]
	v_mfma_f32_16x16x32_bf16 v[108:111], v[132:135], v[226:229], v[108:111]
	v_mfma_f32_16x16x32_bf16 v[104:107], v[136:139], v[222:225], v[104:107]
	v_mfma_f32_16x16x32_bf16 v[104:107], v[140:143], v[226:229], v[104:107]
	v_mfma_f32_16x16x32_bf16 v[100:103], v[174:177], v[222:225], v[100:103]
	v_mfma_f32_16x16x32_bf16 v[100:103], v[184:187], v[226:229], v[100:103]
	v_mfma_f32_16x16x32_bf16 v[96:99], v[188:191], v[222:225], v[96:99]
	v_mfma_f32_16x16x32_bf16 v[96:99], v[210:213], v[226:229], v[96:99]
	v_mfma_f32_16x16x32_bf16 v[92:95], v[128:131], v[230:233], v[92:95]
	v_mfma_f32_16x16x32_bf16 v[92:95], v[132:135], v[234:237], v[92:95]
	v_mfma_f32_16x16x32_bf16 v[88:91], v[136:139], v[230:233], v[88:91]
	v_mfma_f32_16x16x32_bf16 v[88:91], v[140:143], v[234:237], v[88:91]
	v_mfma_f32_16x16x32_bf16 v[84:87], v[174:177], v[230:233], v[84:87]
	v_mfma_f32_16x16x32_bf16 v[84:87], v[184:187], v[234:237], v[84:87]
	v_mfma_f32_16x16x32_bf16 v[80:83], v[188:191], v[230:233], v[80:83]
	v_mfma_f32_16x16x32_bf16 v[80:83], v[210:213], v[234:237], v[80:83]
	v_mfma_f32_16x16x32_bf16 v[76:79], v[128:131], v[238:241], v[76:79]
	v_mfma_f32_16x16x32_bf16 v[76:79], v[132:135], v[242:245], v[76:79]
	v_mfma_f32_16x16x32_bf16 v[72:75], v[136:139], v[238:241], v[72:75]
	v_mfma_f32_16x16x32_bf16 v[72:75], v[140:143], v[242:245], v[72:75]
	v_mfma_f32_16x16x32_bf16 v[68:71], v[174:177], v[238:241], v[68:71]
	v_mfma_f32_16x16x32_bf16 v[68:71], v[184:187], v[242:245], v[68:71]
	v_mfma_f32_16x16x32_bf16 v[64:67], v[188:191], v[238:241], v[64:67]
	v_mfma_f32_16x16x32_bf16 v[64:67], v[210:213], v[242:245], v[64:67]
	s_setprio 0
	s_barrier
	s_mov_b32 m0, s47
	s_add_u32 s0, s4, 0xb0080
	s_addc_u32 s1, s5, 0
	ds_read_b128 v[214:217], v181 offset:49152
	ds_read_b128 v[218:221], v181 offset:50176
	ds_read_b128 v[222:225], v181 offset:51200
	ds_read_b128 v[226:229], v181 offset:52224
	ds_read_b128 v[230:233], v181 offset:53248
	ds_read_b128 v[234:237], v181 offset:54272
	ds_read_b128 v[238:241], v181 offset:55296
	ds_read_b128 v[242:245], v181 offset:56320
	s_add_u32 s98, s4, 0x80
	s_addc_u32 s99, s5, 0
	global_load_lds_dwordx4 v166, s[98:99]
	s_mov_b32 m0, s48
	s_nop 0
	global_load_lds_dwordx4 v162, s[98:99]
	s_mov_b32 m0, s51
	s_nop 0
	global_load_lds_dwordx4 v166, s[0:1]
	s_mov_b32 m0, s52
	s_nop 0
	global_load_lds_dwordx4 v162, s[0:1]
	s_mov_b32 m0, s49
	s_nop 0
	s_add_u32 s100, s6, 0x80
	s_addc_u32 s101, s7, 0
	global_load_lds_dwordx4 v168, s[100:101]
	s_mov_b32 m0, s50
	s_nop 0
	global_load_lds_dwordx4 v164, s[100:101]
	s_waitcnt vmcnt(8)
	s_waitcnt lgkmcnt(0)
	s_barrier
	s_setprio 1
	v_mfma_f32_16x16x32_bf16 v[60:63], v[128:131], v[214:217], v[60:63]
	v_mfma_f32_16x16x32_bf16 v[60:63], v[132:135], v[218:221], v[60:63]
	v_mfma_f32_16x16x32_bf16 v[56:59], v[136:139], v[214:217], v[56:59]
	v_mfma_f32_16x16x32_bf16 v[56:59], v[140:143], v[218:221], v[56:59]
	v_mfma_f32_16x16x32_bf16 v[52:55], v[174:177], v[214:217], v[52:55]
	v_mfma_f32_16x16x32_bf16 v[52:55], v[184:187], v[218:221], v[52:55]
	v_mfma_f32_16x16x32_bf16 v[48:51], v[188:191], v[214:217], v[48:51]
	v_mfma_f32_16x16x32_bf16 v[48:51], v[210:213], v[218:221], v[48:51]
	v_mfma_f32_16x16x32_bf16 v[44:47], v[128:131], v[222:225], v[44:47]
	v_mfma_f32_16x16x32_bf16 v[44:47], v[132:135], v[226:229], v[44:47]
	v_mfma_f32_16x16x32_bf16 v[40:43], v[136:139], v[222:225], v[40:43]
	v_mfma_f32_16x16x32_bf16 v[40:43], v[140:143], v[226:229], v[40:43]
	v_mfma_f32_16x16x32_bf16 v[36:39], v[174:177], v[222:225], v[36:39]
	v_mfma_f32_16x16x32_bf16 v[36:39], v[184:187], v[226:229], v[36:39]
	v_mfma_f32_16x16x32_bf16 v[32:35], v[188:191], v[222:225], v[32:35]
	v_mfma_f32_16x16x32_bf16 v[32:35], v[210:213], v[226:229], v[32:35]
	v_mfma_f32_16x16x32_bf16 v[28:31], v[128:131], v[230:233], v[28:31]
	v_mfma_f32_16x16x32_bf16 v[28:31], v[132:135], v[234:237], v[28:31]
	v_mfma_f32_16x16x32_bf16 v[24:27], v[136:139], v[230:233], v[24:27]
	v_mfma_f32_16x16x32_bf16 v[24:27], v[140:143], v[234:237], v[24:27]
	v_mfma_f32_16x16x32_bf16 v[20:23], v[174:177], v[230:233], v[20:23]
	v_mfma_f32_16x16x32_bf16 v[20:23], v[184:187], v[234:237], v[20:23]
	v_mfma_f32_16x16x32_bf16 v[16:19], v[188:191], v[230:233], v[16:19]
	v_mfma_f32_16x16x32_bf16 v[16:19], v[210:213], v[234:237], v[16:19]
	v_mfma_f32_16x16x32_bf16 v[12:15], v[128:131], v[238:241], v[12:15]
	v_mfma_f32_16x16x32_bf16 v[12:15], v[132:135], v[242:245], v[12:15]
	v_mfma_f32_16x16x32_bf16 v[8:11], v[136:139], v[238:241], v[8:11]
	v_mfma_f32_16x16x32_bf16 v[8:11], v[140:143], v[242:245], v[8:11]
	v_mfma_f32_16x16x32_bf16 v[4:7], v[174:177], v[238:241], v[4:7]
	v_mfma_f32_16x16x32_bf16 v[4:7], v[184:187], v[242:245], v[4:7]
	v_mfma_f32_16x16x32_bf16 v[0:3], v[188:191], v[238:241], v[0:3]
	v_mfma_f32_16x16x32_bf16 v[0:3], v[210:213], v[242:245], v[0:3]
	s_setprio 0
	s_barrier
	s_add_i32 s13, s13, 2
	s_add_u32 s10, s10, 0x100
	s_addc_u32 s11, s11, 0
	s_cmp_gt_u32 s13, 41
	s_mov_b64 s[0:1], s[2:3]
	s_cbranch_scc0 .LBB0_545
	s_and_b64 vcc, exec, s[22:23]
	s_cbranch_vccz .LBB0_548
	s_barrier

; #define PG8_STAGE(bufoff, gbase, voff) do { _Pragma("unroll") for (int _i = 0; _i < 2; ++_i) \
;         __builtin_amdgcn_global_load_lds((const unsigned*)((const char*)(gbase) + (voff)[_i]), (PG8_LAS unsigned*)(lds + (bufoff) + ldsw + _i * 8192), 16, 0, 0); } while (0)
; #define PG8_LDA(dst, b, h) do { _Pragma("unroll") for (int m = 0; m < 4; ++m) _Pragma("unroll") for (int k = 0; k < 2; ++k) dst[m][k] = *(const PG8_LAS bf16x8*)(lds + PG8_SA(b, h) + aoff + m * 2048 + k * 1024); } while (0)
; #define PG8_LDB(dst, b, h) do { _Pragma("unroll") for (int n = 0; n < 2; ++n) _Pragma("unroll") for (int k = 0; k < 2; ++k) dst[n][k] = *(const PG8_LAS bf16x8*)(lds + PG8_SB(b, h) + boff + n * 2048 + k * 1024); } while (0)
; #define PG8_MMA(ai, bj, At, Bt) do { __builtin_amdgcn_s_setprio(1); _Pragma("unroll") for (int m = 0; m < 4; ++m) _Pragma("unroll") for (int n = 0; n < 2; ++n) _Pragma("unroll") for (int k = 0; k < 2; ++k) \
;         acc[ai][bj][m][n] = __builtin_amdgcn_mfma_f32_16x16x32_bf16(Bt[n][k], At[m][k], acc[ai][bj][m][n], 0, 0, 0); __builtin_amdgcn_s_setprio(0); } while (0)
; #define PG8_WAIT_V(n) asm volatile("s_waitcnt vmcnt(" #n ")" ::: "memory")
; #define PG8_WAIT_L(n) asm volatile("s_waitcnt lgkmcnt(" #n ")" ::: "memory")
; template <class Epi, class Sched, bool ALIGN_EPI = false, bool SP2 = false>
; __device__ __forceinline__ void gemm_phase(PG8_LAS unsigned char* lds, const Gemm g, const Sched& S, const Epi& E) {
;     ...
;             const bool last = (t == nt - 2);
;             const char* a1 = cA + (size_t)(t + 1) * kstep;
;             const char* a2 = last ? nA : cA + (size_t)(t + 2) * kstep; const char* b2 = last ? nB : cB + (size_t)(t + 2) * kstep;
;             const char* a3 = a2 + kstep; const char* b3 = b2 + kstep;
;             if (last && has_next) S.a_ready(nxt);
;             if constexpr (SP2) {
;             PG8_LDB(B0, 0, 0); PG8_LDB(B1, 0, 1); PG8_SCHED; PG8_LDA(At, 0, 0); PG8_STAGE(PG8_SA(1, 1), a1 + hstep, voffA);
;             PG8_WAIT_V(8); PG8_WAIT_L(0); PG8_BAR; PG8_MMA(0, 0, At, B0); PG8_MMA(0, 1, At, B1); PG8_BAR; PG8_SCHED;
;             PG8_LDA(At, 0, 1); PG8_STAGE(PG8_SB(0, 0), b2, voffB); PG8_STAGE(PG8_SB(0, 1), b2 + hstep, voffB); PG8_STAGE(PG8_SA(0, 0), a2, voffA);
;             PG8_WAIT_V(8); PG8_WAIT_L(0); PG8_BAR; PG8_MMA(1, 0, At, B0); PG8_MMA(1, 1, At, B1); PG8_BAR; PG8_SCHED;
.Lsgi_peel:
	ds_read_b128 v[140:143], v254
	ds_read_b128 v[162:165], v254 offset:1024
	ds_read_b128 v[166:169], v254 offset:2048
	ds_read_b128 v[170:173], v254 offset:3072
	ds_read_b128 v[180:183], v254 offset:16384
	ds_read_b128 v[184:187], v254 offset:17408
	ds_read_b128 v[188:191], v254 offset:18432
	ds_read_b128 v[210:213], v254 offset:19456
	s_add_u32 s2, s0, 0xfffc0080
	s_addc_u32 s3, s1, -1
	s_cmp_eq_u32 s55, 12
	s_cselect_b32 s5, s13, s3
	s_cselect_b32 s4, s25, s2
	s_cselect_b32 s3, s23, s39
	s_cselect_b32 s2, s33, s38
	s_add_i32 m0, s6, 0xc000
	ds_read_b128 v[214:217], v178
	ds_read_b128 v[218:221], v178 offset:1024
	ds_read_b128 v[222:225], v178 offset:2048
	ds_read_b128 v[226:229], v178 offset:3072
	ds_read_b128 v[230:233], v178 offset:4096
	ds_read_b128 v[234:237], v178 offset:5120
	ds_read_b128 v[238:241], v178 offset:6144
	ds_read_b128 v[242:245], v178 offset:7168
	global_load_lds_dwordx4 v136, s[0:1]
	s_add_i32 m0, s6, 0xe000
	s_nop 0
	global_load_lds_dwordx4 v138, s[0:1]
	s_waitcnt vmcnt(8)
	s_waitcnt lgkmcnt(0)
	s_barrier
	s_setprio 1
	v_mfma_f32_16x16x32_bf16 v[124:127], v[140:143], v[214:217], 0
	v_mfma_f32_16x16x32_bf16 v[124:127], v[162:165], v[218:221], v[124:127]
	v_mfma_f32_16x16x32_bf16 v[120:123], v[166:169], v[214:217], 0
	v_mfma_f32_16x16x32_bf16 v[120:123], v[170:173], v[218:221], v[120:123]
	v_mfma_f32_16x16x32_bf16 v[116:119], v[180:183], v[214:217], 0
	v_mfma_f32_16x16x32_bf16 v[116:119], v[184:187], v[218:221], v[116:119]
	v_mfma_f32_16x16x32_bf16 v[112:115], v[188:191], v[214:217], 0
	v_mfma_f32_16x16x32_bf16 v[112:115], v[210:213], v[218:221], v[112:115]
	v_mfma_f32_16x16x32_bf16 v[108:111], v[140:143], v[222:225], 0
	v_mfma_f32_16x16x32_bf16 v[108:111], v[162:165], v[226:229], v[108:111]
	v_mfma_f32_16x16x32_bf16 v[104:107], v[166:169], v[222:225], 0
	v_mfma_f32_16x16x32_bf16 v[104:107], v[170:173], v[226:229], v[104:107]
	v_mfma_f32_16x16x32_bf16 v[100:103], v[180:183], v[222:225], 0
	v_mfma_f32_16x16x32_bf16 v[100:103], v[184:187], v[226:229], v[100:103]
	v_mfma_f32_16x16x32_bf16 v[96:99], v[188:191], v[222:225], 0
	v_mfma_f32_16x16x32_bf16 v[96:99], v[210:213], v[226:229], v[96:99]
	v_mfma_f32_16x16x32_bf16 v[92:95], v[140:143], v[230:233], 0
	v_mfma_f32_16x16x32_bf16 v[92:95], v[162:165], v[234:237], v[92:95]
	v_mfma_f32_16x16x32_bf16 v[88:91], v[166:169], v[230:233], 0
	v_mfma_f32_16x16x32_bf16 v[88:91], v[170:173], v[234:237], v[88:91]
	v_mfma_f32_16x16x32_bf16 v[84:87], v[180:183], v[230:233], 0
	v_mfma_f32_16x16x32_bf16 v[84:87], v[184:187], v[234:237], v[84:87]
	v_mfma_f32_16x16x32_bf16 v[80:83], v[188:191], v[230:233], 0
	v_mfma_f32_16x16x32_bf16 v[80:83], v[210:213], v[234:237], v[80:83]
	v_mfma_f32_16x16x32_bf16 v[76:79], v[140:143], v[238:241], 0
	v_mfma_f32_16x16x32_bf16 v[76:79], v[162:165], v[242:245], v[76:79]
	v_mfma_f32_16x16x32_bf16 v[72:75], v[166:169], v[238:241], 0
	v_mfma_f32_16x16x32_bf16 v[72:75], v[170:173], v[242:245], v[72:75]
	v_mfma_f32_16x16x32_bf16 v[68:71], v[180:183], v[238:241], 0
	v_mfma_f32_16x16x32_bf16 v[68:71], v[184:187], v[242:245], v[68:71]
	v_mfma_f32_16x16x32_bf16 v[64:67], v[188:191], v[238:241], 0
	v_mfma_f32_16x16x32_bf16 v[64:67], v[210:213], v[242:245], v[64:67]
	s_setprio 0
	s_barrier
	s_mov_b32 m0, s31
	s_add_u32 s56, s2, 0x40000
	s_addc_u32 s57, s3, 0
	ds_read_b128 v[214:217], v178 offset:16384
	ds_read_b128 v[218:221], v178 offset:17408
	ds_read_b128 v[222:225], v178 offset:18432
	ds_read_b128 v[226:229], v178 offset:19456
	ds_read_b128 v[230:233], v178 offset:20480
	ds_read_b128 v[234:237], v178 offset:21504
	ds_read_b128 v[238:241], v178 offset:22528
	ds_read_b128 v[242:245], v178 offset:23552
	global_load_lds_dwordx4 v132, s[2:3]
	s_mov_b32 m0, s34
	s_nop 0
	global_load_lds_dwordx4 v128, s[2:3]
	s_mov_b32 m0, s35
	s_nop 0
	global_load_lds_dwordx4 v132, s[56:57]
	s_mov_b32 m0, s40
	s_nop 0
	global_load_lds_dwordx4 v128, s[56:57]
	s_mov_b32 m0, s6
	s_nop 0
	global_load_lds_dwordx4 v134, s[4:5]
	s_mov_b32 m0, s41
	s_nop 0
	global_load_lds_dwordx4 v130, s[4:5]
	s_waitcnt vmcnt(8)
	s_waitcnt lgkmcnt(0)
	s_barrier
	s_setprio 1
	v_mfma_f32_16x16x32_bf16 v[60:63], v[140:143], v[214:217], 0
	v_mfma_f32_16x16x32_bf16 v[60:63], v[162:165], v[218:221], v[60:63]
	v_mfma_f32_16x16x32_bf16 v[56:59], v[166:169], v[214:217], 0
	v_mfma_f32_16x16x32_bf16 v[56:59], v[170:173], v[218:221], v[56:59]
	v_mfma_f32_16x16x32_bf16 v[52:55], v[180:183], v[214:217], 0
	v_mfma_f32_16x16x32_bf16 v[52:55], v[184:187], v[218:221], v[52:55]
	v_mfma_f32_16x16x32_bf16 v[48:51], v[188:191], v[214:217], 0
	v_mfma_f32_16x16x32_bf16 v[48:51], v[210:213], v[218:221], v[48:51]
	v_mfma_f32_16x16x32_bf16 v[44:47], v[140:143], v[222:225], 0
	v_mfma_f32_16x16x32_bf16 v[44:47], v[162:165], v[226:229], v[44:47]
	v_mfma_f32_16x16x32_bf16 v[40:43], v[166:169], v[222:225], 0
	v_mfma_f32_16x16x32_bf16 v[40:43], v[170:173], v[226:229], v[40:43]
	v_mfma_f32_16x16x32_bf16 v[36:39], v[180:183], v[222:225], 0
	v_mfma_f32_16x16x32_bf16 v[36:39], v[184:187], v[226:229], v[36:39]
	v_mfma_f32_16x16x32_bf16 v[32:35], v[188:191], v[222:225], 0
	v_mfma_f32_16x16x32_bf16 v[32:35], v[210:213], v[226:229], v[32:35]
	v_mfma_f32_16x16x32_bf16 v[28:31], v[140:143], v[230:233], 0
	v_mfma_f32_16x16x32_bf16 v[28:31], v[162:165], v[234:237], v[28:31]
	v_mfma_f32_16x16x32_bf16 v[24:27], v[166:169], v[230:233], 0
	v_mfma_f32_16x16x32_bf16 v[24:27], v[170:173], v[234:237], v[24:27]
	v_mfma_f32_16x16x32_bf16 v[20:23], v[180:183], v[230:233], 0
	v_mfma_f32_16x16x32_bf16 v[20:23], v[184:187], v[234:237], v[20:23]
	v_mfma_f32_16x16x32_bf16 v[16:19], v[188:191], v[230:233], 0
	v_mfma_f32_16x16x32_bf16 v[16:19], v[210:213], v[234:237], v[16:19]
	v_mfma_f32_16x16x32_bf16 v[12:15], v[140:143], v[238:241], 0
	v_mfma_f32_16x16x32_bf16 v[12:15], v[162:165], v[242:245], v[12:15]
	v_mfma_f32_16x16x32_bf16 v[8:11], v[166:169], v[238:241], 0
	v_mfma_f32_16x16x32_bf16 v[8:11], v[170:173], v[242:245], v[8:11]
	v_mfma_f32_16x16x32_bf16 v[4:7], v[180:183], v[238:241], 0
	v_mfma_f32_16x16x32_bf16 v[4:7], v[184:187], v[242:245], v[4:7]
	v_mfma_f32_16x16x32_bf16 v[0:3], v[188:191], v[238:241], 0
	v_mfma_f32_16x16x32_bf16 v[0:3], v[210:213], v[242:245], v[0:3]
	s_setprio 0
	s_barrier
; #define PG8_STAGE(bufoff, gbase, voff) do { _Pragma("unroll") for (int _i = 0; _i < 2; ++_i) \
;         __builtin_amdgcn_global_load_lds((const unsigned*)((const char*)(gbase) + (voff)[_i]), (PG8_LAS unsigned*)(lds + (bufoff) + ldsw + _i * 8192), 16, 0, 0); } while (0)
; #define PG8_LDA(dst, b, h) do { _Pragma("unroll") for (int m = 0; m < 4; ++m) _Pragma("unroll") for (int k = 0; k < 2; ++k) dst[m][k] = *(const PG8_LAS bf16x8*)(lds + PG8_SA(b, h) + aoff + m * 2048 + k * 1024); } while (0)
; #define PG8_LDB(dst, b, h) do { _Pragma("unroll") for (int n = 0; n < 2; ++n) _Pragma("unroll") for (int k = 0; k < 2; ++k) dst[n][k] = *(const PG8_LAS bf16x8*)(lds + PG8_SB(b, h) + boff + n * 2048 + k * 1024); } while (0)
; #define PG8_MMA(ai, bj, At, Bt) do { __builtin_amdgcn_s_setprio(1); _Pragma("unroll") for (int m = 0; m < 4; ++m) _Pragma("unroll") for (int n = 0; n < 2; ++n) _Pragma("unroll") for (int k = 0; k < 2; ++k) \
;         acc[ai][bj][m][n] = __builtin_amdgcn_mfma_f32_16x16x32_bf16(Bt[n][k], At[m][k], acc[ai][bj][m][n], 0, 0, 0); __builtin_amdgcn_s_setprio(0); } while (0)
; #define PG8_WAIT_V(n) asm volatile("s_waitcnt vmcnt(" #n ")" ::: "memory")
; #define PG8_WAIT_L(n) asm volatile("s_waitcnt lgkmcnt(" #n ")" ::: "memory")
; #define PG8_BAR __builtin_amdgcn_s_barrier()
; #define PG8_SCHED __builtin_amdgcn_sched_barrier(0)
; template <class Epi, class Sched, bool ALIGN_EPI = false, bool SP2 = false>
; __device__ __forceinline__ void gemm_phase(PG8_LAS unsigned char* lds, const Gemm g, const Sched& S, const Epi& E) {
;     ...
;         for (int t = 0; t < nt; t += 2) {
;     ...
;             PG8_LDB(B0, 1, 0); PG8_LDB(B1, 1, 1); PG8_SCHED; PG8_LDA(At, 1, 0); PG8_STAGE(PG8_SA(0, 1), a2 + hstep, voffA);
;             PG8_WAIT_V(8); PG8_WAIT_L(0); PG8_BAR; PG8_MMA(0, 0, At, B0); PG8_MMA(0, 1, At, B1); PG8_BAR; PG8_SCHED;
;             PG8_LDA(At, 1, 1); PG8_STAGE(PG8_SB(1, 0), b3, voffB); PG8_STAGE(PG8_SB(1, 1), b3 + hstep, voffB); PG8_STAGE(PG8_SA(1, 0), a3, voffA);
;             PG8_WAIT_V(8); PG8_WAIT_L(0); PG8_BAR; PG8_MMA(1, 0, At, B0); PG8_MMA(1, 1, At, B1); PG8_BAR; PG8_SCHED;
	ds_read_b128 v[140:143], v254 offset:32768
	ds_read_b128 v[162:165], v254 offset:33792
	ds_read_b128 v[166:169], v254 offset:34816
	ds_read_b128 v[170:173], v254 offset:35840
	ds_read_b128 v[180:183], v254 offset:49152
	ds_read_b128 v[184:187], v254 offset:50176
	ds_read_b128 v[188:191], v254 offset:51200
	ds_read_b128 v[210:213], v254 offset:52224
	s_add_u32 s4, s4, 0x40000
	s_addc_u32 s5, s5, 0
	s_mov_b32 m0, s42
	ds_read_b128 v[214:217], v178 offset:32768
	ds_read_b128 v[218:221], v178 offset:33792
	ds_read_b128 v[222:225], v178 offset:34816
	ds_read_b128 v[226:229], v178 offset:35840
	ds_read_b128 v[230:233], v178 offset:36864
	ds_read_b128 v[234:237], v178 offset:37888
	ds_read_b128 v[238:241], v178 offset:38912
	ds_read_b128 v[242:245], v178 offset:39936
	global_load_lds_dwordx4 v134, s[4:5]
	s_mov_b32 m0, s43
	s_nop 0
	global_load_lds_dwordx4 v130, s[4:5]
	s_waitcnt vmcnt(8)
	s_waitcnt lgkmcnt(0)
	s_barrier
	s_setprio 1
	v_mfma_f32_16x16x32_bf16 v[124:127], v[140:143], v[214:217], v[124:127]
	v_mfma_f32_16x16x32_bf16 v[124:127], v[162:165], v[218:221], v[124:127]
	v_mfma_f32_16x16x32_bf16 v[120:123], v[166:169], v[214:217], v[120:123]
	v_mfma_f32_16x16x32_bf16 v[120:123], v[170:173], v[218:221], v[120:123]
	v_mfma_f32_16x16x32_bf16 v[116:119], v[180:183], v[214:217], v[116:119]
	v_mfma_f32_16x16x32_bf16 v[116:119], v[184:187], v[218:221], v[116:119]
	v_mfma_f32_16x16x32_bf16 v[112:115], v[188:191], v[214:217], v[112:115]
	v_mfma_f32_16x16x32_bf16 v[112:115], v[210:213], v[218:221], v[112:115]
	v_mfma_f32_16x16x32_bf16 v[108:111], v[140:143], v[222:225], v[108:111]
	v_mfma_f32_16x16x32_bf16 v[108:111], v[162:165], v[226:229], v[108:111]
	v_mfma_f32_16x16x32_bf16 v[104:107], v[166:169], v[222:225], v[104:107]
	v_mfma_f32_16x16x32_bf16 v[104:107], v[170:173], v[226:229], v[104:107]
	v_mfma_f32_16x16x32_bf16 v[100:103], v[180:183], v[222:225], v[100:103]
	v_mfma_f32_16x16x32_bf16 v[100:103], v[184:187], v[226:229], v[100:103]
	v_mfma_f32_16x16x32_bf16 v[96:99], v[188:191], v[222:225], v[96:99]
	v_mfma_f32_16x16x32_bf16 v[96:99], v[210:213], v[226:229], v[96:99]
	v_mfma_f32_16x16x32_bf16 v[92:95], v[140:143], v[230:233], v[92:95]
	v_mfma_f32_16x16x32_bf16 v[92:95], v[162:165], v[234:237], v[92:95]
	v_mfma_f32_16x16x32_bf16 v[88:91], v[166:169], v[230:233], v[88:91]
	v_mfma_f32_16x16x32_bf16 v[88:91], v[170:173], v[234:237], v[88:91]
	v_mfma_f32_16x16x32_bf16 v[84:87], v[180:183], v[230:233], v[84:87]
	v_mfma_f32_16x16x32_bf16 v[84:87], v[184:187], v[234:237], v[84:87]
	v_mfma_f32_16x16x32_bf16 v[80:83], v[188:191], v[230:233], v[80:83]
	v_mfma_f32_16x16x32_bf16 v[80:83], v[210:213], v[234:237], v[80:83]
	v_mfma_f32_16x16x32_bf16 v[76:79], v[140:143], v[238:241], v[76:79]
	v_mfma_f32_16x16x32_bf16 v[76:79], v[162:165], v[242:245], v[76:79]
	v_mfma_f32_16x16x32_bf16 v[72:75], v[166:169], v[238:241], v[72:75]
	v_mfma_f32_16x16x32_bf16 v[72:75], v[170:173], v[242:245], v[72:75]
	v_mfma_f32_16x16x32_bf16 v[68:71], v[180:183], v[238:241], v[68:71]
	v_mfma_f32_16x16x32_bf16 v[68:71], v[184:187], v[242:245], v[68:71]
	v_mfma_f32_16x16x32_bf16 v[64:67], v[188:191], v[238:241], v[64:67]
	v_mfma_f32_16x16x32_bf16 v[64:67], v[210:213], v[242:245], v[64:67]
	s_setprio 0
	s_barrier
	s_mov_b32 m0, s48
	s_add_u32 s2, s2, 0x40080
	s_addc_u32 s3, s3, 0
	ds_read_b128 v[214:217], v178 offset:49152
	ds_read_b128 v[218:221], v178 offset:50176
	ds_read_b128 v[222:225], v178 offset:51200
	ds_read_b128 v[226:229], v178 offset:52224
	ds_read_b128 v[230:233], v178 offset:53248
	ds_read_b128 v[234:237], v178 offset:54272
	ds_read_b128 v[238:241], v178 offset:55296
	ds_read_b128 v[242:245], v178 offset:56320
	s_add_u32 s98, s2, 0xfffc0000
	s_addc_u32 s99, s3, -1
	global_load_lds_dwordx4 v132, s[98:99]
	s_mov_b32 m0, s49
	s_nop 0
	global_load_lds_dwordx4 v128, s[98:99]
	s_mov_b32 m0, s52
	s_nop 0
	global_load_lds_dwordx4 v132, s[2:3]
	s_mov_b32 m0, s53
	s_nop 0
	global_load_lds_dwordx4 v128, s[2:3]
	s_mov_b32 m0, s50
	s_nop 0
	s_add_u32 s100, s4, 0xfffc0080
	s_addc_u32 s101, s5, -1
	global_load_lds_dwordx4 v134, s[100:101]
	s_mov_b32 m0, s51
	s_nop 0
	global_load_lds_dwordx4 v130, s[100:101]
	s_waitcnt vmcnt(8)
	s_waitcnt lgkmcnt(0)
	s_barrier
	s_setprio 1
	v_mfma_f32_16x16x32_bf16 v[60:63], v[140:143], v[214:217], v[60:63]
	v_mfma_f32_16x16x32_bf16 v[60:63], v[162:165], v[218:221], v[60:63]
	v_mfma_f32_16x16x32_bf16 v[56:59], v[166:169], v[214:217], v[56:59]
	v_mfma_f32_16x16x32_bf16 v[56:59], v[170:173], v[218:221], v[56:59]
	v_mfma_f32_16x16x32_bf16 v[52:55], v[180:183], v[214:217], v[52:55]
	v_mfma_f32_16x16x32_bf16 v[52:55], v[184:187], v[218:221], v[52:55]
	v_mfma_f32_16x16x32_bf16 v[48:51], v[188:191], v[214:217], v[48:51]
	v_mfma_f32_16x16x32_bf16 v[48:51], v[210:213], v[218:221], v[48:51]
	v_mfma_f32_16x16x32_bf16 v[44:47], v[140:143], v[222:225], v[44:47]
	v_mfma_f32_16x16x32_bf16 v[44:47], v[162:165], v[226:229], v[44:47]
	v_mfma_f32_16x16x32_bf16 v[40:43], v[166:169], v[222:225], v[40:43]
	v_mfma_f32_16x16x32_bf16 v[40:43], v[170:173], v[226:229], v[40:43]
	v_mfma_f32_16x16x32_bf16 v[36:39], v[180:183], v[222:225], v[36:39]
	v_mfma_f32_16x16x32_bf16 v[36:39], v[184:187], v[226:229], v[36:39]
	v_mfma_f32_16x16x32_bf16 v[32:35], v[188:191], v[222:225], v[32:35]
	v_mfma_f32_16x16x32_bf16 v[32:35], v[210:213], v[226:229], v[32:35]
	v_mfma_f32_16x16x32_bf16 v[28:31], v[140:143], v[230:233], v[28:31]
	v_mfma_f32_16x16x32_bf16 v[28:31], v[162:165], v[234:237], v[28:31]
	v_mfma_f32_16x16x32_bf16 v[24:27], v[166:169], v[230:233], v[24:27]
	v_mfma_f32_16x16x32_bf16 v[24:27], v[170:173], v[234:237], v[24:27]
	v_mfma_f32_16x16x32_bf16 v[20:23], v[180:183], v[230:233], v[20:23]
	v_mfma_f32_16x16x32_bf16 v[20:23], v[184:187], v[234:237], v[20:23]
	v_mfma_f32_16x16x32_bf16 v[16:19], v[188:191], v[230:233], v[16:19]
	v_mfma_f32_16x16x32_bf16 v[16:19], v[210:213], v[234:237], v[16:19]
	v_mfma_f32_16x16x32_bf16 v[12:15], v[140:143], v[238:241], v[12:15]
	v_mfma_f32_16x16x32_bf16 v[12:15], v[162:165], v[242:245], v[12:15]
	v_mfma_f32_16x16x32_bf16 v[8:11], v[166:169], v[238:241], v[8:11]
	v_mfma_f32_16x16x32_bf16 v[8:11], v[170:173], v[242:245], v[8:11]
	v_mfma_f32_16x16x32_bf16 v[4:7], v[180:183], v[238:241], v[4:7]
	v_mfma_f32_16x16x32_bf16 v[4:7], v[184:187], v[242:245], v[4:7]
	v_mfma_f32_16x16x32_bf16 v[0:3], v[188:191], v[238:241], v[0:3]
	v_mfma_f32_16x16x32_bf16 v[0:3], v[210:213], v[242:245], v[0:3]
	s_setprio 0
	s_barrier
	s_add_i32 s55, s55, 2
	s_add_u32 s0, s0, 0x100
	s_addc_u32 s1, s1, 0
	s_add_u32 s38, s38, 0x100
	s_addc_u32 s39, s39, 0
	s_cmp_gt_u32 s55, 13
; #define PG8_STAGE(bufoff, gbase, voff) do { _Pragma("unroll") for (int _i = 0; _i < 2; ++_i) \
;         __builtin_amdgcn_global_load_lds((const unsigned*)((const char*)(gbase) + (voff)[_i]), (PG8_LAS unsigned*)(lds + (bufoff) + ldsw + _i * 8192), 16, 0, 0); } while (0)
; #define PG8_LDA(dst, b, h) do { _Pragma("unroll") for (int m = 0; m < 4; ++m) _Pragma("unroll") for (int k = 0; k < 2; ++k) dst[m][k] = *(const PG8_LAS bf16x8*)(lds + PG8_SA(b, h) + aoff + m * 2048 + k * 1024); } while (0)
; #define PG8_LDB(dst, b, h) do { _Pragma("unroll") for (int n = 0; n < 2; ++n) _Pragma("unroll") for (int k = 0; k < 2; ++k) dst[n][k] = *(const PG8_LAS bf16x8*)(lds + PG8_SB(b, h) + boff + n * 2048 + k * 1024); } while (0)
; #define PG8_MMA(ai, bj, At, Bt) do { __builtin_amdgcn_s_setprio(1); _Pragma("unroll") for (int m = 0; m < 4; ++m) _Pragma("unroll") for (int n = 0; n < 2; ++n) _Pragma("unroll") for (int k = 0; k < 2; ++k) \
;         acc[ai][bj][m][n] = __builtin_amdgcn_mfma_f32_16x16x32_bf16(Bt[n][k], At[m][k], acc[ai][bj][m][n], 0, 0, 0); __builtin_amdgcn_s_setprio(0); } while (0)
; #define PG8_WAIT_V(n) asm volatile("s_waitcnt vmcnt(" #n ")" ::: "memory")
; #define PG8_BAR __builtin_amdgcn_s_barrier()
; template <class Epi, class Sched, bool ALIGN_EPI = false, bool SP2 = false>
; __device__ __forceinline__ void gemm_phase(PG8_LAS unsigned char* lds, const Gemm g, const Sched& S, const Epi& E) {
;     ...
;         for (int t = 0; t < nt; t += 2) {
;             const bool last = (t == nt - 2);
;             const char* a1 = cA + (size_t)(t + 1) * kstep;
;             const char* a2 = last ? nA : cA + (size_t)(t + 2) * kstep; const char* b2 = last ? nB : cB + (size_t)(t + 2) * kstep;
;             const char* a3 = a2 + kstep; const char* b3 = b2 + kstep;
;             if (last && has_next) S.a_ready(nxt);
;             if constexpr (SP2) {
;             PG8_LDB(B0, 0, 0); PG8_LDB(B1, 0, 1); PG8_SCHED; PG8_LDA(At, 0, 0); PG8_STAGE(PG8_SA(1, 1), a1 + hstep, voffA);
;             PG8_WAIT_V(8); PG8_WAIT_L(0); PG8_BAR; PG8_MMA(0, 0, At, B0); PG8_MMA(0, 1, At, B1); PG8_BAR; PG8_SCHED;
;             PG8_LDA(At, 0, 1); PG8_STAGE(PG8_SB(0, 0), b2, voffB); PG8_STAGE(PG8_SB(0, 1), b2 + hstep, voffB); PG8_STAGE(PG8_SA(0, 0), a2, voffA);
;             PG8_WAIT_V(8); PG8_WAIT_L(0); PG8_BAR; PG8_MMA(1, 0, At, B0); PG8_MMA(1, 1, At, B1); PG8_BAR; PG8_SCHED;
.LBB0_749:
	ds_read_b128 v[140:143], v254
	ds_read_b128 v[162:165], v254 offset:1024
	ds_read_b128 v[166:169], v254 offset:2048
	ds_read_b128 v[170:173], v254 offset:3072
	ds_read_b128 v[180:183], v254 offset:16384
	ds_read_b128 v[184:187], v254 offset:17408
	ds_read_b128 v[188:191], v254 offset:18432
	ds_read_b128 v[210:213], v254 offset:19456
	s_add_u32 s2, s0, 0xfffc0080
	s_addc_u32 s3, s1, -1
	s_cmp_eq_u32 s55, 12
	s_cselect_b32 s5, s13, s3
	s_cselect_b32 s4, s25, s2
	s_cselect_b32 s3, s23, s39
	s_cselect_b32 s2, s33, s38
	s_add_i32 m0, s6, 0xc000
	ds_read_b128 v[214:217], v178
	ds_read_b128 v[218:221], v178 offset:1024
	ds_read_b128 v[222:225], v178 offset:2048
	ds_read_b128 v[226:229], v178 offset:3072
	ds_read_b128 v[230:233], v178 offset:4096
	ds_read_b128 v[234:237], v178 offset:5120
	ds_read_b128 v[238:241], v178 offset:6144
	ds_read_b128 v[242:245], v178 offset:7168
	global_load_lds_dwordx4 v136, s[0:1]
	s_add_i32 m0, s6, 0xe000
	s_nop 0
	global_load_lds_dwordx4 v138, s[0:1]
	s_waitcnt vmcnt(8)
	s_waitcnt lgkmcnt(0)
	s_barrier
	s_setprio 1
	v_mfma_f32_16x16x32_bf16 v[124:127], v[140:143], v[214:217], v[124:127]
	v_mfma_f32_16x16x32_bf16 v[124:127], v[162:165], v[218:221], v[124:127]
	v_mfma_f32_16x16x32_bf16 v[120:123], v[166:169], v[214:217], v[120:123]
	v_mfma_f32_16x16x32_bf16 v[120:123], v[170:173], v[218:221], v[120:123]
	v_mfma_f32_16x16x32_bf16 v[116:119], v[180:183], v[214:217], v[116:119]
	v_mfma_f32_16x16x32_bf16 v[116:119], v[184:187], v[218:221], v[116:119]
	v_mfma_f32_16x16x32_bf16 v[112:115], v[188:191], v[214:217], v[112:115]
	v_mfma_f32_16x16x32_bf16 v[112:115], v[210:213], v[218:221], v[112:115]
	v_mfma_f32_16x16x32_bf16 v[108:111], v[140:143], v[222:225], v[108:111]
	v_mfma_f32_16x16x32_bf16 v[108:111], v[162:165], v[226:229], v[108:111]
	v_mfma_f32_16x16x32_bf16 v[104:107], v[166:169], v[222:225], v[104:107]
	v_mfma_f32_16x16x32_bf16 v[104:107], v[170:173], v[226:229], v[104:107]
	v_mfma_f32_16x16x32_bf16 v[100:103], v[180:183], v[222:225], v[100:103]
	v_mfma_f32_16x16x32_bf16 v[100:103], v[184:187], v[226:229], v[100:103]
	v_mfma_f32_16x16x32_bf16 v[96:99], v[188:191], v[222:225], v[96:99]
	v_mfma_f32_16x16x32_bf16 v[96:99], v[210:213], v[226:229], v[96:99]
	v_mfma_f32_16x16x32_bf16 v[92:95], v[140:143], v[230:233], v[92:95]
	v_mfma_f32_16x16x32_bf16 v[92:95], v[162:165], v[234:237], v[92:95]
	v_mfma_f32_16x16x32_bf16 v[88:91], v[166:169], v[230:233], v[88:91]
	v_mfma_f32_16x16x32_bf16 v[88:91], v[170:173], v[234:237], v[88:91]
	v_mfma_f32_16x16x32_bf16 v[84:87], v[180:183], v[230:233], v[84:87]
	v_mfma_f32_16x16x32_bf16 v[84:87], v[184:187], v[234:237], v[84:87]
	v_mfma_f32_16x16x32_bf16 v[80:83], v[188:191], v[230:233], v[80:83]
	v_mfma_f32_16x16x32_bf16 v[80:83], v[210:213], v[234:237], v[80:83]
	v_mfma_f32_16x16x32_bf16 v[76:79], v[140:143], v[238:241], v[76:79]
	v_mfma_f32_16x16x32_bf16 v[76:79], v[162:165], v[242:245], v[76:79]
	v_mfma_f32_16x16x32_bf16 v[72:75], v[166:169], v[238:241], v[72:75]
	v_mfma_f32_16x16x32_bf16 v[72:75], v[170:173], v[242:245], v[72:75]
	v_mfma_f32_16x16x32_bf16 v[68:71], v[180:183], v[238:241], v[68:71]
	v_mfma_f32_16x16x32_bf16 v[68:71], v[184:187], v[242:245], v[68:71]
	v_mfma_f32_16x16x32_bf16 v[64:67], v[188:191], v[238:241], v[64:67]
	v_mfma_f32_16x16x32_bf16 v[64:67], v[210:213], v[242:245], v[64:67]
	s_setprio 0
	s_barrier
	s_mov_b32 m0, s31
	s_add_u32 s56, s2, 0x40000
	s_addc_u32 s57, s3, 0
	ds_read_b128 v[214:217], v178 offset:16384
	ds_read_b128 v[218:221], v178 offset:17408
	ds_read_b128 v[222:225], v178 offset:18432
	ds_read_b128 v[226:229], v178 offset:19456
	ds_read_b128 v[230:233], v178 offset:20480
	ds_read_b128 v[234:237], v178 offset:21504
	ds_read_b128 v[238:241], v178 offset:22528
	ds_read_b128 v[242:245], v178 offset:23552
	global_load_lds_dwordx4 v132, s[2:3]
	s_mov_b32 m0, s34
	s_nop 0
	global_load_lds_dwordx4 v128, s[2:3]
	s_mov_b32 m0, s35
	s_nop 0
	global_load_lds_dwordx4 v132, s[56:57]
	s_mov_b32 m0, s40
	s_nop 0
	global_load_lds_dwordx4 v128, s[56:57]
	s_mov_b32 m0, s6
	s_nop 0
	global_load_lds_dwordx4 v134, s[4:5]
	s_mov_b32 m0, s41
	s_nop 0
	global_load_lds_dwordx4 v130, s[4:5]
	s_waitcnt vmcnt(8)
	s_waitcnt lgkmcnt(0)
	s_barrier
	s_setprio 1
	v_mfma_f32_16x16x32_bf16 v[60:63], v[140:143], v[214:217], v[60:63]
	v_mfma_f32_16x16x32_bf16 v[60:63], v[162:165], v[218:221], v[60:63]
	v_mfma_f32_16x16x32_bf16 v[56:59], v[166:169], v[214:217], v[56:59]
	v_mfma_f32_16x16x32_bf16 v[56:59], v[170:173], v[218:221], v[56:59]
	v_mfma_f32_16x16x32_bf16 v[52:55], v[180:183], v[214:217], v[52:55]
	v_mfma_f32_16x16x32_bf16 v[52:55], v[184:187], v[218:221], v[52:55]
	v_mfma_f32_16x16x32_bf16 v[48:51], v[188:191], v[214:217], v[48:51]
	v_mfma_f32_16x16x32_bf16 v[48:51], v[210:213], v[218:221], v[48:51]
	v_mfma_f32_16x16x32_bf16 v[44:47], v[140:143], v[222:225], v[44:47]
	v_mfma_f32_16x16x32_bf16 v[44:47], v[162:165], v[226:229], v[44:47]
	v_mfma_f32_16x16x32_bf16 v[40:43], v[166:169], v[222:225], v[40:43]
	v_mfma_f32_16x16x32_bf16 v[40:43], v[170:173], v[226:229], v[40:43]
	v_mfma_f32_16x16x32_bf16 v[36:39], v[180:183], v[222:225], v[36:39]
	v_mfma_f32_16x16x32_bf16 v[36:39], v[184:187], v[226:229], v[36:39]
	v_mfma_f32_16x16x32_bf16 v[32:35], v[188:191], v[222:225], v[32:35]
	v_mfma_f32_16x16x32_bf16 v[32:35], v[210:213], v[226:229], v[32:35]
	v_mfma_f32_16x16x32_bf16 v[28:31], v[140:143], v[230:233], v[28:31]
	v_mfma_f32_16x16x32_bf16 v[28:31], v[162:165], v[234:237], v[28:31]
	v_mfma_f32_16x16x32_bf16 v[24:27], v[166:169], v[230:233], v[24:27]
	v_mfma_f32_16x16x32_bf16 v[24:27], v[170:173], v[234:237], v[24:27]
	v_mfma_f32_16x16x32_bf16 v[20:23], v[180:183], v[230:233], v[20:23]
	v_mfma_f32_16x16x32_bf16 v[20:23], v[184:187], v[234:237], v[20:23]
	v_mfma_f32_16x16x32_bf16 v[16:19], v[188:191], v[230:233], v[16:19]
	v_mfma_f32_16x16x32_bf16 v[16:19], v[210:213], v[234:237], v[16:19]
	v_mfma_f32_16x16x32_bf16 v[12:15], v[140:143], v[238:241], v[12:15]
	v_mfma_f32_16x16x32_bf16 v[12:15], v[162:165], v[242:245], v[12:15]
	v_mfma_f32_16x16x32_bf16 v[8:11], v[166:169], v[238:241], v[8:11]
	v_mfma_f32_16x16x32_bf16 v[8:11], v[170:173], v[242:245], v[8:11]
	v_mfma_f32_16x16x32_bf16 v[4:7], v[180:183], v[238:241], v[4:7]
	v_mfma_f32_16x16x32_bf16 v[4:7], v[184:187], v[242:245], v[4:7]
	v_mfma_f32_16x16x32_bf16 v[0:3], v[188:191], v[238:241], v[0:3]
	v_mfma_f32_16x16x32_bf16 v[0:3], v[210:213], v[242:245], v[0:3]
	s_setprio 0
	s_barrier
; #define PG8_STAGE(bufoff, gbase, voff) do { _Pragma("unroll") for (int _i = 0; _i < 2; ++_i) \
;         __builtin_amdgcn_global_load_lds((const unsigned*)((const char*)(gbase) + (voff)[_i]), (PG8_LAS unsigned*)(lds + (bufoff) + ldsw + _i * 8192), 16, 0, 0); } while (0)
; #define PG8_LDA(dst, b, h) do { _Pragma("unroll") for (int m = 0; m < 4; ++m) _Pragma("unroll") for (int k = 0; k < 2; ++k) dst[m][k] = *(const PG8_LAS bf16x8*)(lds + PG8_SA(b, h) + aoff + m * 2048 + k * 1024); } while (0)
; #define PG8_LDB(dst, b, h) do { _Pragma("unroll") for (int n = 0; n < 2; ++n) _Pragma("unroll") for (int k = 0; k < 2; ++k) dst[n][k] = *(const PG8_LAS bf16x8*)(lds + PG8_SB(b, h) + boff + n * 2048 + k * 1024); } while (0)
; #define PG8_MMA(ai, bj, At, Bt) do { __builtin_amdgcn_s_setprio(1); _Pragma("unroll") for (int m = 0; m < 4; ++m) _Pragma("unroll") for (int n = 0; n < 2; ++n) _Pragma("unroll") for (int k = 0; k < 2; ++k) \
;         acc[ai][bj][m][n] = __builtin_amdgcn_mfma_f32_16x16x32_bf16(Bt[n][k], At[m][k], acc[ai][bj][m][n], 0, 0, 0); __builtin_amdgcn_s_setprio(0); } while (0)
; #define PG8_WAIT_V(n) asm volatile("s_waitcnt vmcnt(" #n ")" ::: "memory")
; #define PG8_WAIT_L(n) asm volatile("s_waitcnt lgkmcnt(" #n ")" ::: "memory")
; #define PG8_BAR __builtin_amdgcn_s_barrier()
; #define PG8_SCHED __builtin_amdgcn_sched_barrier(0)
; template <class Epi, class Sched, bool ALIGN_EPI = false, bool SP2 = false>
; __device__ __forceinline__ void gemm_phase(PG8_LAS unsigned char* lds, const Gemm g, const Sched& S, const Epi& E) {
;     ...
;             PG8_LDB(B0, 1, 0); PG8_LDB(B1, 1, 1); PG8_SCHED; PG8_LDA(At, 1, 0); PG8_STAGE(PG8_SA(0, 1), a2 + hstep, voffA);
;             PG8_WAIT_V(8); PG8_WAIT_L(0); PG8_BAR; PG8_MMA(0, 0, At, B0); PG8_MMA(0, 1, At, B1); PG8_BAR; PG8_SCHED;
;             PG8_LDA(At, 1, 1); PG8_STAGE(PG8_SB(1, 0), b3, voffB); PG8_STAGE(PG8_SB(1, 1), b3 + hstep, voffB); PG8_STAGE(PG8_SA(1, 0), a3, voffA);
;             PG8_WAIT_V(8); PG8_WAIT_L(0); PG8_BAR; PG8_MMA(1, 0, At, B0); PG8_MMA(1, 1, At, B1); PG8_BAR; PG8_SCHED;
;     ...
;         if constexpr (ALIGN_EPI) { if (wr == 0) PG8_BAR; }
	ds_read_b128 v[140:143], v254 offset:32768
	ds_read_b128 v[162:165], v254 offset:33792
	ds_read_b128 v[166:169], v254 offset:34816
	ds_read_b128 v[170:173], v254 offset:35840
	ds_read_b128 v[180:183], v254 offset:49152
	ds_read_b128 v[184:187], v254 offset:50176
	ds_read_b128 v[188:191], v254 offset:51200
	ds_read_b128 v[210:213], v254 offset:52224
	s_add_u32 s4, s4, 0x40000
	s_addc_u32 s5, s5, 0
	s_mov_b32 m0, s42
	ds_read_b128 v[214:217], v178 offset:32768
	ds_read_b128 v[218:221], v178 offset:33792
	ds_read_b128 v[222:225], v178 offset:34816
	ds_read_b128 v[226:229], v178 offset:35840
	ds_read_b128 v[230:233], v178 offset:36864
	ds_read_b128 v[234:237], v178 offset:37888
	ds_read_b128 v[238:241], v178 offset:38912
	ds_read_b128 v[242:245], v178 offset:39936
	global_load_lds_dwordx4 v134, s[4:5]
	s_mov_b32 m0, s43
	s_nop 0
	global_load_lds_dwordx4 v130, s[4:5]
	s_waitcnt vmcnt(8)
	s_waitcnt lgkmcnt(0)
	s_barrier
	s_setprio 1
	v_mfma_f32_16x16x32_bf16 v[124:127], v[140:143], v[214:217], v[124:127]
	v_mfma_f32_16x16x32_bf16 v[124:127], v[162:165], v[218:221], v[124:127]
	v_mfma_f32_16x16x32_bf16 v[120:123], v[166:169], v[214:217], v[120:123]
	v_mfma_f32_16x16x32_bf16 v[120:123], v[170:173], v[218:221], v[120:123]
	v_mfma_f32_16x16x32_bf16 v[116:119], v[180:183], v[214:217], v[116:119]
	v_mfma_f32_16x16x32_bf16 v[116:119], v[184:187], v[218:221], v[116:119]
	v_mfma_f32_16x16x32_bf16 v[112:115], v[188:191], v[214:217], v[112:115]
	v_mfma_f32_16x16x32_bf16 v[112:115], v[210:213], v[218:221], v[112:115]
	v_mfma_f32_16x16x32_bf16 v[108:111], v[140:143], v[222:225], v[108:111]
	v_mfma_f32_16x16x32_bf16 v[108:111], v[162:165], v[226:229], v[108:111]
	v_mfma_f32_16x16x32_bf16 v[104:107], v[166:169], v[222:225], v[104:107]
	v_mfma_f32_16x16x32_bf16 v[104:107], v[170:173], v[226:229], v[104:107]
	v_mfma_f32_16x16x32_bf16 v[100:103], v[180:183], v[222:225], v[100:103]
	v_mfma_f32_16x16x32_bf16 v[100:103], v[184:187], v[226:229], v[100:103]
	v_mfma_f32_16x16x32_bf16 v[96:99], v[188:191], v[222:225], v[96:99]
	v_mfma_f32_16x16x32_bf16 v[96:99], v[210:213], v[226:229], v[96:99]
	v_mfma_f32_16x16x32_bf16 v[92:95], v[140:143], v[230:233], v[92:95]
	v_mfma_f32_16x16x32_bf16 v[92:95], v[162:165], v[234:237], v[92:95]
	v_mfma_f32_16x16x32_bf16 v[88:91], v[166:169], v[230:233], v[88:91]
	v_mfma_f32_16x16x32_bf16 v[88:91], v[170:173], v[234:237], v[88:91]
	v_mfma_f32_16x16x32_bf16 v[84:87], v[180:183], v[230:233], v[84:87]
	v_mfma_f32_16x16x32_bf16 v[84:87], v[184:187], v[234:237], v[84:87]
	v_mfma_f32_16x16x32_bf16 v[80:83], v[188:191], v[230:233], v[80:83]
	v_mfma_f32_16x16x32_bf16 v[80:83], v[210:213], v[234:237], v[80:83]
	v_mfma_f32_16x16x32_bf16 v[76:79], v[140:143], v[238:241], v[76:79]
	v_mfma_f32_16x16x32_bf16 v[76:79], v[162:165], v[242:245], v[76:79]
	v_mfma_f32_16x16x32_bf16 v[72:75], v[166:169], v[238:241], v[72:75]
	v_mfma_f32_16x16x32_bf16 v[72:75], v[170:173], v[242:245], v[72:75]
	v_mfma_f32_16x16x32_bf16 v[68:71], v[180:183], v[238:241], v[68:71]
	v_mfma_f32_16x16x32_bf16 v[68:71], v[184:187], v[242:245], v[68:71]
	v_mfma_f32_16x16x32_bf16 v[64:67], v[188:191], v[238:241], v[64:67]
	v_mfma_f32_16x16x32_bf16 v[64:67], v[210:213], v[242:245], v[64:67]
	s_setprio 0
	s_barrier
	s_mov_b32 m0, s48
	s_add_u32 s2, s2, 0x40080
	s_addc_u32 s3, s3, 0
	ds_read_b128 v[214:217], v178 offset:49152
	ds_read_b128 v[218:221], v178 offset:50176
	ds_read_b128 v[222:225], v178 offset:51200
	ds_read_b128 v[226:229], v178 offset:52224
	ds_read_b128 v[230:233], v178 offset:53248
	ds_read_b128 v[234:237], v178 offset:54272
	ds_read_b128 v[238:241], v178 offset:55296
	ds_read_b128 v[242:245], v178 offset:56320
	s_add_u32 s98, s2, 0xfffc0000
	s_addc_u32 s99, s3, -1
	global_load_lds_dwordx4 v132, s[98:99]
	s_mov_b32 m0, s49
	s_nop 0
	global_load_lds_dwordx4 v128, s[98:99]
	s_mov_b32 m0, s52
	s_nop 0
	global_load_lds_dwordx4 v132, s[2:3]
	s_mov_b32 m0, s53
	s_nop 0
	global_load_lds_dwordx4 v128, s[2:3]
	s_mov_b32 m0, s50
	s_nop 0
	s_add_u32 s100, s4, 0xfffc0080
	s_addc_u32 s101, s5, -1
	global_load_lds_dwordx4 v134, s[100:101]
	s_mov_b32 m0, s51
	s_nop 0
	global_load_lds_dwordx4 v130, s[100:101]
	s_waitcnt vmcnt(8)
	s_waitcnt lgkmcnt(0)
	s_barrier
	s_setprio 1
	v_mfma_f32_16x16x32_bf16 v[60:63], v[140:143], v[214:217], v[60:63]
	v_mfma_f32_16x16x32_bf16 v[60:63], v[162:165], v[218:221], v[60:63]
	v_mfma_f32_16x16x32_bf16 v[56:59], v[166:169], v[214:217], v[56:59]
	v_mfma_f32_16x16x32_bf16 v[56:59], v[170:173], v[218:221], v[56:59]
	v_mfma_f32_16x16x32_bf16 v[52:55], v[180:183], v[214:217], v[52:55]
	v_mfma_f32_16x16x32_bf16 v[52:55], v[184:187], v[218:221], v[52:55]
	v_mfma_f32_16x16x32_bf16 v[48:51], v[188:191], v[214:217], v[48:51]
	v_mfma_f32_16x16x32_bf16 v[48:51], v[210:213], v[218:221], v[48:51]
	v_mfma_f32_16x16x32_bf16 v[44:47], v[140:143], v[222:225], v[44:47]
	v_mfma_f32_16x16x32_bf16 v[44:47], v[162:165], v[226:229], v[44:47]
	v_mfma_f32_16x16x32_bf16 v[40:43], v[166:169], v[222:225], v[40:43]
	v_mfma_f32_16x16x32_bf16 v[40:43], v[170:173], v[226:229], v[40:43]
	v_mfma_f32_16x16x32_bf16 v[36:39], v[180:183], v[222:225], v[36:39]
	v_mfma_f32_16x16x32_bf16 v[36:39], v[184:187], v[226:229], v[36:39]
	v_mfma_f32_16x16x32_bf16 v[32:35], v[188:191], v[222:225], v[32:35]
	v_mfma_f32_16x16x32_bf16 v[32:35], v[210:213], v[226:229], v[32:35]
	v_mfma_f32_16x16x32_bf16 v[28:31], v[140:143], v[230:233], v[28:31]
	v_mfma_f32_16x16x32_bf16 v[28:31], v[162:165], v[234:237], v[28:31]
	v_mfma_f32_16x16x32_bf16 v[24:27], v[166:169], v[230:233], v[24:27]
	v_mfma_f32_16x16x32_bf16 v[24:27], v[170:173], v[234:237], v[24:27]
	v_mfma_f32_16x16x32_bf16 v[20:23], v[180:183], v[230:233], v[20:23]
	v_mfma_f32_16x16x32_bf16 v[20:23], v[184:187], v[234:237], v[20:23]
	v_mfma_f32_16x16x32_bf16 v[16:19], v[188:191], v[230:233], v[16:19]
	v_mfma_f32_16x16x32_bf16 v[16:19], v[210:213], v[234:237], v[16:19]
	v_mfma_f32_16x16x32_bf16 v[12:15], v[140:143], v[238:241], v[12:15]
	v_mfma_f32_16x16x32_bf16 v[12:15], v[162:165], v[242:245], v[12:15]
	v_mfma_f32_16x16x32_bf16 v[8:11], v[166:169], v[238:241], v[8:11]
	v_mfma_f32_16x16x32_bf16 v[8:11], v[170:173], v[242:245], v[8:11]
	v_mfma_f32_16x16x32_bf16 v[4:7], v[180:183], v[238:241], v[4:7]
	v_mfma_f32_16x16x32_bf16 v[4:7], v[184:187], v[242:245], v[4:7]
	v_mfma_f32_16x16x32_bf16 v[0:3], v[188:191], v[238:241], v[0:3]
	v_mfma_f32_16x16x32_bf16 v[0:3], v[210:213], v[242:245], v[0:3]
	s_setprio 0
	s_barrier
	s_add_i32 s55, s55, 2
	s_add_u32 s0, s0, 0x100
	s_addc_u32 s1, s1, 0
	s_add_u32 s38, s38, 0x100
	s_addc_u32 s39, s39, 0
	s_cmp_gt_u32 s55, 13
	s_cbranch_scc0 .LBB0_749
	s_and_b64 vcc, exec, s[18:19]
	s_cbranch_vccz .LBB0_752
	s_barrier

; #define PG8_STAGE(bufoff, gbase, voff) do { _Pragma("unroll") for (int _i = 0; _i < 2; ++_i) \
;         __builtin_amdgcn_global_load_lds((const unsigned*)((const char*)(gbase) + (voff)[_i]), (PG8_LAS unsigned*)(lds + (bufoff) + ldsw + _i * 8192), 16, 0, 0); } while (0)
; #define PG8_LDA(dst, b, h) do { _Pragma("unroll") for (int m = 0; m < 4; ++m) _Pragma("unroll") for (int k = 0; k < 2; ++k) dst[m][k] = *(const PG8_LAS bf16x8*)(lds + PG8_SA(b, h) + aoff + m * 2048 + k * 1024); } while (0)
; #define PG8_LDB(dst, b, h) do { _Pragma("unroll") for (int n = 0; n < 2; ++n) _Pragma("unroll") for (int k = 0; k < 2; ++k) dst[n][k] = *(const PG8_LAS bf16x8*)(lds + PG8_SB(b, h) + boff + n * 2048 + k * 1024); } while (0)
; #define PG8_MMA(ai, bj, At, Bt) do { __builtin_amdgcn_s_setprio(1); _Pragma("unroll") for (int m = 0; m < 4; ++m) _Pragma("unroll") for (int n = 0; n < 2; ++n) _Pragma("unroll") for (int k = 0; k < 2; ++k) \
;         acc[ai][bj][m][n] = __builtin_amdgcn_mfma_f32_16x16x32_bf16(Bt[n][k], At[m][k], acc[ai][bj][m][n], 0, 0, 0); __builtin_amdgcn_s_setprio(0); } while (0)
; #define PG8_WAIT_V(n) asm volatile("s_waitcnt vmcnt(" #n ")" ::: "memory")
; #define PG8_WAIT_L(n) asm volatile("s_waitcnt lgkmcnt(" #n ")" ::: "memory")
; template <class Epi, class Sched, bool ALIGN_EPI = false, bool SP2 = false>
; __device__ __forceinline__ void gemm_phase(PG8_LAS unsigned char* lds, const Gemm g, const Sched& S, const Epi& E) {
;     ...
;             const bool last = (t == nt - 2);
;             const char* a1 = cA + (size_t)(t + 1) * kstep;
;             const char* a2 = last ? nA : cA + (size_t)(t + 2) * kstep; const char* b2 = last ? nB : cB + (size_t)(t + 2) * kstep;
;             const char* a3 = a2 + kstep; const char* b3 = b2 + kstep;
;             if (last && has_next) S.a_ready(nxt);
;             if constexpr (SP2) {
;             PG8_LDB(B0, 0, 0); PG8_LDB(B1, 0, 1); PG8_SCHED; PG8_LDA(At, 0, 0); PG8_STAGE(PG8_SA(1, 1), a1 + hstep, voffA);
;             PG8_WAIT_V(8); PG8_WAIT_L(0); PG8_BAR; PG8_MMA(0, 0, At, B0); PG8_MMA(0, 1, At, B1); PG8_BAR; PG8_SCHED;
;             PG8_LDA(At, 0, 1); PG8_STAGE(PG8_SB(0, 0), b2, voffB); PG8_STAGE(PG8_SB(0, 1), b2 + hstep, voffB); PG8_STAGE(PG8_SA(0, 0), a2, voffA);
;             PG8_WAIT_V(8); PG8_WAIT_L(0); PG8_BAR; PG8_MMA(1, 0, At, B0); PG8_MMA(1, 1, At, B1); PG8_BAR; PG8_SCHED;
.Labi_peel:
	s_waitcnt lgkmcnt(0)
	ds_read_b128 v[140:143], v254
	ds_read_b128 v[162:165], v254 offset:1024
	ds_read_b128 v[166:169], v254 offset:2048
	ds_read_b128 v[176:179], v254 offset:3072
	ds_read_b128 v[180:183], v254 offset:16384
	ds_read_b128 v[184:187], v254 offset:17408
	ds_read_b128 v[188:191], v254 offset:18432
	ds_read_b128 v[210:213], v254 offset:19456
	s_add_u32 s2, s0, 0xfffc0080
	s_addc_u32 s3, s1, -1
	s_cmp_eq_u32 s52, 12
	s_cselect_b32 s5, s17, s3
	s_cselect_b32 s4, s48, s2
	s_cselect_b32 s3, s15, s51
	s_cselect_b32 s2, s49, s50
	s_add_i32 m0, s6, 0xc000
	ds_read_b128 v[214:217], v173
	ds_read_b128 v[218:221], v173 offset:1024
	ds_read_b128 v[222:225], v173 offset:2048
	ds_read_b128 v[226:229], v173 offset:3072
	ds_read_b128 v[230:233], v173 offset:4096
	ds_read_b128 v[234:237], v173 offset:5120
	ds_read_b128 v[238:241], v173 offset:6144
	ds_read_b128 v[242:245], v173 offset:7168
	global_load_lds_dwordx4 v136, s[0:1]
	s_add_i32 m0, s6, 0xe000
	s_nop 0
	global_load_lds_dwordx4 v138, s[0:1]
	s_waitcnt vmcnt(8)
	s_waitcnt lgkmcnt(0)
	s_barrier
	s_setprio 1
	v_mfma_f32_16x16x32_bf16 v[124:127], v[140:143], v[214:217], 0
	v_mfma_f32_16x16x32_bf16 v[124:127], v[162:165], v[218:221], v[124:127]
	v_mfma_f32_16x16x32_bf16 v[120:123], v[166:169], v[214:217], 0
	v_mfma_f32_16x16x32_bf16 v[120:123], v[176:179], v[218:221], v[120:123]
	v_mfma_f32_16x16x32_bf16 v[116:119], v[180:183], v[214:217], 0
	v_mfma_f32_16x16x32_bf16 v[116:119], v[184:187], v[218:221], v[116:119]
	v_mfma_f32_16x16x32_bf16 v[108:111], v[188:191], v[214:217], 0
	v_mfma_f32_16x16x32_bf16 v[108:111], v[210:213], v[218:221], v[108:111]
	v_mfma_f32_16x16x32_bf16 v[112:115], v[140:143], v[222:225], 0
	v_mfma_f32_16x16x32_bf16 v[112:115], v[162:165], v[226:229], v[112:115]
	v_mfma_f32_16x16x32_bf16 v[104:107], v[166:169], v[222:225], 0
	v_mfma_f32_16x16x32_bf16 v[104:107], v[176:179], v[226:229], v[104:107]
	v_mfma_f32_16x16x32_bf16 v[100:103], v[180:183], v[222:225], 0
	v_mfma_f32_16x16x32_bf16 v[100:103], v[184:187], v[226:229], v[100:103]
	v_mfma_f32_16x16x32_bf16 v[92:95], v[188:191], v[222:225], 0
	v_mfma_f32_16x16x32_bf16 v[92:95], v[210:213], v[226:229], v[92:95]
	v_mfma_f32_16x16x32_bf16 v[96:99], v[140:143], v[230:233], 0
	v_mfma_f32_16x16x32_bf16 v[96:99], v[162:165], v[234:237], v[96:99]
	v_mfma_f32_16x16x32_bf16 v[88:91], v[166:169], v[230:233], 0
	v_mfma_f32_16x16x32_bf16 v[88:91], v[176:179], v[234:237], v[88:91]
	v_mfma_f32_16x16x32_bf16 v[84:87], v[180:183], v[230:233], 0
	v_mfma_f32_16x16x32_bf16 v[84:87], v[184:187], v[234:237], v[84:87]
	v_mfma_f32_16x16x32_bf16 v[76:79], v[188:191], v[230:233], 0
	v_mfma_f32_16x16x32_bf16 v[76:79], v[210:213], v[234:237], v[76:79]
	v_mfma_f32_16x16x32_bf16 v[80:83], v[140:143], v[238:241], 0
	v_mfma_f32_16x16x32_bf16 v[80:83], v[162:165], v[242:245], v[80:83]
	v_mfma_f32_16x16x32_bf16 v[72:75], v[166:169], v[238:241], 0
	v_mfma_f32_16x16x32_bf16 v[72:75], v[176:179], v[242:245], v[72:75]
	v_mfma_f32_16x16x32_bf16 v[68:71], v[180:183], v[238:241], 0
	v_mfma_f32_16x16x32_bf16 v[68:71], v[184:187], v[242:245], v[68:71]
	v_mfma_f32_16x16x32_bf16 v[64:67], v[188:191], v[238:241], 0
	v_mfma_f32_16x16x32_bf16 v[64:67], v[210:213], v[242:245], v[64:67]
	s_setprio 0
	s_barrier
	s_mov_b32 m0, s27
	s_add_u32 s54, s2, 0x40000
	s_addc_u32 s55, s3, 0
	ds_read_b128 v[214:217], v173 offset:16384
	ds_read_b128 v[218:221], v173 offset:17408
	ds_read_b128 v[222:225], v173 offset:18432
	ds_read_b128 v[226:229], v173 offset:19456
	ds_read_b128 v[230:233], v173 offset:20480
	ds_read_b128 v[234:237], v173 offset:21504
	ds_read_b128 v[238:241], v173 offset:22528
	ds_read_b128 v[242:245], v173 offset:23552
	global_load_lds_dwordx4 v132, s[2:3]
	s_mov_b32 m0, s28
	s_nop 0
	global_load_lds_dwordx4 v128, s[2:3]
	s_mov_b32 m0, s29
	s_nop 0
	global_load_lds_dwordx4 v132, s[54:55]
	s_mov_b32 m0, s30
	s_nop 0
	global_load_lds_dwordx4 v128, s[54:55]
	s_mov_b32 m0, s6
	s_nop 0
	global_load_lds_dwordx4 v134, s[4:5]
	s_mov_b32 m0, s31
	s_nop 0
	global_load_lds_dwordx4 v130, s[4:5]
	s_waitcnt vmcnt(8)
	s_waitcnt lgkmcnt(0)
	s_barrier
	s_setprio 1
	v_mfma_f32_16x16x32_bf16 v[60:63], v[140:143], v[214:217], 0
	v_mfma_f32_16x16x32_bf16 v[60:63], v[162:165], v[218:221], v[60:63]
	v_mfma_f32_16x16x32_bf16 v[56:59], v[166:169], v[214:217], 0
	v_mfma_f32_16x16x32_bf16 v[56:59], v[176:179], v[218:221], v[56:59]
	v_mfma_f32_16x16x32_bf16 v[52:55], v[180:183], v[214:217], 0
	v_mfma_f32_16x16x32_bf16 v[52:55], v[184:187], v[218:221], v[52:55]
	v_mfma_f32_16x16x32_bf16 v[44:47], v[188:191], v[214:217], 0
	v_mfma_f32_16x16x32_bf16 v[44:47], v[210:213], v[218:221], v[44:47]
	v_mfma_f32_16x16x32_bf16 v[48:51], v[140:143], v[222:225], 0
	v_mfma_f32_16x16x32_bf16 v[48:51], v[162:165], v[226:229], v[48:51]
	v_mfma_f32_16x16x32_bf16 v[40:43], v[166:169], v[222:225], 0
	v_mfma_f32_16x16x32_bf16 v[40:43], v[176:179], v[226:229], v[40:43]
	v_mfma_f32_16x16x32_bf16 v[36:39], v[180:183], v[222:225], 0
	v_mfma_f32_16x16x32_bf16 v[36:39], v[184:187], v[226:229], v[36:39]
	v_mfma_f32_16x16x32_bf16 v[28:31], v[188:191], v[222:225], 0
	v_mfma_f32_16x16x32_bf16 v[28:31], v[210:213], v[226:229], v[28:31]
	v_mfma_f32_16x16x32_bf16 v[32:35], v[140:143], v[230:233], 0
	v_mfma_f32_16x16x32_bf16 v[32:35], v[162:165], v[234:237], v[32:35]
	v_mfma_f32_16x16x32_bf16 v[24:27], v[166:169], v[230:233], 0
	v_mfma_f32_16x16x32_bf16 v[24:27], v[176:179], v[234:237], v[24:27]
	v_mfma_f32_16x16x32_bf16 v[20:23], v[180:183], v[230:233], 0
	v_mfma_f32_16x16x32_bf16 v[20:23], v[184:187], v[234:237], v[20:23]
	v_mfma_f32_16x16x32_bf16 v[12:15], v[188:191], v[230:233], 0
	v_mfma_f32_16x16x32_bf16 v[12:15], v[210:213], v[234:237], v[12:15]
	v_mfma_f32_16x16x32_bf16 v[16:19], v[140:143], v[238:241], 0
	v_mfma_f32_16x16x32_bf16 v[16:19], v[162:165], v[242:245], v[16:19]
	v_mfma_f32_16x16x32_bf16 v[8:11], v[166:169], v[238:241], 0
	v_mfma_f32_16x16x32_bf16 v[8:11], v[176:179], v[242:245], v[8:11]
	v_mfma_f32_16x16x32_bf16 v[4:7], v[180:183], v[238:241], 0
	v_mfma_f32_16x16x32_bf16 v[4:7], v[184:187], v[242:245], v[4:7]
	v_mfma_f32_16x16x32_bf16 v[0:3], v[188:191], v[238:241], 0
	v_mfma_f32_16x16x32_bf16 v[0:3], v[210:213], v[242:245], v[0:3]
	s_setprio 0
	s_barrier
; #define PG8_STAGE(bufoff, gbase, voff) do { _Pragma("unroll") for (int _i = 0; _i < 2; ++_i) \
;         __builtin_amdgcn_global_load_lds((const unsigned*)((const char*)(gbase) + (voff)[_i]), (PG8_LAS unsigned*)(lds + (bufoff) + ldsw + _i * 8192), 16, 0, 0); } while (0)
; #define PG8_LDA(dst, b, h) do { _Pragma("unroll") for (int m = 0; m < 4; ++m) _Pragma("unroll") for (int k = 0; k < 2; ++k) dst[m][k] = *(const PG8_LAS bf16x8*)(lds + PG8_SA(b, h) + aoff + m * 2048 + k * 1024); } while (0)
; #define PG8_LDB(dst, b, h) do { _Pragma("unroll") for (int n = 0; n < 2; ++n) _Pragma("unroll") for (int k = 0; k < 2; ++k) dst[n][k] = *(const PG8_LAS bf16x8*)(lds + PG8_SB(b, h) + boff + n * 2048 + k * 1024); } while (0)
; #define PG8_MMA(ai, bj, At, Bt) do { __builtin_amdgcn_s_setprio(1); _Pragma("unroll") for (int m = 0; m < 4; ++m) _Pragma("unroll") for (int n = 0; n < 2; ++n) _Pragma("unroll") for (int k = 0; k < 2; ++k) \
;         acc[ai][bj][m][n] = __builtin_amdgcn_mfma_f32_16x16x32_bf16(Bt[n][k], At[m][k], acc[ai][bj][m][n], 0, 0, 0); __builtin_amdgcn_s_setprio(0); } while (0)
; #define PG8_WAIT_V(n) asm volatile("s_waitcnt vmcnt(" #n ")" ::: "memory")
; #define PG8_WAIT_L(n) asm volatile("s_waitcnt lgkmcnt(" #n ")" ::: "memory")
; #define PG8_BAR __builtin_amdgcn_s_barrier()
; #define PG8_SCHED __builtin_amdgcn_sched_barrier(0)
; template <class Epi, class Sched, bool ALIGN_EPI = false, bool SP2 = false>
; __device__ __forceinline__ void gemm_phase(PG8_LAS unsigned char* lds, const Gemm g, const Sched& S, const Epi& E) {
;     ...
;         for (int t = 0; t < nt; t += 2) {
;     ...
;             PG8_LDB(B0, 1, 0); PG8_LDB(B1, 1, 1); PG8_SCHED; PG8_LDA(At, 1, 0); PG8_STAGE(PG8_SA(0, 1), a2 + hstep, voffA);
;             PG8_WAIT_V(8); PG8_WAIT_L(0); PG8_BAR; PG8_MMA(0, 0, At, B0); PG8_MMA(0, 1, At, B1); PG8_BAR; PG8_SCHED;
;             PG8_LDA(At, 1, 1); PG8_STAGE(PG8_SB(1, 0), b3, voffB); PG8_STAGE(PG8_SB(1, 1), b3 + hstep, voffB); PG8_STAGE(PG8_SA(1, 0), a3, voffA);
;             PG8_WAIT_V(8); PG8_WAIT_L(0); PG8_BAR; PG8_MMA(1, 0, At, B0); PG8_MMA(1, 1, At, B1); PG8_BAR; PG8_SCHED;
	ds_read_b128 v[140:143], v254 offset:32768
	ds_read_b128 v[162:165], v254 offset:33792
	ds_read_b128 v[166:169], v254 offset:34816
	ds_read_b128 v[176:179], v254 offset:35840
	ds_read_b128 v[180:183], v254 offset:49152
	ds_read_b128 v[184:187], v254 offset:50176
	ds_read_b128 v[188:191], v254 offset:51200
	ds_read_b128 v[210:213], v254 offset:52224
	s_add_u32 s4, s4, 0x40000
	s_addc_u32 s5, s5, 0
	s_mov_b32 m0, s33
	ds_read_b128 v[214:217], v173 offset:32768
	ds_read_b128 v[218:221], v173 offset:33792
	ds_read_b128 v[222:225], v173 offset:34816
	ds_read_b128 v[226:229], v173 offset:35840
	ds_read_b128 v[230:233], v173 offset:36864
	ds_read_b128 v[234:237], v173 offset:37888
	ds_read_b128 v[238:241], v173 offset:38912
	ds_read_b128 v[242:245], v173 offset:39936
	global_load_lds_dwordx4 v134, s[4:5]
	s_mov_b32 m0, s34
	s_nop 0
	global_load_lds_dwordx4 v130, s[4:5]
	s_waitcnt vmcnt(8)
	s_waitcnt lgkmcnt(0)
	s_barrier
	s_setprio 1
	v_mfma_f32_16x16x32_bf16 v[124:127], v[140:143], v[214:217], v[124:127]
	v_mfma_f32_16x16x32_bf16 v[124:127], v[162:165], v[218:221], v[124:127]
	v_mfma_f32_16x16x32_bf16 v[120:123], v[166:169], v[214:217], v[120:123]
	v_mfma_f32_16x16x32_bf16 v[120:123], v[176:179], v[218:221], v[120:123]
	v_mfma_f32_16x16x32_bf16 v[116:119], v[180:183], v[214:217], v[116:119]
	v_mfma_f32_16x16x32_bf16 v[116:119], v[184:187], v[218:221], v[116:119]
	v_mfma_f32_16x16x32_bf16 v[108:111], v[188:191], v[214:217], v[108:111]
	v_mfma_f32_16x16x32_bf16 v[108:111], v[210:213], v[218:221], v[108:111]
	v_mfma_f32_16x16x32_bf16 v[112:115], v[140:143], v[222:225], v[112:115]
	v_mfma_f32_16x16x32_bf16 v[112:115], v[162:165], v[226:229], v[112:115]
	v_mfma_f32_16x16x32_bf16 v[104:107], v[166:169], v[222:225], v[104:107]
	v_mfma_f32_16x16x32_bf16 v[104:107], v[176:179], v[226:229], v[104:107]
	v_mfma_f32_16x16x32_bf16 v[100:103], v[180:183], v[222:225], v[100:103]
	v_mfma_f32_16x16x32_bf16 v[100:103], v[184:187], v[226:229], v[100:103]
	v_mfma_f32_16x16x32_bf16 v[92:95], v[188:191], v[222:225], v[92:95]
	v_mfma_f32_16x16x32_bf16 v[92:95], v[210:213], v[226:229], v[92:95]
	v_mfma_f32_16x16x32_bf16 v[96:99], v[140:143], v[230:233], v[96:99]
	v_mfma_f32_16x16x32_bf16 v[96:99], v[162:165], v[234:237], v[96:99]
	v_mfma_f32_16x16x32_bf16 v[88:91], v[166:169], v[230:233], v[88:91]
	v_mfma_f32_16x16x32_bf16 v[88:91], v[176:179], v[234:237], v[88:91]
	v_mfma_f32_16x16x32_bf16 v[84:87], v[180:183], v[230:233], v[84:87]
	v_mfma_f32_16x16x32_bf16 v[84:87], v[184:187], v[234:237], v[84:87]
	v_mfma_f32_16x16x32_bf16 v[76:79], v[188:191], v[230:233], v[76:79]
	v_mfma_f32_16x16x32_bf16 v[76:79], v[210:213], v[234:237], v[76:79]
	v_mfma_f32_16x16x32_bf16 v[80:83], v[140:143], v[238:241], v[80:83]
	v_mfma_f32_16x16x32_bf16 v[80:83], v[162:165], v[242:245], v[80:83]
	v_mfma_f32_16x16x32_bf16 v[72:75], v[166:169], v[238:241], v[72:75]
	v_mfma_f32_16x16x32_bf16 v[72:75], v[176:179], v[242:245], v[72:75]
	v_mfma_f32_16x16x32_bf16 v[68:71], v[180:183], v[238:241], v[68:71]
	v_mfma_f32_16x16x32_bf16 v[68:71], v[184:187], v[242:245], v[68:71]
	v_mfma_f32_16x16x32_bf16 v[64:67], v[188:191], v[238:241], v[64:67]
	v_mfma_f32_16x16x32_bf16 v[64:67], v[210:213], v[242:245], v[64:67]
	s_setprio 0
	s_barrier
	s_mov_b32 m0, s37
	s_add_u32 s2, s2, 0x40080
	s_addc_u32 s3, s3, 0
	ds_read_b128 v[214:217], v173 offset:49152
	ds_read_b128 v[218:221], v173 offset:50176
	ds_read_b128 v[222:225], v173 offset:51200
	ds_read_b128 v[226:229], v173 offset:52224
	ds_read_b128 v[230:233], v173 offset:53248
	ds_read_b128 v[234:237], v173 offset:54272
	ds_read_b128 v[238:241], v173 offset:55296
	ds_read_b128 v[242:245], v173 offset:56320
	s_add_u32 s98, s2, 0xfffc0000
	s_addc_u32 s99, s3, -1
	global_load_lds_dwordx4 v132, s[98:99]
	s_mov_b32 m0, s38
	s_nop 0
	global_load_lds_dwordx4 v128, s[98:99]
	s_mov_b32 m0, s41
	s_nop 0
	global_load_lds_dwordx4 v132, s[2:3]
	s_mov_b32 m0, s42
	s_nop 0
	global_load_lds_dwordx4 v128, s[2:3]
	s_mov_b32 m0, s39
	s_nop 0
	s_add_u32 s100, s4, 0xfffc0080
	s_addc_u32 s101, s5, -1
	global_load_lds_dwordx4 v134, s[100:101]
	s_mov_b32 m0, s40
	s_nop 0
	global_load_lds_dwordx4 v130, s[100:101]
	s_waitcnt vmcnt(8)
	s_waitcnt lgkmcnt(0)
	s_barrier
	s_setprio 1
	v_mfma_f32_16x16x32_bf16 v[60:63], v[140:143], v[214:217], v[60:63]
	v_mfma_f32_16x16x32_bf16 v[60:63], v[162:165], v[218:221], v[60:63]
	v_mfma_f32_16x16x32_bf16 v[56:59], v[166:169], v[214:217], v[56:59]
	v_mfma_f32_16x16x32_bf16 v[56:59], v[176:179], v[218:221], v[56:59]
	v_mfma_f32_16x16x32_bf16 v[52:55], v[180:183], v[214:217], v[52:55]
	v_mfma_f32_16x16x32_bf16 v[52:55], v[184:187], v[218:221], v[52:55]
	v_mfma_f32_16x16x32_bf16 v[44:47], v[188:191], v[214:217], v[44:47]
	v_mfma_f32_16x16x32_bf16 v[44:47], v[210:213], v[218:221], v[44:47]
	v_mfma_f32_16x16x32_bf16 v[48:51], v[140:143], v[222:225], v[48:51]
	v_mfma_f32_16x16x32_bf16 v[48:51], v[162:165], v[226:229], v[48:51]
	v_mfma_f32_16x16x32_bf16 v[40:43], v[166:169], v[222:225], v[40:43]
	v_mfma_f32_16x16x32_bf16 v[40:43], v[176:179], v[226:229], v[40:43]
	v_mfma_f32_16x16x32_bf16 v[36:39], v[180:183], v[222:225], v[36:39]
	v_mfma_f32_16x16x32_bf16 v[36:39], v[184:187], v[226:229], v[36:39]
	v_mfma_f32_16x16x32_bf16 v[28:31], v[188:191], v[222:225], v[28:31]
	v_mfma_f32_16x16x32_bf16 v[28:31], v[210:213], v[226:229], v[28:31]
	v_mfma_f32_16x16x32_bf16 v[32:35], v[140:143], v[230:233], v[32:35]
	v_mfma_f32_16x16x32_bf16 v[32:35], v[162:165], v[234:237], v[32:35]
	v_mfma_f32_16x16x32_bf16 v[24:27], v[166:169], v[230:233], v[24:27]
	v_mfma_f32_16x16x32_bf16 v[24:27], v[176:179], v[234:237], v[24:27]
	v_mfma_f32_16x16x32_bf16 v[20:23], v[180:183], v[230:233], v[20:23]
	v_mfma_f32_16x16x32_bf16 v[20:23], v[184:187], v[234:237], v[20:23]
	v_mfma_f32_16x16x32_bf16 v[12:15], v[188:191], v[230:233], v[12:15]
	v_mfma_f32_16x16x32_bf16 v[12:15], v[210:213], v[234:237], v[12:15]
	v_mfma_f32_16x16x32_bf16 v[16:19], v[140:143], v[238:241], v[16:19]
	v_mfma_f32_16x16x32_bf16 v[16:19], v[162:165], v[242:245], v[16:19]
	v_mfma_f32_16x16x32_bf16 v[8:11], v[166:169], v[238:241], v[8:11]
	v_mfma_f32_16x16x32_bf16 v[8:11], v[176:179], v[242:245], v[8:11]
	v_mfma_f32_16x16x32_bf16 v[4:7], v[180:183], v[238:241], v[4:7]
	v_mfma_f32_16x16x32_bf16 v[4:7], v[184:187], v[242:245], v[4:7]
	v_mfma_f32_16x16x32_bf16 v[0:3], v[188:191], v[238:241], v[0:3]
	v_mfma_f32_16x16x32_bf16 v[0:3], v[210:213], v[242:245], v[0:3]
	s_setprio 0
	s_barrier
	s_add_i32 s52, s52, 2
	s_add_u32 s0, s0, 0x100
	s_addc_u32 s1, s1, 0
	s_add_u32 s50, s50, 0x100
	s_addc_u32 s51, s51, 0
	s_cmp_gt_u32 s52, 13
; #define PG8_STAGE(bufoff, gbase, voff) do { _Pragma("unroll") for (int _i = 0; _i < 2; ++_i) \
;         __builtin_amdgcn_global_load_lds((const unsigned*)((const char*)(gbase) + (voff)[_i]), (PG8_LAS unsigned*)(lds + (bufoff) + ldsw + _i * 8192), 16, 0, 0); } while (0)
; #define PG8_LDA(dst, b, h) do { _Pragma("unroll") for (int m = 0; m < 4; ++m) _Pragma("unroll") for (int k = 0; k < 2; ++k) dst[m][k] = *(const PG8_LAS bf16x8*)(lds + PG8_SA(b, h) + aoff + m * 2048 + k * 1024); } while (0)
; #define PG8_LDB(dst, b, h) do { _Pragma("unroll") for (int n = 0; n < 2; ++n) _Pragma("unroll") for (int k = 0; k < 2; ++k) dst[n][k] = *(const PG8_LAS bf16x8*)(lds + PG8_SB(b, h) + boff + n * 2048 + k * 1024); } while (0)
; #define PG8_MMA(ai, bj, At, Bt) do { __builtin_amdgcn_s_setprio(1); _Pragma("unroll") for (int m = 0; m < 4; ++m) _Pragma("unroll") for (int n = 0; n < 2; ++n) _Pragma("unroll") for (int k = 0; k < 2; ++k) \
;         acc[ai][bj][m][n] = __builtin_amdgcn_mfma_f32_16x16x32_bf16(Bt[n][k], At[m][k], acc[ai][bj][m][n], 0, 0, 0); __builtin_amdgcn_s_setprio(0); } while (0)
; #define PG8_WAIT_V(n) asm volatile("s_waitcnt vmcnt(" #n ")" ::: "memory")
; #define PG8_BAR __builtin_amdgcn_s_barrier()
; template <class Epi, class Sched, bool ALIGN_EPI = false, bool SP2 = false>
; __device__ __forceinline__ void gemm_phase(PG8_LAS unsigned char* lds, const Gemm g, const Sched& S, const Epi& E) {
;     ...
;         for (int t = 0; t < nt; t += 2) {
;             const bool last = (t == nt - 2);
;             const char* a1 = cA + (size_t)(t + 1) * kstep;
;             const char* a2 = last ? nA : cA + (size_t)(t + 2) * kstep; const char* b2 = last ? nB : cB + (size_t)(t + 2) * kstep;
;             const char* a3 = a2 + kstep; const char* b3 = b2 + kstep;
;             if (last && has_next) S.a_ready(nxt);
;             if constexpr (SP2) {
;             PG8_LDB(B0, 0, 0); PG8_LDB(B1, 0, 1); PG8_SCHED; PG8_LDA(At, 0, 0); PG8_STAGE(PG8_SA(1, 1), a1 + hstep, voffA);
;             PG8_WAIT_V(8); PG8_WAIT_L(0); PG8_BAR; PG8_MMA(0, 0, At, B0); PG8_MMA(0, 1, At, B1); PG8_BAR; PG8_SCHED;
;             PG8_LDA(At, 0, 1); PG8_STAGE(PG8_SB(0, 0), b2, voffB); PG8_STAGE(PG8_SB(0, 1), b2 + hstep, voffB); PG8_STAGE(PG8_SA(0, 0), a2, voffA);
;             PG8_WAIT_V(8); PG8_WAIT_L(0); PG8_BAR; PG8_MMA(1, 0, At, B0); PG8_MMA(1, 1, At, B1); PG8_BAR; PG8_SCHED;
.LBB0_792:
	s_waitcnt lgkmcnt(0)
	ds_read_b128 v[140:143], v254
	ds_read_b128 v[162:165], v254 offset:1024
	ds_read_b128 v[166:169], v254 offset:2048
	ds_read_b128 v[176:179], v254 offset:3072
	ds_read_b128 v[180:183], v254 offset:16384
	ds_read_b128 v[184:187], v254 offset:17408
	ds_read_b128 v[188:191], v254 offset:18432
	ds_read_b128 v[210:213], v254 offset:19456
	s_add_u32 s2, s0, 0xfffc0080
	s_addc_u32 s3, s1, -1
	s_cmp_eq_u32 s52, 12
	s_cselect_b32 s5, s17, s3
	s_cselect_b32 s4, s48, s2
	s_cselect_b32 s3, s15, s51
	s_cselect_b32 s2, s49, s50
	s_add_i32 m0, s6, 0xc000
	ds_read_b128 v[214:217], v173
	ds_read_b128 v[218:221], v173 offset:1024
	ds_read_b128 v[222:225], v173 offset:2048
	ds_read_b128 v[226:229], v173 offset:3072
	ds_read_b128 v[230:233], v173 offset:4096
	ds_read_b128 v[234:237], v173 offset:5120
	ds_read_b128 v[238:241], v173 offset:6144
	ds_read_b128 v[242:245], v173 offset:7168
	global_load_lds_dwordx4 v136, s[0:1]
	s_add_i32 m0, s6, 0xe000
	s_nop 0
	global_load_lds_dwordx4 v138, s[0:1]
	s_waitcnt vmcnt(8)
	s_waitcnt lgkmcnt(0)
	s_barrier
	s_setprio 1
	v_mfma_f32_16x16x32_bf16 v[124:127], v[140:143], v[214:217], v[124:127]
	v_mfma_f32_16x16x32_bf16 v[124:127], v[162:165], v[218:221], v[124:127]
	v_mfma_f32_16x16x32_bf16 v[120:123], v[166:169], v[214:217], v[120:123]
	v_mfma_f32_16x16x32_bf16 v[120:123], v[176:179], v[218:221], v[120:123]
	v_mfma_f32_16x16x32_bf16 v[116:119], v[180:183], v[214:217], v[116:119]
	v_mfma_f32_16x16x32_bf16 v[116:119], v[184:187], v[218:221], v[116:119]
	v_mfma_f32_16x16x32_bf16 v[108:111], v[188:191], v[214:217], v[108:111]
	v_mfma_f32_16x16x32_bf16 v[108:111], v[210:213], v[218:221], v[108:111]
	v_mfma_f32_16x16x32_bf16 v[112:115], v[140:143], v[222:225], v[112:115]
	v_mfma_f32_16x16x32_bf16 v[112:115], v[162:165], v[226:229], v[112:115]
	v_mfma_f32_16x16x32_bf16 v[104:107], v[166:169], v[222:225], v[104:107]
	v_mfma_f32_16x16x32_bf16 v[104:107], v[176:179], v[226:229], v[104:107]
	v_mfma_f32_16x16x32_bf16 v[100:103], v[180:183], v[222:225], v[100:103]
	v_mfma_f32_16x16x32_bf16 v[100:103], v[184:187], v[226:229], v[100:103]
	v_mfma_f32_16x16x32_bf16 v[92:95], v[188:191], v[222:225], v[92:95]
	v_mfma_f32_16x16x32_bf16 v[92:95], v[210:213], v[226:229], v[92:95]
	v_mfma_f32_16x16x32_bf16 v[96:99], v[140:143], v[230:233], v[96:99]
	v_mfma_f32_16x16x32_bf16 v[96:99], v[162:165], v[234:237], v[96:99]
	v_mfma_f32_16x16x32_bf16 v[88:91], v[166:169], v[230:233], v[88:91]
	v_mfma_f32_16x16x32_bf16 v[88:91], v[176:179], v[234:237], v[88:91]
	v_mfma_f32_16x16x32_bf16 v[84:87], v[180:183], v[230:233], v[84:87]
	v_mfma_f32_16x16x32_bf16 v[84:87], v[184:187], v[234:237], v[84:87]
	v_mfma_f32_16x16x32_bf16 v[76:79], v[188:191], v[230:233], v[76:79]
	v_mfma_f32_16x16x32_bf16 v[76:79], v[210:213], v[234:237], v[76:79]
	v_mfma_f32_16x16x32_bf16 v[80:83], v[140:143], v[238:241], v[80:83]
	v_mfma_f32_16x16x32_bf16 v[80:83], v[162:165], v[242:245], v[80:83]
	v_mfma_f32_16x16x32_bf16 v[72:75], v[166:169], v[238:241], v[72:75]
	v_mfma_f32_16x16x32_bf16 v[72:75], v[176:179], v[242:245], v[72:75]
	v_mfma_f32_16x16x32_bf16 v[68:71], v[180:183], v[238:241], v[68:71]
	v_mfma_f32_16x16x32_bf16 v[68:71], v[184:187], v[242:245], v[68:71]
	v_mfma_f32_16x16x32_bf16 v[64:67], v[188:191], v[238:241], v[64:67]
	v_mfma_f32_16x16x32_bf16 v[64:67], v[210:213], v[242:245], v[64:67]
	s_setprio 0
	s_barrier
	s_mov_b32 m0, s27
	s_add_u32 s54, s2, 0x40000
	s_addc_u32 s55, s3, 0
	ds_read_b128 v[214:217], v173 offset:16384
	ds_read_b128 v[218:221], v173 offset:17408
	ds_read_b128 v[222:225], v173 offset:18432
	ds_read_b128 v[226:229], v173 offset:19456
	ds_read_b128 v[230:233], v173 offset:20480
	ds_read_b128 v[234:237], v173 offset:21504
	ds_read_b128 v[238:241], v173 offset:22528
	ds_read_b128 v[242:245], v173 offset:23552
	global_load_lds_dwordx4 v132, s[2:3]
	s_mov_b32 m0, s28
	s_nop 0
	global_load_lds_dwordx4 v128, s[2:3]
	s_mov_b32 m0, s29
	s_nop 0
	global_load_lds_dwordx4 v132, s[54:55]
	s_mov_b32 m0, s30
	s_nop 0
	global_load_lds_dwordx4 v128, s[54:55]
	s_mov_b32 m0, s6
	s_nop 0
	global_load_lds_dwordx4 v134, s[4:5]
	s_mov_b32 m0, s31
	s_nop 0
	global_load_lds_dwordx4 v130, s[4:5]
	s_waitcnt vmcnt(8)
	s_waitcnt lgkmcnt(0)
	s_barrier
	s_setprio 1
	v_mfma_f32_16x16x32_bf16 v[60:63], v[140:143], v[214:217], v[60:63]
	v_mfma_f32_16x16x32_bf16 v[60:63], v[162:165], v[218:221], v[60:63]
	v_mfma_f32_16x16x32_bf16 v[56:59], v[166:169], v[214:217], v[56:59]
	v_mfma_f32_16x16x32_bf16 v[56:59], v[176:179], v[218:221], v[56:59]
	v_mfma_f32_16x16x32_bf16 v[52:55], v[180:183], v[214:217], v[52:55]
	v_mfma_f32_16x16x32_bf16 v[52:55], v[184:187], v[218:221], v[52:55]
	v_mfma_f32_16x16x32_bf16 v[44:47], v[188:191], v[214:217], v[44:47]
	v_mfma_f32_16x16x32_bf16 v[44:47], v[210:213], v[218:221], v[44:47]
	v_mfma_f32_16x16x32_bf16 v[48:51], v[140:143], v[222:225], v[48:51]
	v_mfma_f32_16x16x32_bf16 v[48:51], v[162:165], v[226:229], v[48:51]
	v_mfma_f32_16x16x32_bf16 v[40:43], v[166:169], v[222:225], v[40:43]
	v_mfma_f32_16x16x32_bf16 v[40:43], v[176:179], v[226:229], v[40:43]
	v_mfma_f32_16x16x32_bf16 v[36:39], v[180:183], v[222:225], v[36:39]
	v_mfma_f32_16x16x32_bf16 v[36:39], v[184:187], v[226:229], v[36:39]
	v_mfma_f32_16x16x32_bf16 v[28:31], v[188:191], v[222:225], v[28:31]
	v_mfma_f32_16x16x32_bf16 v[28:31], v[210:213], v[226:229], v[28:31]
	v_mfma_f32_16x16x32_bf16 v[32:35], v[140:143], v[230:233], v[32:35]
	v_mfma_f32_16x16x32_bf16 v[32:35], v[162:165], v[234:237], v[32:35]
	v_mfma_f32_16x16x32_bf16 v[24:27], v[166:169], v[230:233], v[24:27]
	v_mfma_f32_16x16x32_bf16 v[24:27], v[176:179], v[234:237], v[24:27]
	v_mfma_f32_16x16x32_bf16 v[20:23], v[180:183], v[230:233], v[20:23]
	v_mfma_f32_16x16x32_bf16 v[20:23], v[184:187], v[234:237], v[20:23]
	v_mfma_f32_16x16x32_bf16 v[12:15], v[188:191], v[230:233], v[12:15]
	v_mfma_f32_16x16x32_bf16 v[12:15], v[210:213], v[234:237], v[12:15]
	v_mfma_f32_16x16x32_bf16 v[16:19], v[140:143], v[238:241], v[16:19]
	v_mfma_f32_16x16x32_bf16 v[16:19], v[162:165], v[242:245], v[16:19]
	v_mfma_f32_16x16x32_bf16 v[8:11], v[166:169], v[238:241], v[8:11]
	v_mfma_f32_16x16x32_bf16 v[8:11], v[176:179], v[242:245], v[8:11]
	v_mfma_f32_16x16x32_bf16 v[4:7], v[180:183], v[238:241], v[4:7]
	v_mfma_f32_16x16x32_bf16 v[4:7], v[184:187], v[242:245], v[4:7]
	v_mfma_f32_16x16x32_bf16 v[0:3], v[188:191], v[238:241], v[0:3]
	v_mfma_f32_16x16x32_bf16 v[0:3], v[210:213], v[242:245], v[0:3]
	s_setprio 0
	s_barrier
; #define PG8_STAGE(bufoff, gbase, voff) do { _Pragma("unroll") for (int _i = 0; _i < 2; ++_i) \
;         __builtin_amdgcn_global_load_lds((const unsigned*)((const char*)(gbase) + (voff)[_i]), (PG8_LAS unsigned*)(lds + (bufoff) + ldsw + _i * 8192), 16, 0, 0); } while (0)
; #define PG8_LDA(dst, b, h) do { _Pragma("unroll") for (int m = 0; m < 4; ++m) _Pragma("unroll") for (int k = 0; k < 2; ++k) dst[m][k] = *(const PG8_LAS bf16x8*)(lds + PG8_SA(b, h) + aoff + m * 2048 + k * 1024); } while (0)
; #define PG8_LDB(dst, b, h) do { _Pragma("unroll") for (int n = 0; n < 2; ++n) _Pragma("unroll") for (int k = 0; k < 2; ++k) dst[n][k] = *(const PG8_LAS bf16x8*)(lds + PG8_SB(b, h) + boff + n * 2048 + k * 1024); } while (0)
; #define PG8_MMA(ai, bj, At, Bt) do { __builtin_amdgcn_s_setprio(1); _Pragma("unroll") for (int m = 0; m < 4; ++m) _Pragma("unroll") for (int n = 0; n < 2; ++n) _Pragma("unroll") for (int k = 0; k < 2; ++k) \
;         acc[ai][bj][m][n] = __builtin_amdgcn_mfma_f32_16x16x32_bf16(Bt[n][k], At[m][k], acc[ai][bj][m][n], 0, 0, 0); __builtin_amdgcn_s_setprio(0); } while (0)
; #define PG8_WAIT_V(n) asm volatile("s_waitcnt vmcnt(" #n ")" ::: "memory")
; #define PG8_WAIT_L(n) asm volatile("s_waitcnt lgkmcnt(" #n ")" ::: "memory")
; #define PG8_BAR __builtin_amdgcn_s_barrier()
; #define PG8_SCHED __builtin_amdgcn_sched_barrier(0)
; template <class Epi, class Sched, bool ALIGN_EPI = false, bool SP2 = false>
; __device__ __forceinline__ void gemm_phase(PG8_LAS unsigned char* lds, const Gemm g, const Sched& S, const Epi& E) {
;     ...
;             PG8_LDB(B0, 1, 0); PG8_LDB(B1, 1, 1); PG8_SCHED; PG8_LDA(At, 1, 0); PG8_STAGE(PG8_SA(0, 1), a2 + hstep, voffA);
;             PG8_WAIT_V(8); PG8_WAIT_L(0); PG8_BAR; PG8_MMA(0, 0, At, B0); PG8_MMA(0, 1, At, B1); PG8_BAR; PG8_SCHED;
;             PG8_LDA(At, 1, 1); PG8_STAGE(PG8_SB(1, 0), b3, voffB); PG8_STAGE(PG8_SB(1, 1), b3 + hstep, voffB); PG8_STAGE(PG8_SA(1, 0), a3, voffA);
;             PG8_WAIT_V(8); PG8_WAIT_L(0); PG8_BAR; PG8_MMA(1, 0, At, B0); PG8_MMA(1, 1, At, B1); PG8_BAR; PG8_SCHED;
;     ...
;         if constexpr (ALIGN_EPI) { if (wr == 0) PG8_BAR; }
	ds_read_b128 v[140:143], v254 offset:32768
	ds_read_b128 v[162:165], v254 offset:33792
	ds_read_b128 v[166:169], v254 offset:34816
	ds_read_b128 v[176:179], v254 offset:35840
	ds_read_b128 v[180:183], v254 offset:49152
	ds_read_b128 v[184:187], v254 offset:50176
	ds_read_b128 v[188:191], v254 offset:51200
	ds_read_b128 v[210:213], v254 offset:52224
	s_add_u32 s4, s4, 0x40000
	s_addc_u32 s5, s5, 0
	s_mov_b32 m0, s33
	ds_read_b128 v[214:217], v173 offset:32768
	ds_read_b128 v[218:221], v173 offset:33792
	ds_read_b128 v[222:225], v173 offset:34816
	ds_read_b128 v[226:229], v173 offset:35840
	ds_read_b128 v[230:233], v173 offset:36864
	ds_read_b128 v[234:237], v173 offset:37888
	ds_read_b128 v[238:241], v173 offset:38912
	ds_read_b128 v[242:245], v173 offset:39936
	global_load_lds_dwordx4 v134, s[4:5]
	s_mov_b32 m0, s34
	s_nop 0
	global_load_lds_dwordx4 v130, s[4:5]
	s_waitcnt vmcnt(8)
	s_waitcnt lgkmcnt(0)
	s_barrier
	s_setprio 1
	v_mfma_f32_16x16x32_bf16 v[124:127], v[140:143], v[214:217], v[124:127]
	v_mfma_f32_16x16x32_bf16 v[124:127], v[162:165], v[218:221], v[124:127]
	v_mfma_f32_16x16x32_bf16 v[120:123], v[166:169], v[214:217], v[120:123]
	v_mfma_f32_16x16x32_bf16 v[120:123], v[176:179], v[218:221], v[120:123]
	v_mfma_f32_16x16x32_bf16 v[116:119], v[180:183], v[214:217], v[116:119]
	v_mfma_f32_16x16x32_bf16 v[116:119], v[184:187], v[218:221], v[116:119]
	v_mfma_f32_16x16x32_bf16 v[108:111], v[188:191], v[214:217], v[108:111]
	v_mfma_f32_16x16x32_bf16 v[108:111], v[210:213], v[218:221], v[108:111]
	v_mfma_f32_16x16x32_bf16 v[112:115], v[140:143], v[222:225], v[112:115]
	v_mfma_f32_16x16x32_bf16 v[112:115], v[162:165], v[226:229], v[112:115]
	v_mfma_f32_16x16x32_bf16 v[104:107], v[166:169], v[222:225], v[104:107]
	v_mfma_f32_16x16x32_bf16 v[104:107], v[176:179], v[226:229], v[104:107]
	v_mfma_f32_16x16x32_bf16 v[100:103], v[180:183], v[222:225], v[100:103]
	v_mfma_f32_16x16x32_bf16 v[100:103], v[184:187], v[226:229], v[100:103]
	v_mfma_f32_16x16x32_bf16 v[92:95], v[188:191], v[222:225], v[92:95]
	v_mfma_f32_16x16x32_bf16 v[92:95], v[210:213], v[226:229], v[92:95]
	v_mfma_f32_16x16x32_bf16 v[96:99], v[140:143], v[230:233], v[96:99]
	v_mfma_f32_16x16x32_bf16 v[96:99], v[162:165], v[234:237], v[96:99]
	v_mfma_f32_16x16x32_bf16 v[88:91], v[166:169], v[230:233], v[88:91]
	v_mfma_f32_16x16x32_bf16 v[88:91], v[176:179], v[234:237], v[88:91]
	v_mfma_f32_16x16x32_bf16 v[84:87], v[180:183], v[230:233], v[84:87]
	v_mfma_f32_16x16x32_bf16 v[84:87], v[184:187], v[234:237], v[84:87]
	v_mfma_f32_16x16x32_bf16 v[76:79], v[188:191], v[230:233], v[76:79]
	v_mfma_f32_16x16x32_bf16 v[76:79], v[210:213], v[234:237], v[76:79]
	v_mfma_f32_16x16x32_bf16 v[80:83], v[140:143], v[238:241], v[80:83]
	v_mfma_f32_16x16x32_bf16 v[80:83], v[162:165], v[242:245], v[80:83]
	v_mfma_f32_16x16x32_bf16 v[72:75], v[166:169], v[238:241], v[72:75]
	v_mfma_f32_16x16x32_bf16 v[72:75], v[176:179], v[242:245], v[72:75]
	v_mfma_f32_16x16x32_bf16 v[68:71], v[180:183], v[238:241], v[68:71]
	v_mfma_f32_16x16x32_bf16 v[68:71], v[184:187], v[242:245], v[68:71]
	v_mfma_f32_16x16x32_bf16 v[64:67], v[188:191], v[238:241], v[64:67]
	v_mfma_f32_16x16x32_bf16 v[64:67], v[210:213], v[242:245], v[64:67]
	s_setprio 0
	s_barrier
	s_mov_b32 m0, s37
	s_add_u32 s2, s2, 0x40080
	s_addc_u32 s3, s3, 0
	ds_read_b128 v[214:217], v173 offset:49152
	ds_read_b128 v[218:221], v173 offset:50176
	ds_read_b128 v[222:225], v173 offset:51200
	ds_read_b128 v[226:229], v173 offset:52224
	ds_read_b128 v[230:233], v173 offset:53248
	ds_read_b128 v[234:237], v173 offset:54272
	ds_read_b128 v[238:241], v173 offset:55296
	ds_read_b128 v[242:245], v173 offset:56320
	s_add_u32 s98, s2, 0xfffc0000
	s_addc_u32 s99, s3, -1
	global_load_lds_dwordx4 v132, s[98:99]
	s_mov_b32 m0, s38
	s_nop 0
	global_load_lds_dwordx4 v128, s[98:99]
	s_mov_b32 m0, s41
	s_nop 0
	global_load_lds_dwordx4 v132, s[2:3]
	s_mov_b32 m0, s42
	s_nop 0
	global_load_lds_dwordx4 v128, s[2:3]
	s_mov_b32 m0, s39
	s_nop 0
	s_add_u32 s100, s4, 0xfffc0080
	s_addc_u32 s101, s5, -1
	global_load_lds_dwordx4 v134, s[100:101]
	s_mov_b32 m0, s40
	s_nop 0
	global_load_lds_dwordx4 v130, s[100:101]
	s_waitcnt vmcnt(8)
	s_waitcnt lgkmcnt(0)
	s_barrier
	s_setprio 1
	v_mfma_f32_16x16x32_bf16 v[60:63], v[140:143], v[214:217], v[60:63]
	v_mfma_f32_16x16x32_bf16 v[60:63], v[162:165], v[218:221], v[60:63]
	v_mfma_f32_16x16x32_bf16 v[56:59], v[166:169], v[214:217], v[56:59]
	v_mfma_f32_16x16x32_bf16 v[56:59], v[176:179], v[218:221], v[56:59]
	v_mfma_f32_16x16x32_bf16 v[52:55], v[180:183], v[214:217], v[52:55]
	v_mfma_f32_16x16x32_bf16 v[52:55], v[184:187], v[218:221], v[52:55]
	v_mfma_f32_16x16x32_bf16 v[44:47], v[188:191], v[214:217], v[44:47]
	v_mfma_f32_16x16x32_bf16 v[44:47], v[210:213], v[218:221], v[44:47]
	v_mfma_f32_16x16x32_bf16 v[48:51], v[140:143], v[222:225], v[48:51]
	v_mfma_f32_16x16x32_bf16 v[48:51], v[162:165], v[226:229], v[48:51]
	v_mfma_f32_16x16x32_bf16 v[40:43], v[166:169], v[222:225], v[40:43]
	v_mfma_f32_16x16x32_bf16 v[40:43], v[176:179], v[226:229], v[40:43]
	v_mfma_f32_16x16x32_bf16 v[36:39], v[180:183], v[222:225], v[36:39]
	v_mfma_f32_16x16x32_bf16 v[36:39], v[184:187], v[226:229], v[36:39]
	v_mfma_f32_16x16x32_bf16 v[28:31], v[188:191], v[222:225], v[28:31]
	v_mfma_f32_16x16x32_bf16 v[28:31], v[210:213], v[226:229], v[28:31]
	v_mfma_f32_16x16x32_bf16 v[32:35], v[140:143], v[230:233], v[32:35]
	v_mfma_f32_16x16x32_bf16 v[32:35], v[162:165], v[234:237], v[32:35]
	v_mfma_f32_16x16x32_bf16 v[24:27], v[166:169], v[230:233], v[24:27]
	v_mfma_f32_16x16x32_bf16 v[24:27], v[176:179], v[234:237], v[24:27]
	v_mfma_f32_16x16x32_bf16 v[20:23], v[180:183], v[230:233], v[20:23]
	v_mfma_f32_16x16x32_bf16 v[20:23], v[184:187], v[234:237], v[20:23]
	v_mfma_f32_16x16x32_bf16 v[12:15], v[188:191], v[230:233], v[12:15]
	v_mfma_f32_16x16x32_bf16 v[12:15], v[210:213], v[234:237], v[12:15]
	v_mfma_f32_16x16x32_bf16 v[16:19], v[140:143], v[238:241], v[16:19]
	v_mfma_f32_16x16x32_bf16 v[16:19], v[162:165], v[242:245], v[16:19]
	v_mfma_f32_16x16x32_bf16 v[8:11], v[166:169], v[238:241], v[8:11]
	v_mfma_f32_16x16x32_bf16 v[8:11], v[176:179], v[242:245], v[8:11]
	v_mfma_f32_16x16x32_bf16 v[4:7], v[180:183], v[238:241], v[4:7]
	v_mfma_f32_16x16x32_bf16 v[4:7], v[184:187], v[242:245], v[4:7]
	v_mfma_f32_16x16x32_bf16 v[0:3], v[188:191], v[238:241], v[0:3]
	v_mfma_f32_16x16x32_bf16 v[0:3], v[210:213], v[242:245], v[0:3]
	s_setprio 0
	s_barrier
	s_add_i32 s52, s52, 2
	s_add_u32 s0, s0, 0x100
	s_addc_u32 s1, s1, 0
	s_add_u32 s50, s50, 0x100
	s_addc_u32 s51, s51, 0
	s_cmp_gt_u32 s52, 13
	s_cbranch_scc0 .LBB0_792
	s_and_b64 vcc, exec, s[12:13]
	s_cbranch_vccz .LBB0_795
	s_barrier

; #define PG8_STAGE(bufoff, gbase, voff) do { _Pragma("unroll") for (int _i = 0; _i < 2; ++_i) \
;         __builtin_amdgcn_global_load_lds((const unsigned*)((const char*)(gbase) + (voff)[_i]), (PG8_LAS unsigned*)(lds + (bufoff) + ldsw + _i * 8192), 16, 0, 0); } while (0)
; #define PG8_LDA(dst, b, h) do { _Pragma("unroll") for (int m = 0; m < 4; ++m) _Pragma("unroll") for (int k = 0; k < 2; ++k) dst[m][k] = *(const PG8_LAS bf16x8*)(lds + PG8_SA(b, h) + aoff + m * 2048 + k * 1024); } while (0)
; #define PG8_LDB(dst, b, h) do { _Pragma("unroll") for (int n = 0; n < 2; ++n) _Pragma("unroll") for (int k = 0; k < 2; ++k) dst[n][k] = *(const PG8_LAS bf16x8*)(lds + PG8_SB(b, h) + boff + n * 2048 + k * 1024); } while (0)
; #define PG8_MMA(ai, bj, At, Bt) do { __builtin_amdgcn_s_setprio(1); _Pragma("unroll") for (int m = 0; m < 4; ++m) _Pragma("unroll") for (int n = 0; n < 2; ++n) _Pragma("unroll") for (int k = 0; k < 2; ++k) \
;         acc[ai][bj][m][n] = __builtin_amdgcn_mfma_f32_16x16x32_bf16(Bt[n][k], At[m][k], acc[ai][bj][m][n], 0, 0, 0); __builtin_amdgcn_s_setprio(0); } while (0)
; #define PG8_WAIT_V(n) asm volatile("s_waitcnt vmcnt(" #n ")" ::: "memory")
; #define PG8_WAIT_L(n) asm volatile("s_waitcnt lgkmcnt(" #n ")" ::: "memory")
; template <class Epi, class Sched, bool ALIGN_EPI = false, bool SP2 = false>
; __device__ __forceinline__ void gemm_phase(PG8_LAS unsigned char* lds, const Gemm g, const Sched& S, const Epi& E) {
;     ...
;             const bool last = (t == nt - 2);
;             const char* a1 = cA + (size_t)(t + 1) * kstep;
;             const char* a2 = last ? nA : cA + (size_t)(t + 2) * kstep; const char* b2 = last ? nB : cB + (size_t)(t + 2) * kstep;
;             const char* a3 = a2 + kstep; const char* b3 = b2 + kstep;
;             if (last && has_next) S.a_ready(nxt);
;             if constexpr (SP2) {
;             PG8_LDB(B0, 0, 0); PG8_LDB(B1, 0, 1); PG8_SCHED; PG8_LDA(At, 0, 0); PG8_STAGE(PG8_SA(1, 1), a1 + hstep, voffA);
;             PG8_WAIT_V(8); PG8_WAIT_L(0); PG8_BAR; PG8_MMA(0, 0, At, B0); PG8_MMA(0, 1, At, B1); PG8_BAR; PG8_SCHED;
;             PG8_LDA(At, 0, 1); PG8_STAGE(PG8_SB(0, 0), b2, voffB); PG8_STAGE(PG8_SB(0, 1), b2 + hstep, voffB); PG8_STAGE(PG8_SA(0, 0), a2, voffA);
;             PG8_WAIT_V(8); PG8_WAIT_L(0); PG8_BAR; PG8_MMA(1, 0, At, B0); PG8_MMA(1, 1, At, B1); PG8_BAR; PG8_SCHED;
.Lsgo_peel:
	ds_read_b128 v[140:143], v254
	ds_read_b128 v[166:169], v254 offset:1024
	ds_read_b128 v[170:173], v254 offset:2048
	ds_read_b128 v[174:177], v254 offset:3072
	ds_read_b128 v[178:181], v254 offset:16384
	ds_read_b128 v[182:185], v254 offset:17408
	ds_read_b128 v[186:189], v254 offset:18432
	ds_read_b128 v[210:213], v254 offset:19456
	s_add_u32 s2, s0, 0xfffc0080
	s_addc_u32 s3, s1, -1
	s_cmp_eq_u32 s55, 12
	s_cselect_b32 s5, s23, s3
	s_cselect_b32 s4, s51, s2
	s_cselect_b32 s3, s21, s54
	s_cselect_b32 s2, s52, s53
	s_add_i32 m0, s31, 0xc000
	ds_read_b128 v[214:217], v163
	ds_read_b128 v[218:221], v163 offset:1024
	ds_read_b128 v[222:225], v163 offset:2048
	ds_read_b128 v[226:229], v163 offset:3072
	ds_read_b128 v[230:233], v163 offset:4096
	ds_read_b128 v[234:237], v163 offset:5120
	ds_read_b128 v[238:241], v163 offset:6144
	ds_read_b128 v[242:245], v163 offset:7168
	global_load_lds_dwordx4 v136, s[0:1]
	s_add_i32 m0, s31, 0xe000
	s_nop 0
	global_load_lds_dwordx4 v138, s[0:1]
	s_waitcnt vmcnt(8)
	s_waitcnt lgkmcnt(0)
	s_barrier
	s_setprio 1
	v_mfma_f32_16x16x32_bf16 v[124:127], v[140:143], v[214:217], 0
	v_mfma_f32_16x16x32_bf16 v[124:127], v[166:169], v[218:221], v[124:127]
	v_mfma_f32_16x16x32_bf16 v[120:123], v[170:173], v[214:217], 0
	v_mfma_f32_16x16x32_bf16 v[120:123], v[174:177], v[218:221], v[120:123]
	v_mfma_f32_16x16x32_bf16 v[116:119], v[178:181], v[214:217], 0
	v_mfma_f32_16x16x32_bf16 v[116:119], v[182:185], v[218:221], v[116:119]
	v_mfma_f32_16x16x32_bf16 v[112:115], v[186:189], v[214:217], 0
	v_mfma_f32_16x16x32_bf16 v[112:115], v[210:213], v[218:221], v[112:115]
	v_mfma_f32_16x16x32_bf16 v[108:111], v[140:143], v[222:225], 0
	v_mfma_f32_16x16x32_bf16 v[108:111], v[166:169], v[226:229], v[108:111]
	v_mfma_f32_16x16x32_bf16 v[104:107], v[170:173], v[222:225], 0
	v_mfma_f32_16x16x32_bf16 v[104:107], v[174:177], v[226:229], v[104:107]
	v_mfma_f32_16x16x32_bf16 v[100:103], v[178:181], v[222:225], 0
	v_mfma_f32_16x16x32_bf16 v[100:103], v[182:185], v[226:229], v[100:103]
	v_mfma_f32_16x16x32_bf16 v[96:99], v[186:189], v[222:225], 0
	v_mfma_f32_16x16x32_bf16 v[96:99], v[210:213], v[226:229], v[96:99]
	v_mfma_f32_16x16x32_bf16 v[92:95], v[140:143], v[230:233], 0
	v_mfma_f32_16x16x32_bf16 v[92:95], v[166:169], v[234:237], v[92:95]
	v_mfma_f32_16x16x32_bf16 v[88:91], v[170:173], v[230:233], 0
	v_mfma_f32_16x16x32_bf16 v[88:91], v[174:177], v[234:237], v[88:91]
	v_mfma_f32_16x16x32_bf16 v[84:87], v[178:181], v[230:233], 0
	v_mfma_f32_16x16x32_bf16 v[84:87], v[182:185], v[234:237], v[84:87]
	v_mfma_f32_16x16x32_bf16 v[80:83], v[186:189], v[230:233], 0
	v_mfma_f32_16x16x32_bf16 v[80:83], v[210:213], v[234:237], v[80:83]
	v_mfma_f32_16x16x32_bf16 v[76:79], v[140:143], v[238:241], 0
	v_mfma_f32_16x16x32_bf16 v[76:79], v[166:169], v[242:245], v[76:79]
	v_mfma_f32_16x16x32_bf16 v[72:75], v[170:173], v[238:241], 0
	v_mfma_f32_16x16x32_bf16 v[72:75], v[174:177], v[242:245], v[72:75]
	v_mfma_f32_16x16x32_bf16 v[68:71], v[178:181], v[238:241], 0
	v_mfma_f32_16x16x32_bf16 v[68:71], v[182:185], v[242:245], v[68:71]
	v_mfma_f32_16x16x32_bf16 v[64:67], v[186:189], v[238:241], 0
	v_mfma_f32_16x16x32_bf16 v[64:67], v[210:213], v[242:245], v[64:67]
	s_setprio 0
	s_barrier
	s_mov_b32 m0, s33
	s_add_u32 s56, s2, 0x40000
	s_addc_u32 s57, s3, 0
	ds_read_b128 v[214:217], v163 offset:16384
	ds_read_b128 v[218:221], v163 offset:17408
	ds_read_b128 v[222:225], v163 offset:18432
	ds_read_b128 v[226:229], v163 offset:19456
	ds_read_b128 v[230:233], v163 offset:20480
	ds_read_b128 v[234:237], v163 offset:21504
	ds_read_b128 v[238:241], v163 offset:22528
	ds_read_b128 v[242:245], v163 offset:23552
	global_load_lds_dwordx4 v132, s[2:3]
	s_mov_b32 m0, s34
	s_nop 0
	global_load_lds_dwordx4 v128, s[2:3]
	s_mov_b32 m0, s35
	s_nop 0
	global_load_lds_dwordx4 v132, s[56:57]
	s_mov_b32 m0, s36
	s_nop 0
	global_load_lds_dwordx4 v128, s[56:57]
	s_mov_b32 m0, s31
	s_nop 0
	global_load_lds_dwordx4 v134, s[4:5]
	s_mov_b32 m0, s37
	s_nop 0
	global_load_lds_dwordx4 v130, s[4:5]
	s_waitcnt vmcnt(8)
	s_waitcnt lgkmcnt(0)
	s_barrier
	s_setprio 1
	v_mfma_f32_16x16x32_bf16 v[60:63], v[140:143], v[214:217], 0
	v_mfma_f32_16x16x32_bf16 v[60:63], v[166:169], v[218:221], v[60:63]
	v_mfma_f32_16x16x32_bf16 v[56:59], v[170:173], v[214:217], 0
	v_mfma_f32_16x16x32_bf16 v[56:59], v[174:177], v[218:221], v[56:59]
	v_mfma_f32_16x16x32_bf16 v[52:55], v[178:181], v[214:217], 0
	v_mfma_f32_16x16x32_bf16 v[52:55], v[182:185], v[218:221], v[52:55]
	v_mfma_f32_16x16x32_bf16 v[48:51], v[186:189], v[214:217], 0
	v_mfma_f32_16x16x32_bf16 v[48:51], v[210:213], v[218:221], v[48:51]
	v_mfma_f32_16x16x32_bf16 v[44:47], v[140:143], v[222:225], 0
	v_mfma_f32_16x16x32_bf16 v[44:47], v[166:169], v[226:229], v[44:47]
	v_mfma_f32_16x16x32_bf16 v[40:43], v[170:173], v[222:225], 0
	v_mfma_f32_16x16x32_bf16 v[40:43], v[174:177], v[226:229], v[40:43]
	v_mfma_f32_16x16x32_bf16 v[36:39], v[178:181], v[222:225], 0
	v_mfma_f32_16x16x32_bf16 v[36:39], v[182:185], v[226:229], v[36:39]
	v_mfma_f32_16x16x32_bf16 v[32:35], v[186:189], v[222:225], 0
	v_mfma_f32_16x16x32_bf16 v[32:35], v[210:213], v[226:229], v[32:35]
	v_mfma_f32_16x16x32_bf16 v[28:31], v[140:143], v[230:233], 0
	v_mfma_f32_16x16x32_bf16 v[28:31], v[166:169], v[234:237], v[28:31]
	v_mfma_f32_16x16x32_bf16 v[24:27], v[170:173], v[230:233], 0
	v_mfma_f32_16x16x32_bf16 v[24:27], v[174:177], v[234:237], v[24:27]
	v_mfma_f32_16x16x32_bf16 v[20:23], v[178:181], v[230:233], 0
	v_mfma_f32_16x16x32_bf16 v[20:23], v[182:185], v[234:237], v[20:23]
	v_mfma_f32_16x16x32_bf16 v[16:19], v[186:189], v[230:233], 0
	v_mfma_f32_16x16x32_bf16 v[16:19], v[210:213], v[234:237], v[16:19]
	v_mfma_f32_16x16x32_bf16 v[12:15], v[140:143], v[238:241], 0
	v_mfma_f32_16x16x32_bf16 v[12:15], v[166:169], v[242:245], v[12:15]
	v_mfma_f32_16x16x32_bf16 v[8:11], v[170:173], v[238:241], 0
	v_mfma_f32_16x16x32_bf16 v[8:11], v[174:177], v[242:245], v[8:11]
	v_mfma_f32_16x16x32_bf16 v[4:7], v[178:181], v[238:241], 0
	v_mfma_f32_16x16x32_bf16 v[4:7], v[182:185], v[242:245], v[4:7]
	v_mfma_f32_16x16x32_bf16 v[0:3], v[186:189], v[238:241], 0
	v_mfma_f32_16x16x32_bf16 v[0:3], v[210:213], v[242:245], v[0:3]
	s_setprio 0
	s_barrier
; #define PG8_STAGE(bufoff, gbase, voff) do { _Pragma("unroll") for (int _i = 0; _i < 2; ++_i) \
;         __builtin_amdgcn_global_load_lds((const unsigned*)((const char*)(gbase) + (voff)[_i]), (PG8_LAS unsigned*)(lds + (bufoff) + ldsw + _i * 8192), 16, 0, 0); } while (0)
; #define PG8_LDA(dst, b, h) do { _Pragma("unroll") for (int m = 0; m < 4; ++m) _Pragma("unroll") for (int k = 0; k < 2; ++k) dst[m][k] = *(const PG8_LAS bf16x8*)(lds + PG8_SA(b, h) + aoff + m * 2048 + k * 1024); } while (0)
; #define PG8_LDB(dst, b, h) do { _Pragma("unroll") for (int n = 0; n < 2; ++n) _Pragma("unroll") for (int k = 0; k < 2; ++k) dst[n][k] = *(const PG8_LAS bf16x8*)(lds + PG8_SB(b, h) + boff + n * 2048 + k * 1024); } while (0)
; #define PG8_MMA(ai, bj, At, Bt) do { __builtin_amdgcn_s_setprio(1); _Pragma("unroll") for (int m = 0; m < 4; ++m) _Pragma("unroll") for (int n = 0; n < 2; ++n) _Pragma("unroll") for (int k = 0; k < 2; ++k) \
;         acc[ai][bj][m][n] = __builtin_amdgcn_mfma_f32_16x16x32_bf16(Bt[n][k], At[m][k], acc[ai][bj][m][n], 0, 0, 0); __builtin_amdgcn_s_setprio(0); } while (0)
; #define PG8_WAIT_V(n) asm volatile("s_waitcnt vmcnt(" #n ")" ::: "memory")
; #define PG8_WAIT_L(n) asm volatile("s_waitcnt lgkmcnt(" #n ")" ::: "memory")
; #define PG8_BAR __builtin_amdgcn_s_barrier()
; #define PG8_SCHED __builtin_amdgcn_sched_barrier(0)
; template <class Epi, class Sched, bool ALIGN_EPI = false, bool SP2 = false>
; __device__ __forceinline__ void gemm_phase(PG8_LAS unsigned char* lds, const Gemm g, const Sched& S, const Epi& E) {
;     ...
;         for (int t = 0; t < nt; t += 2) {
;     ...
;             PG8_LDB(B0, 1, 0); PG8_LDB(B1, 1, 1); PG8_SCHED; PG8_LDA(At, 1, 0); PG8_STAGE(PG8_SA(0, 1), a2 + hstep, voffA);
;             PG8_WAIT_V(8); PG8_WAIT_L(0); PG8_BAR; PG8_MMA(0, 0, At, B0); PG8_MMA(0, 1, At, B1); PG8_BAR; PG8_SCHED;
;             PG8_LDA(At, 1, 1); PG8_STAGE(PG8_SB(1, 0), b3, voffB); PG8_STAGE(PG8_SB(1, 1), b3 + hstep, voffB); PG8_STAGE(PG8_SA(1, 0), a3, voffA);
;             PG8_WAIT_V(8); PG8_WAIT_L(0); PG8_BAR; PG8_MMA(1, 0, At, B0); PG8_MMA(1, 1, At, B1); PG8_BAR; PG8_SCHED;
	ds_read_b128 v[140:143], v254 offset:32768
	ds_read_b128 v[166:169], v254 offset:33792
	ds_read_b128 v[170:173], v254 offset:34816
	ds_read_b128 v[174:177], v254 offset:35840
	ds_read_b128 v[178:181], v254 offset:49152
	ds_read_b128 v[182:185], v254 offset:50176
	ds_read_b128 v[186:189], v254 offset:51200
	ds_read_b128 v[210:213], v254 offset:52224
	s_add_u32 s4, s4, 0x40000
	s_addc_u32 s5, s5, 0
	s_mov_b32 m0, s38
	ds_read_b128 v[214:217], v163 offset:32768
	ds_read_b128 v[218:221], v163 offset:33792
	ds_read_b128 v[222:225], v163 offset:34816
	ds_read_b128 v[226:229], v163 offset:35840
	ds_read_b128 v[230:233], v163 offset:36864
	ds_read_b128 v[234:237], v163 offset:37888
	ds_read_b128 v[238:241], v163 offset:38912
	ds_read_b128 v[242:245], v163 offset:39936
	global_load_lds_dwordx4 v134, s[4:5]
	s_mov_b32 m0, s39
	s_nop 0
	global_load_lds_dwordx4 v130, s[4:5]
	s_waitcnt vmcnt(8)
	s_waitcnt lgkmcnt(0)
	s_barrier
	s_setprio 1
	v_mfma_f32_16x16x32_bf16 v[124:127], v[140:143], v[214:217], v[124:127]
	v_mfma_f32_16x16x32_bf16 v[124:127], v[166:169], v[218:221], v[124:127]
	v_mfma_f32_16x16x32_bf16 v[120:123], v[170:173], v[214:217], v[120:123]
	v_mfma_f32_16x16x32_bf16 v[120:123], v[174:177], v[218:221], v[120:123]
	v_mfma_f32_16x16x32_bf16 v[116:119], v[178:181], v[214:217], v[116:119]
	v_mfma_f32_16x16x32_bf16 v[116:119], v[182:185], v[218:221], v[116:119]
	v_mfma_f32_16x16x32_bf16 v[112:115], v[186:189], v[214:217], v[112:115]
	v_mfma_f32_16x16x32_bf16 v[112:115], v[210:213], v[218:221], v[112:115]
	v_mfma_f32_16x16x32_bf16 v[108:111], v[140:143], v[222:225], v[108:111]
	v_mfma_f32_16x16x32_bf16 v[108:111], v[166:169], v[226:229], v[108:111]
	v_mfma_f32_16x16x32_bf16 v[104:107], v[170:173], v[222:225], v[104:107]
	v_mfma_f32_16x16x32_bf16 v[104:107], v[174:177], v[226:229], v[104:107]
	v_mfma_f32_16x16x32_bf16 v[100:103], v[178:181], v[222:225], v[100:103]
	v_mfma_f32_16x16x32_bf16 v[100:103], v[182:185], v[226:229], v[100:103]
	v_mfma_f32_16x16x32_bf16 v[96:99], v[186:189], v[222:225], v[96:99]
	v_mfma_f32_16x16x32_bf16 v[96:99], v[210:213], v[226:229], v[96:99]
	v_mfma_f32_16x16x32_bf16 v[92:95], v[140:143], v[230:233], v[92:95]
	v_mfma_f32_16x16x32_bf16 v[92:95], v[166:169], v[234:237], v[92:95]
	v_mfma_f32_16x16x32_bf16 v[88:91], v[170:173], v[230:233], v[88:91]
	v_mfma_f32_16x16x32_bf16 v[88:91], v[174:177], v[234:237], v[88:91]
	v_mfma_f32_16x16x32_bf16 v[84:87], v[178:181], v[230:233], v[84:87]
	v_mfma_f32_16x16x32_bf16 v[84:87], v[182:185], v[234:237], v[84:87]
	v_mfma_f32_16x16x32_bf16 v[80:83], v[186:189], v[230:233], v[80:83]
	v_mfma_f32_16x16x32_bf16 v[80:83], v[210:213], v[234:237], v[80:83]
	v_mfma_f32_16x16x32_bf16 v[76:79], v[140:143], v[238:241], v[76:79]
	v_mfma_f32_16x16x32_bf16 v[76:79], v[166:169], v[242:245], v[76:79]
	v_mfma_f32_16x16x32_bf16 v[72:75], v[170:173], v[238:241], v[72:75]
	v_mfma_f32_16x16x32_bf16 v[72:75], v[174:177], v[242:245], v[72:75]
	v_mfma_f32_16x16x32_bf16 v[68:71], v[178:181], v[238:241], v[68:71]
	v_mfma_f32_16x16x32_bf16 v[68:71], v[182:185], v[242:245], v[68:71]
	v_mfma_f32_16x16x32_bf16 v[64:67], v[186:189], v[238:241], v[64:67]
	v_mfma_f32_16x16x32_bf16 v[64:67], v[210:213], v[242:245], v[64:67]
	s_setprio 0
	s_barrier
	s_mov_b32 m0, s43
	s_add_u32 s2, s2, 0x40080
	s_addc_u32 s3, s3, 0
	ds_read_b128 v[214:217], v163 offset:49152
	ds_read_b128 v[218:221], v163 offset:50176
	ds_read_b128 v[222:225], v163 offset:51200
	ds_read_b128 v[226:229], v163 offset:52224
	ds_read_b128 v[230:233], v163 offset:53248
	ds_read_b128 v[234:237], v163 offset:54272
	ds_read_b128 v[238:241], v163 offset:55296
	ds_read_b128 v[242:245], v163 offset:56320
	s_add_u32 s98, s2, 0xfffc0000
	s_addc_u32 s99, s3, -1
	global_load_lds_dwordx4 v132, s[98:99]
	s_mov_b32 m0, s44
	s_nop 0
	global_load_lds_dwordx4 v128, s[98:99]
	s_mov_b32 m0, s48
	s_nop 0
	global_load_lds_dwordx4 v132, s[2:3]
	s_mov_b32 m0, s49
	s_nop 0
	global_load_lds_dwordx4 v128, s[2:3]
	s_mov_b32 m0, s45
	s_nop 0
	s_add_u32 s100, s4, 0xfffc0080
	s_addc_u32 s101, s5, -1
	global_load_lds_dwordx4 v134, s[100:101]
	s_mov_b32 m0, s47
	s_nop 0
	global_load_lds_dwordx4 v130, s[100:101]
	s_waitcnt vmcnt(8)
	s_waitcnt lgkmcnt(0)
	s_barrier
	s_setprio 1
	v_mfma_f32_16x16x32_bf16 v[60:63], v[140:143], v[214:217], v[60:63]
	v_mfma_f32_16x16x32_bf16 v[60:63], v[166:169], v[218:221], v[60:63]
	v_mfma_f32_16x16x32_bf16 v[56:59], v[170:173], v[214:217], v[56:59]
	v_mfma_f32_16x16x32_bf16 v[56:59], v[174:177], v[218:221], v[56:59]
	v_mfma_f32_16x16x32_bf16 v[52:55], v[178:181], v[214:217], v[52:55]
	v_mfma_f32_16x16x32_bf16 v[52:55], v[182:185], v[218:221], v[52:55]
	v_mfma_f32_16x16x32_bf16 v[48:51], v[186:189], v[214:217], v[48:51]
	v_mfma_f32_16x16x32_bf16 v[48:51], v[210:213], v[218:221], v[48:51]
	v_mfma_f32_16x16x32_bf16 v[44:47], v[140:143], v[222:225], v[44:47]
	v_mfma_f32_16x16x32_bf16 v[44:47], v[166:169], v[226:229], v[44:47]
	v_mfma_f32_16x16x32_bf16 v[40:43], v[170:173], v[222:225], v[40:43]
	v_mfma_f32_16x16x32_bf16 v[40:43], v[174:177], v[226:229], v[40:43]
	v_mfma_f32_16x16x32_bf16 v[36:39], v[178:181], v[222:225], v[36:39]
	v_mfma_f32_16x16x32_bf16 v[36:39], v[182:185], v[226:229], v[36:39]
	v_mfma_f32_16x16x32_bf16 v[32:35], v[186:189], v[222:225], v[32:35]
	v_mfma_f32_16x16x32_bf16 v[32:35], v[210:213], v[226:229], v[32:35]
	v_mfma_f32_16x16x32_bf16 v[28:31], v[140:143], v[230:233], v[28:31]
	v_mfma_f32_16x16x32_bf16 v[28:31], v[166:169], v[234:237], v[28:31]
	v_mfma_f32_16x16x32_bf16 v[24:27], v[170:173], v[230:233], v[24:27]
	v_mfma_f32_16x16x32_bf16 v[24:27], v[174:177], v[234:237], v[24:27]
	v_mfma_f32_16x16x32_bf16 v[20:23], v[178:181], v[230:233], v[20:23]
	v_mfma_f32_16x16x32_bf16 v[20:23], v[182:185], v[234:237], v[20:23]
	v_mfma_f32_16x16x32_bf16 v[16:19], v[186:189], v[230:233], v[16:19]
	v_mfma_f32_16x16x32_bf16 v[16:19], v[210:213], v[234:237], v[16:19]
	v_mfma_f32_16x16x32_bf16 v[12:15], v[140:143], v[238:241], v[12:15]
	v_mfma_f32_16x16x32_bf16 v[12:15], v[166:169], v[242:245], v[12:15]
	v_mfma_f32_16x16x32_bf16 v[8:11], v[170:173], v[238:241], v[8:11]
	v_mfma_f32_16x16x32_bf16 v[8:11], v[174:177], v[242:245], v[8:11]
	v_mfma_f32_16x16x32_bf16 v[4:7], v[178:181], v[238:241], v[4:7]
	v_mfma_f32_16x16x32_bf16 v[4:7], v[182:185], v[242:245], v[4:7]
	v_mfma_f32_16x16x32_bf16 v[0:3], v[186:189], v[238:241], v[0:3]
	v_mfma_f32_16x16x32_bf16 v[0:3], v[210:213], v[242:245], v[0:3]
	s_setprio 0
	s_barrier
	s_add_i32 s55, s55, 2
	s_add_u32 s0, s0, 0x100
	s_addc_u32 s1, s1, 0
	s_add_u32 s53, s53, 0x100
	s_addc_u32 s54, s54, 0
	s_cmp_gt_u32 s55, 13
; #define PG8_STAGE(bufoff, gbase, voff) do { _Pragma("unroll") for (int _i = 0; _i < 2; ++_i) \
;         __builtin_amdgcn_global_load_lds((const unsigned*)((const char*)(gbase) + (voff)[_i]), (PG8_LAS unsigned*)(lds + (bufoff) + ldsw + _i * 8192), 16, 0, 0); } while (0)
; #define PG8_LDA(dst, b, h) do { _Pragma("unroll") for (int m = 0; m < 4; ++m) _Pragma("unroll") for (int k = 0; k < 2; ++k) dst[m][k] = *(const PG8_LAS bf16x8*)(lds + PG8_SA(b, h) + aoff + m * 2048 + k * 1024); } while (0)
; #define PG8_LDB(dst, b, h) do { _Pragma("unroll") for (int n = 0; n < 2; ++n) _Pragma("unroll") for (int k = 0; k < 2; ++k) dst[n][k] = *(const PG8_LAS bf16x8*)(lds + PG8_SB(b, h) + boff + n * 2048 + k * 1024); } while (0)
; #define PG8_MMA(ai, bj, At, Bt) do { __builtin_amdgcn_s_setprio(1); _Pragma("unroll") for (int m = 0; m < 4; ++m) _Pragma("unroll") for (int n = 0; n < 2; ++n) _Pragma("unroll") for (int k = 0; k < 2; ++k) \
;         acc[ai][bj][m][n] = __builtin_amdgcn_mfma_f32_16x16x32_bf16(Bt[n][k], At[m][k], acc[ai][bj][m][n], 0, 0, 0); __builtin_amdgcn_s_setprio(0); } while (0)
; #define PG8_WAIT_V(n) asm volatile("s_waitcnt vmcnt(" #n ")" ::: "memory")
; #define PG8_BAR __builtin_amdgcn_s_barrier()
; template <class Epi, class Sched, bool ALIGN_EPI = false, bool SP2 = false>
; __device__ __forceinline__ void gemm_phase(PG8_LAS unsigned char* lds, const Gemm g, const Sched& S, const Epi& E) {
;     ...
;         for (int t = 0; t < nt; t += 2) {
;             const bool last = (t == nt - 2);
;             const char* a1 = cA + (size_t)(t + 1) * kstep;
;             const char* a2 = last ? nA : cA + (size_t)(t + 2) * kstep; const char* b2 = last ? nB : cB + (size_t)(t + 2) * kstep;
;             const char* a3 = a2 + kstep; const char* b3 = b2 + kstep;
;             if (last && has_next) S.a_ready(nxt);
;             if constexpr (SP2) {
;             PG8_LDB(B0, 0, 0); PG8_LDB(B1, 0, 1); PG8_SCHED; PG8_LDA(At, 0, 0); PG8_STAGE(PG8_SA(1, 1), a1 + hstep, voffA);
;             PG8_WAIT_V(8); PG8_WAIT_L(0); PG8_BAR; PG8_MMA(0, 0, At, B0); PG8_MMA(0, 1, At, B1); PG8_BAR; PG8_SCHED;
;             PG8_LDA(At, 0, 1); PG8_STAGE(PG8_SB(0, 0), b2, voffB); PG8_STAGE(PG8_SB(0, 1), b2 + hstep, voffB); PG8_STAGE(PG8_SA(0, 0), a2, voffA);
;             PG8_WAIT_V(8); PG8_WAIT_L(0); PG8_BAR; PG8_MMA(1, 0, At, B0); PG8_MMA(1, 1, At, B1); PG8_BAR; PG8_SCHED;
.LBB0_1042:
	ds_read_b128 v[140:143], v254
	ds_read_b128 v[166:169], v254 offset:1024
	ds_read_b128 v[170:173], v254 offset:2048
	ds_read_b128 v[174:177], v254 offset:3072
	ds_read_b128 v[178:181], v254 offset:16384
	ds_read_b128 v[182:185], v254 offset:17408
	ds_read_b128 v[186:189], v254 offset:18432
	ds_read_b128 v[210:213], v254 offset:19456
	s_add_u32 s2, s0, 0xfffc0080
	s_addc_u32 s3, s1, -1
	s_cmp_eq_u32 s55, 12
	s_cselect_b32 s5, s23, s3
	s_cselect_b32 s4, s51, s2
	s_cselect_b32 s3, s21, s54
	s_cselect_b32 s2, s52, s53
	s_add_i32 m0, s31, 0xc000
	ds_read_b128 v[214:217], v163
	ds_read_b128 v[218:221], v163 offset:1024
	ds_read_b128 v[222:225], v163 offset:2048
	ds_read_b128 v[226:229], v163 offset:3072
	ds_read_b128 v[230:233], v163 offset:4096
	ds_read_b128 v[234:237], v163 offset:5120
	ds_read_b128 v[238:241], v163 offset:6144
	ds_read_b128 v[242:245], v163 offset:7168
	global_load_lds_dwordx4 v136, s[0:1]
	s_add_i32 m0, s31, 0xe000
	s_nop 0
	global_load_lds_dwordx4 v138, s[0:1]
	s_waitcnt vmcnt(8)
	s_waitcnt lgkmcnt(0)
	s_barrier
	s_setprio 1
	v_mfma_f32_16x16x32_bf16 v[124:127], v[140:143], v[214:217], v[124:127]
	v_mfma_f32_16x16x32_bf16 v[124:127], v[166:169], v[218:221], v[124:127]
	v_mfma_f32_16x16x32_bf16 v[120:123], v[170:173], v[214:217], v[120:123]
	v_mfma_f32_16x16x32_bf16 v[120:123], v[174:177], v[218:221], v[120:123]
	v_mfma_f32_16x16x32_bf16 v[116:119], v[178:181], v[214:217], v[116:119]
	v_mfma_f32_16x16x32_bf16 v[116:119], v[182:185], v[218:221], v[116:119]
	v_mfma_f32_16x16x32_bf16 v[112:115], v[186:189], v[214:217], v[112:115]
	v_mfma_f32_16x16x32_bf16 v[112:115], v[210:213], v[218:221], v[112:115]
	v_mfma_f32_16x16x32_bf16 v[108:111], v[140:143], v[222:225], v[108:111]
	v_mfma_f32_16x16x32_bf16 v[108:111], v[166:169], v[226:229], v[108:111]
	v_mfma_f32_16x16x32_bf16 v[104:107], v[170:173], v[222:225], v[104:107]
	v_mfma_f32_16x16x32_bf16 v[104:107], v[174:177], v[226:229], v[104:107]
	v_mfma_f32_16x16x32_bf16 v[100:103], v[178:181], v[222:225], v[100:103]
	v_mfma_f32_16x16x32_bf16 v[100:103], v[182:185], v[226:229], v[100:103]
	v_mfma_f32_16x16x32_bf16 v[96:99], v[186:189], v[222:225], v[96:99]
	v_mfma_f32_16x16x32_bf16 v[96:99], v[210:213], v[226:229], v[96:99]
	v_mfma_f32_16x16x32_bf16 v[92:95], v[140:143], v[230:233], v[92:95]
	v_mfma_f32_16x16x32_bf16 v[92:95], v[166:169], v[234:237], v[92:95]
	v_mfma_f32_16x16x32_bf16 v[88:91], v[170:173], v[230:233], v[88:91]
	v_mfma_f32_16x16x32_bf16 v[88:91], v[174:177], v[234:237], v[88:91]
	v_mfma_f32_16x16x32_bf16 v[84:87], v[178:181], v[230:233], v[84:87]
	v_mfma_f32_16x16x32_bf16 v[84:87], v[182:185], v[234:237], v[84:87]
	v_mfma_f32_16x16x32_bf16 v[80:83], v[186:189], v[230:233], v[80:83]
	v_mfma_f32_16x16x32_bf16 v[80:83], v[210:213], v[234:237], v[80:83]
	v_mfma_f32_16x16x32_bf16 v[76:79], v[140:143], v[238:241], v[76:79]
	v_mfma_f32_16x16x32_bf16 v[76:79], v[166:169], v[242:245], v[76:79]
	v_mfma_f32_16x16x32_bf16 v[72:75], v[170:173], v[238:241], v[72:75]
	v_mfma_f32_16x16x32_bf16 v[72:75], v[174:177], v[242:245], v[72:75]
	v_mfma_f32_16x16x32_bf16 v[68:71], v[178:181], v[238:241], v[68:71]
	v_mfma_f32_16x16x32_bf16 v[68:71], v[182:185], v[242:245], v[68:71]
	v_mfma_f32_16x16x32_bf16 v[64:67], v[186:189], v[238:241], v[64:67]
	v_mfma_f32_16x16x32_bf16 v[64:67], v[210:213], v[242:245], v[64:67]
	s_setprio 0
	s_barrier
	s_mov_b32 m0, s33
	s_add_u32 s56, s2, 0x40000
	s_addc_u32 s57, s3, 0
	ds_read_b128 v[214:217], v163 offset:16384
	ds_read_b128 v[218:221], v163 offset:17408
	ds_read_b128 v[222:225], v163 offset:18432
	ds_read_b128 v[226:229], v163 offset:19456
	ds_read_b128 v[230:233], v163 offset:20480
	ds_read_b128 v[234:237], v163 offset:21504
	ds_read_b128 v[238:241], v163 offset:22528
	ds_read_b128 v[242:245], v163 offset:23552
	global_load_lds_dwordx4 v132, s[2:3]
	s_mov_b32 m0, s34
	s_nop 0
	global_load_lds_dwordx4 v128, s[2:3]
	s_mov_b32 m0, s35
	s_nop 0
	global_load_lds_dwordx4 v132, s[56:57]
	s_mov_b32 m0, s36
	s_nop 0
	global_load_lds_dwordx4 v128, s[56:57]
	s_mov_b32 m0, s31
	s_nop 0
	global_load_lds_dwordx4 v134, s[4:5]
	s_mov_b32 m0, s37
	s_nop 0
	global_load_lds_dwordx4 v130, s[4:5]
	s_waitcnt vmcnt(8)
	s_waitcnt lgkmcnt(0)
	s_barrier
	s_setprio 1
	v_mfma_f32_16x16x32_bf16 v[60:63], v[140:143], v[214:217], v[60:63]
	v_mfma_f32_16x16x32_bf16 v[60:63], v[166:169], v[218:221], v[60:63]
	v_mfma_f32_16x16x32_bf16 v[56:59], v[170:173], v[214:217], v[56:59]
	v_mfma_f32_16x16x32_bf16 v[56:59], v[174:177], v[218:221], v[56:59]
	v_mfma_f32_16x16x32_bf16 v[52:55], v[178:181], v[214:217], v[52:55]
	v_mfma_f32_16x16x32_bf16 v[52:55], v[182:185], v[218:221], v[52:55]
	v_mfma_f32_16x16x32_bf16 v[48:51], v[186:189], v[214:217], v[48:51]
	v_mfma_f32_16x16x32_bf16 v[48:51], v[210:213], v[218:221], v[48:51]
	v_mfma_f32_16x16x32_bf16 v[44:47], v[140:143], v[222:225], v[44:47]
	v_mfma_f32_16x16x32_bf16 v[44:47], v[166:169], v[226:229], v[44:47]
	v_mfma_f32_16x16x32_bf16 v[40:43], v[170:173], v[222:225], v[40:43]
	v_mfma_f32_16x16x32_bf16 v[40:43], v[174:177], v[226:229], v[40:43]
	v_mfma_f32_16x16x32_bf16 v[36:39], v[178:181], v[222:225], v[36:39]
	v_mfma_f32_16x16x32_bf16 v[36:39], v[182:185], v[226:229], v[36:39]
	v_mfma_f32_16x16x32_bf16 v[32:35], v[186:189], v[222:225], v[32:35]
	v_mfma_f32_16x16x32_bf16 v[32:35], v[210:213], v[226:229], v[32:35]
	v_mfma_f32_16x16x32_bf16 v[28:31], v[140:143], v[230:233], v[28:31]
	v_mfma_f32_16x16x32_bf16 v[28:31], v[166:169], v[234:237], v[28:31]
	v_mfma_f32_16x16x32_bf16 v[24:27], v[170:173], v[230:233], v[24:27]
	v_mfma_f32_16x16x32_bf16 v[24:27], v[174:177], v[234:237], v[24:27]
	v_mfma_f32_16x16x32_bf16 v[20:23], v[178:181], v[230:233], v[20:23]
	v_mfma_f32_16x16x32_bf16 v[20:23], v[182:185], v[234:237], v[20:23]
	v_mfma_f32_16x16x32_bf16 v[16:19], v[186:189], v[230:233], v[16:19]
	v_mfma_f32_16x16x32_bf16 v[16:19], v[210:213], v[234:237], v[16:19]
	v_mfma_f32_16x16x32_bf16 v[12:15], v[140:143], v[238:241], v[12:15]
	v_mfma_f32_16x16x32_bf16 v[12:15], v[166:169], v[242:245], v[12:15]
	v_mfma_f32_16x16x32_bf16 v[8:11], v[170:173], v[238:241], v[8:11]
	v_mfma_f32_16x16x32_bf16 v[8:11], v[174:177], v[242:245], v[8:11]
	v_mfma_f32_16x16x32_bf16 v[4:7], v[178:181], v[238:241], v[4:7]
	v_mfma_f32_16x16x32_bf16 v[4:7], v[182:185], v[242:245], v[4:7]
	v_mfma_f32_16x16x32_bf16 v[0:3], v[186:189], v[238:241], v[0:3]
	v_mfma_f32_16x16x32_bf16 v[0:3], v[210:213], v[242:245], v[0:3]
	s_setprio 0
	s_barrier
; #define PG8_STAGE(bufoff, gbase, voff) do { _Pragma("unroll") for (int _i = 0; _i < 2; ++_i) \
;         __builtin_amdgcn_global_load_lds((const unsigned*)((const char*)(gbase) + (voff)[_i]), (PG8_LAS unsigned*)(lds + (bufoff) + ldsw + _i * 8192), 16, 0, 0); } while (0)
; #define PG8_LDA(dst, b, h) do { _Pragma("unroll") for (int m = 0; m < 4; ++m) _Pragma("unroll") for (int k = 0; k < 2; ++k) dst[m][k] = *(const PG8_LAS bf16x8*)(lds + PG8_SA(b, h) + aoff + m * 2048 + k * 1024); } while (0)
; #define PG8_LDB(dst, b, h) do { _Pragma("unroll") for (int n = 0; n < 2; ++n) _Pragma("unroll") for (int k = 0; k < 2; ++k) dst[n][k] = *(const PG8_LAS bf16x8*)(lds + PG8_SB(b, h) + boff + n * 2048 + k * 1024); } while (0)
; #define PG8_MMA(ai, bj, At, Bt) do { __builtin_amdgcn_s_setprio(1); _Pragma("unroll") for (int m = 0; m < 4; ++m) _Pragma("unroll") for (int n = 0; n < 2; ++n) _Pragma("unroll") for (int k = 0; k < 2; ++k) \
;         acc[ai][bj][m][n] = __builtin_amdgcn_mfma_f32_16x16x32_bf16(Bt[n][k], At[m][k], acc[ai][bj][m][n], 0, 0, 0); __builtin_amdgcn_s_setprio(0); } while (0)
; #define PG8_WAIT_V(n) asm volatile("s_waitcnt vmcnt(" #n ")" ::: "memory")
; #define PG8_WAIT_L(n) asm volatile("s_waitcnt lgkmcnt(" #n ")" ::: "memory")
; #define PG8_BAR __builtin_amdgcn_s_barrier()
; #define PG8_SCHED __builtin_amdgcn_sched_barrier(0)
; template <class Epi, class Sched, bool ALIGN_EPI = false, bool SP2 = false>
; __device__ __forceinline__ void gemm_phase(PG8_LAS unsigned char* lds, const Gemm g, const Sched& S, const Epi& E) {
;     ...
;             PG8_LDB(B0, 1, 0); PG8_LDB(B1, 1, 1); PG8_SCHED; PG8_LDA(At, 1, 0); PG8_STAGE(PG8_SA(0, 1), a2 + hstep, voffA);
;             PG8_WAIT_V(8); PG8_WAIT_L(0); PG8_BAR; PG8_MMA(0, 0, At, B0); PG8_MMA(0, 1, At, B1); PG8_BAR; PG8_SCHED;
;             PG8_LDA(At, 1, 1); PG8_STAGE(PG8_SB(1, 0), b3, voffB); PG8_STAGE(PG8_SB(1, 1), b3 + hstep, voffB); PG8_STAGE(PG8_SA(1, 0), a3, voffA);
;             PG8_WAIT_V(8); PG8_WAIT_L(0); PG8_BAR; PG8_MMA(1, 0, At, B0); PG8_MMA(1, 1, At, B1); PG8_BAR; PG8_SCHED;
;     ...
;         if constexpr (ALIGN_EPI) { if (wr == 0) PG8_BAR; }
	ds_read_b128 v[140:143], v254 offset:32768
	ds_read_b128 v[166:169], v254 offset:33792
	ds_read_b128 v[170:173], v254 offset:34816
	ds_read_b128 v[174:177], v254 offset:35840
	ds_read_b128 v[178:181], v254 offset:49152
	ds_read_b128 v[182:185], v254 offset:50176
	ds_read_b128 v[186:189], v254 offset:51200
	ds_read_b128 v[210:213], v254 offset:52224
	s_add_u32 s4, s4, 0x40000
	s_addc_u32 s5, s5, 0
	s_mov_b32 m0, s38
	ds_read_b128 v[214:217], v163 offset:32768
	ds_read_b128 v[218:221], v163 offset:33792
	ds_read_b128 v[222:225], v163 offset:34816
	ds_read_b128 v[226:229], v163 offset:35840
	ds_read_b128 v[230:233], v163 offset:36864
	ds_read_b128 v[234:237], v163 offset:37888
	ds_read_b128 v[238:241], v163 offset:38912
	ds_read_b128 v[242:245], v163 offset:39936
	global_load_lds_dwordx4 v134, s[4:5]
	s_mov_b32 m0, s39
	s_nop 0
	global_load_lds_dwordx4 v130, s[4:5]
	s_waitcnt vmcnt(8)
	s_waitcnt lgkmcnt(0)
	s_barrier
	s_setprio 1
	v_mfma_f32_16x16x32_bf16 v[124:127], v[140:143], v[214:217], v[124:127]
	v_mfma_f32_16x16x32_bf16 v[124:127], v[166:169], v[218:221], v[124:127]
	v_mfma_f32_16x16x32_bf16 v[120:123], v[170:173], v[214:217], v[120:123]
	v_mfma_f32_16x16x32_bf16 v[120:123], v[174:177], v[218:221], v[120:123]
	v_mfma_f32_16x16x32_bf16 v[116:119], v[178:181], v[214:217], v[116:119]
	v_mfma_f32_16x16x32_bf16 v[116:119], v[182:185], v[218:221], v[116:119]
	v_mfma_f32_16x16x32_bf16 v[112:115], v[186:189], v[214:217], v[112:115]
	v_mfma_f32_16x16x32_bf16 v[112:115], v[210:213], v[218:221], v[112:115]
	v_mfma_f32_16x16x32_bf16 v[108:111], v[140:143], v[222:225], v[108:111]
	v_mfma_f32_16x16x32_bf16 v[108:111], v[166:169], v[226:229], v[108:111]
	v_mfma_f32_16x16x32_bf16 v[104:107], v[170:173], v[222:225], v[104:107]
	v_mfma_f32_16x16x32_bf16 v[104:107], v[174:177], v[226:229], v[104:107]
	v_mfma_f32_16x16x32_bf16 v[100:103], v[178:181], v[222:225], v[100:103]
	v_mfma_f32_16x16x32_bf16 v[100:103], v[182:185], v[226:229], v[100:103]
	v_mfma_f32_16x16x32_bf16 v[96:99], v[186:189], v[222:225], v[96:99]
	v_mfma_f32_16x16x32_bf16 v[96:99], v[210:213], v[226:229], v[96:99]
	v_mfma_f32_16x16x32_bf16 v[92:95], v[140:143], v[230:233], v[92:95]
	v_mfma_f32_16x16x32_bf16 v[92:95], v[166:169], v[234:237], v[92:95]
	v_mfma_f32_16x16x32_bf16 v[88:91], v[170:173], v[230:233], v[88:91]
	v_mfma_f32_16x16x32_bf16 v[88:91], v[174:177], v[234:237], v[88:91]
	v_mfma_f32_16x16x32_bf16 v[84:87], v[178:181], v[230:233], v[84:87]
	v_mfma_f32_16x16x32_bf16 v[84:87], v[182:185], v[234:237], v[84:87]
	v_mfma_f32_16x16x32_bf16 v[80:83], v[186:189], v[230:233], v[80:83]
	v_mfma_f32_16x16x32_bf16 v[80:83], v[210:213], v[234:237], v[80:83]
	v_mfma_f32_16x16x32_bf16 v[76:79], v[140:143], v[238:241], v[76:79]
	v_mfma_f32_16x16x32_bf16 v[76:79], v[166:169], v[242:245], v[76:79]
	v_mfma_f32_16x16x32_bf16 v[72:75], v[170:173], v[238:241], v[72:75]
	v_mfma_f32_16x16x32_bf16 v[72:75], v[174:177], v[242:245], v[72:75]
	v_mfma_f32_16x16x32_bf16 v[68:71], v[178:181], v[238:241], v[68:71]
	v_mfma_f32_16x16x32_bf16 v[68:71], v[182:185], v[242:245], v[68:71]
	v_mfma_f32_16x16x32_bf16 v[64:67], v[186:189], v[238:241], v[64:67]
	v_mfma_f32_16x16x32_bf16 v[64:67], v[210:213], v[242:245], v[64:67]
	s_setprio 0
	s_barrier
	s_mov_b32 m0, s43
	s_add_u32 s2, s2, 0x40080
	s_addc_u32 s3, s3, 0
	ds_read_b128 v[214:217], v163 offset:49152
	ds_read_b128 v[218:221], v163 offset:50176
	ds_read_b128 v[222:225], v163 offset:51200
	ds_read_b128 v[226:229], v163 offset:52224
	ds_read_b128 v[230:233], v163 offset:53248
	ds_read_b128 v[234:237], v163 offset:54272
	ds_read_b128 v[238:241], v163 offset:55296
	ds_read_b128 v[242:245], v163 offset:56320
	s_add_u32 s98, s2, 0xfffc0000
	s_addc_u32 s99, s3, -1
	global_load_lds_dwordx4 v132, s[98:99]
	s_mov_b32 m0, s44
	s_nop 0
	global_load_lds_dwordx4 v128, s[98:99]
	s_mov_b32 m0, s48
	s_nop 0
	global_load_lds_dwordx4 v132, s[2:3]
	s_mov_b32 m0, s49
	s_nop 0
	global_load_lds_dwordx4 v128, s[2:3]
	s_mov_b32 m0, s45
	s_nop 0
	s_add_u32 s100, s4, 0xfffc0080
	s_addc_u32 s101, s5, -1
	global_load_lds_dwordx4 v134, s[100:101]
	s_mov_b32 m0, s47
	s_nop 0
	global_load_lds_dwordx4 v130, s[100:101]
	s_waitcnt vmcnt(8)
	s_waitcnt lgkmcnt(0)
	s_barrier
	s_setprio 1
	v_mfma_f32_16x16x32_bf16 v[60:63], v[140:143], v[214:217], v[60:63]
	v_mfma_f32_16x16x32_bf16 v[60:63], v[166:169], v[218:221], v[60:63]
	v_mfma_f32_16x16x32_bf16 v[56:59], v[170:173], v[214:217], v[56:59]
	v_mfma_f32_16x16x32_bf16 v[56:59], v[174:177], v[218:221], v[56:59]
	v_mfma_f32_16x16x32_bf16 v[52:55], v[178:181], v[214:217], v[52:55]
	v_mfma_f32_16x16x32_bf16 v[52:55], v[182:185], v[218:221], v[52:55]
	v_mfma_f32_16x16x32_bf16 v[48:51], v[186:189], v[214:217], v[48:51]
	v_mfma_f32_16x16x32_bf16 v[48:51], v[210:213], v[218:221], v[48:51]
	v_mfma_f32_16x16x32_bf16 v[44:47], v[140:143], v[222:225], v[44:47]
	v_mfma_f32_16x16x32_bf16 v[44:47], v[166:169], v[226:229], v[44:47]
	v_mfma_f32_16x16x32_bf16 v[40:43], v[170:173], v[222:225], v[40:43]
	v_mfma_f32_16x16x32_bf16 v[40:43], v[174:177], v[226:229], v[40:43]
	v_mfma_f32_16x16x32_bf16 v[36:39], v[178:181], v[222:225], v[36:39]
	v_mfma_f32_16x16x32_bf16 v[36:39], v[182:185], v[226:229], v[36:39]
	v_mfma_f32_16x16x32_bf16 v[32:35], v[186:189], v[222:225], v[32:35]
	v_mfma_f32_16x16x32_bf16 v[32:35], v[210:213], v[226:229], v[32:35]
	v_mfma_f32_16x16x32_bf16 v[28:31], v[140:143], v[230:233], v[28:31]
	v_mfma_f32_16x16x32_bf16 v[28:31], v[166:169], v[234:237], v[28:31]
	v_mfma_f32_16x16x32_bf16 v[24:27], v[170:173], v[230:233], v[24:27]
	v_mfma_f32_16x16x32_bf16 v[24:27], v[174:177], v[234:237], v[24:27]
	v_mfma_f32_16x16x32_bf16 v[20:23], v[178:181], v[230:233], v[20:23]
	v_mfma_f32_16x16x32_bf16 v[20:23], v[182:185], v[234:237], v[20:23]
	v_mfma_f32_16x16x32_bf16 v[16:19], v[186:189], v[230:233], v[16:19]
	v_mfma_f32_16x16x32_bf16 v[16:19], v[210:213], v[234:237], v[16:19]
	v_mfma_f32_16x16x32_bf16 v[12:15], v[140:143], v[238:241], v[12:15]
	v_mfma_f32_16x16x32_bf16 v[12:15], v[166:169], v[242:245], v[12:15]
	v_mfma_f32_16x16x32_bf16 v[8:11], v[170:173], v[238:241], v[8:11]
	v_mfma_f32_16x16x32_bf16 v[8:11], v[174:177], v[242:245], v[8:11]
	v_mfma_f32_16x16x32_bf16 v[4:7], v[178:181], v[238:241], v[4:7]
	v_mfma_f32_16x16x32_bf16 v[4:7], v[182:185], v[242:245], v[4:7]
	v_mfma_f32_16x16x32_bf16 v[0:3], v[186:189], v[238:241], v[0:3]
	v_mfma_f32_16x16x32_bf16 v[0:3], v[210:213], v[242:245], v[0:3]
	s_setprio 0
	s_barrier
	s_add_i32 s55, s55, 2
	s_add_u32 s0, s0, 0x100
	s_addc_u32 s1, s1, 0
	s_add_u32 s53, s53, 0x100
	s_addc_u32 s54, s54, 0
	s_cmp_gt_u32 s55, 13
	s_cbranch_scc0 .LBB0_1042
	s_and_b64 vcc, exec, s[18:19]
	s_cbranch_vccz .LBB0_1045
	s_barrier
